# speedup vs baseline: 1.0008x; 1.0008x over previous
; __device__ __forceinline__ unsigned pk2(float lo, float hi) { f32x2 v = {lo, hi}; bf16x2_t b = __builtin_convertvector(v, bf16x2_t); return __builtin_bit_cast(unsigned, b); }
; __device__ __forceinline__ float bflo(unsigned w) { return __uint_as_float(w << 16); }
; __device__ __forceinline__ float bfhi(unsigned w) { return __uint_as_float(w & 0xffff0000u); }
; __device__ __forceinline__ float fast_sigmoid(float g) { return __builtin_amdgcn_rcpf(1.0f + __expf(-g)); }
;     __device__ __forceinline__ void operator()(const f32x4 (&acc)[2][2][4][2], const Unit& u, int wr, int wc, int fr, int fq) const {
;         const int row0 = u.pm * BM + wr * 64 + fr, col0 = u.pn * HALF + wc * 32 + 8 * fq;
;         const f32x4 bv0 = *(const f32x4*)(bias + col0), bv1 = *(const f32x4*)(bias + col0 + 4), bg0 = *(const f32x4*)(bias + DM + col0), bg1 = *(const f32x4*)(bias + DM + col0 + 4);
;         u32x4 cur = *(const u32x4*)(xb + (size_t)row0 * DM + col0), nxt = cur;
; #pragma unroll
;         for (int j = 0; j < 8; ++j) { const int ai = j >> 2, m = j & 3; const int row = row0 + ai * HALF + m * 16; const size_t off = (size_t)row * DM + col0; float ss = 0.f; f32x4 o[2];
;             if (j < 7) nxt = *(const u32x4*)(xb + (size_t)(row0 + ((j + 1) >> 2) * HALF + ((j + 1) & 3) * 16) * DM + col0);
; #pragma unroll
;             for (int n = 0; n < 2; ++n) {
;                 const f32x4 v = acc[ai][0][m][n] + (n ? bv1 : bv0), g = acc[ai][1][m][n] + (n ? bg1 : bg0);
;                 const unsigned w0 = n ? cur.z : cur.x, w1 = n ? cur.w : cur.y; o[n] = (f32x4){bflo(w0), bfhi(w0), bflo(w1), bfhi(w1)};
;                 o[n][0] += v[0] * fast_sigmoid(g[0]); o[n][1] += v[1] * fast_sigmoid(g[1]); o[n][2] += v[2] * fast_sigmoid(g[2]); o[n][3] += v[3] * fast_sigmoid(g[3]);
;                 ss += (o[n][0] * o[n][0] + o[n][1] * o[n][1]) + (o[n][2] * o[n][2] + o[n][3] * o[n][3]); }
;             { u32x4 w; w.x = pk2(o[0][0], o[0][1]); w.y = pk2(o[0][2], o[0][3]); w.z = pk2(o[1][0], o[1][1]); w.w = pk2(o[1][2], o[1][3]); *(u32x4*)(xb + off) = w; }
;             ss += __shfl_xor(ss, 16); ss += __shfl_xor(ss, 32); if (fq == 0) rsq[(size_t)row * 64 + u.pn * 4 + wc] = ss;
.LBB0_266:
	v_lshl_or_b32 v164, s52, 7, v176
	v_ashrrev_i32_e32 v165, 31, v164
	v_lshlrev_b64 v[84:85], 2, v[164:165]
	v_lshl_add_u64 v[86:87], s[8:9], 0, v[84:85]
	v_lshl_add_u64 v[102:103], s[60:61], 0, v[84:85]
	global_load_dwordx4 v[88:91], v[86:87], off offset:16
	global_load_dwordx4 v[106:109], v[86:87], off
	s_nop 0
	global_load_dwordx4 v[84:87], v[102:103], off offset:16
	s_nop 0
	global_load_dwordx4 v[102:105], v[102:103], off
	v_lshl_add_u32 v166, s54, 8, v174
	v_ashrrev_i32_e32 v167, 31, v166
	v_lshlrev_b64 v[146:147], 12, v[166:167]
	v_lshl_add_u64 v[146:147], s[12:13], 0, v[146:147]
	v_lshlrev_b64 v[148:149], 1, v[164:165]
	v_lshl_add_u64 v[172:173], v[146:147], 0, v[148:149]
	global_load_dwordx4 v[150:153], v[172:173], off
	v_and_b32_e32 v147, 64, v251
	v_xor_b32_e32 v146, 16, v251
	v_add_u32_e32 v147, 64, v147
	v_cmp_lt_i32_e32 vcc, v146, v147
	v_or_b32_e32 v168, 16, v166
	v_ashrrev_i32_e32 v169, 31, v168
	v_cndmask_b32_e32 v146, v251, v146, vcc
	v_lshlrev_b32_e32 v178, 2, v146
	v_xor_b32_e32 v146, 32, v251
	v_cmp_lt_i32_e32 vcc, v146, v147
	s_lshl_b32 s52, s52, 2
	s_ashr_i32 s53, s52, 31
	v_cndmask_b32_e32 v146, v251, v146, vcc
	v_lshlrev_b32_e32 v179, 2, v146
	v_lshlrev_b64 v[146:147], 12, v[168:169]
	v_lshl_add_u64 v[146:147], s[12:13], 0, v[146:147]
	v_lshl_add_u64 v[170:171], v[146:147], 0, v[148:149]
	global_load_dwordx4 v[146:149], v[170:171], off
	s_waitcnt vmcnt(0)
	v_pk_add_f32 v[134:135], v[134:135], v[88:89]
	v_pk_add_f32 v[130:131], v[130:131], v[84:85]
	v_pk_add_f32 v[138:139], v[138:139], v[102:103]
	v_mul_f32_e32 v130, 0xbfb8aa3b, v130
	v_mul_f32_e32 v138, 0xbfb8aa3b, v138
	v_mul_f32_e32 v139, 0xbfb8aa3b, v139
	v_exp_f32_e32 v138, v138
	v_exp_f32_e32 v139, v139
	v_mul_f32_e32 v131, 0xbfb8aa3b, v131
	v_exp_f32_e32 v130, v130
	v_exp_f32_e32 v131, v131
	v_add_f32_e32 v138, 1.0, v138
	v_add_f32_e32 v139, 1.0, v139
	v_rcp_f32_e32 v138, v138
	v_rcp_f32_e32 v139, v139
	v_add_f32_e32 v130, 1.0, v130
	v_add_f32_e32 v131, 1.0, v131
	v_rcp_f32_e32 v130, v130
	v_rcp_f32_e32 v131, v131
	v_pk_add_f32 v[142:143], v[142:143], v[106:107]
	v_lshlrev_b32_e32 v180, 16, v150
	v_and_b32_e32 v181, 0xffff0000, v150
	v_pk_fma_f32 v[138:139], v[142:143], v[138:139], v[180:181]
	v_lshlrev_b32_e32 v142, 16, v151
	v_and_b32_e32 v143, 0xffff0000, v151
	v_pk_add_f32 v[132:133], v[132:133], v[86:87]
	v_lshlrev_b32_e32 v150, 16, v152
	v_and_b32_e32 v151, 0xffff0000, v152
	v_pk_add_f32 v[140:141], v[140:141], v[104:105]
	v_pk_fma_f32 v[134:135], v[134:135], v[130:131], v[150:151]
	v_mul_f32_e32 v130, 0xbfb8aa3b, v132
	v_mul_f32_e32 v131, 0xbfb8aa3b, v133
	v_mul_f32_e32 v140, 0xbfb8aa3b, v140
	v_mul_f32_e32 v141, 0xbfb8aa3b, v141
	v_exp_f32_e32 v130, v130
	v_exp_f32_e32 v131, v131
	v_exp_f32_e32 v140, v140
	v_exp_f32_e32 v141, v141
	v_add_f32_e32 v130, 1.0, v130
	v_add_f32_e32 v131, 1.0, v131
	v_add_f32_e32 v140, 1.0, v140
	v_add_f32_e32 v141, 1.0, v141
	v_rcp_f32_e32 v130, v130
	v_rcp_f32_e32 v131, v131
	v_rcp_f32_e32 v140, v140
	v_rcp_f32_e32 v141, v141
	v_pk_add_f32 v[136:137], v[136:137], v[90:91]
	v_lshlrev_b32_e32 v132, 16, v153
	v_and_b32_e32 v133, 0xffff0000, v153
	v_pk_add_f32 v[144:145], v[144:145], v[108:109]
	v_pk_fma_f32 v[136:137], v[136:137], v[130:131], v[132:133]
	v_pk_fma_f32 v[140:141], v[144:145], v[140:141], v[142:143]
	v_pk_mul_f32 v[130:131], v[134:135], v[134:135]
	v_pk_mul_f32 v[132:133], v[136:137], v[136:137]
	v_pk_mul_f32 v[142:143], v[138:139], v[138:139]
	v_pk_mul_f32 v[144:145], v[140:141], v[140:141]
	v_add_f32_e32 v132, v132, v133
	v_add_f32_e32 v130, v130, v131
	v_add_f32_e32 v130, v130, v132
	v_add_f32_e32 v131, v144, v145
	v_add_f32_e32 v132, v142, v143
	v_add_f32_e32 v131, v132, v131
	v_add_f32_e32 v142, v131, v130
	v_cvt_pk_bf16_f32 v130, v138, v139
	v_cvt_pk_bf16_f32 v131, v140, v141
	v_cvt_pk_bf16_f32 v132, v134, v135
	v_cvt_pk_bf16_f32 v133, v136, v137
	global_store_dwordx4 v[172:173], v[130:133], off
	ds_bpermute_b32 v130, v178, v142
	s_waitcnt lgkmcnt(0)
	v_add_f32_e32 v130, v142, v130
	v_mov_b32_e32 v131, v130
	v_mov_b32_e32 v245, v130
	s_nop 1
	v_permlane32_swap_b32_e32 v131, v245
	s_and_saveexec_b64 s[16:17], s[4:5]
	s_cbranch_execz .LBB0_268
	v_lshlrev_b64 v[132:133], 8, v[166:167]
	v_lshl_add_u64 v[132:133], s[14:15], 0, v[132:133]
	v_lshl_add_u64 v[132:133], s[52:53], 2, v[132:133]
	s_lshl_b32 s18, s37, 2
	v_lshl_add_u64 v[132:133], v[132:133], 0, s[18:19]
	s_waitcnt lgkmcnt(0)
	v_add_f32_e32 v130, v131, v245
	global_store_dword v[132:133], v130, off
; __device__ __forceinline__ unsigned pk2(float lo, float hi) { f32x2 v = {lo, hi}; bf16x2_t b = __builtin_convertvector(v, bf16x2_t); return __builtin_bit_cast(unsigned, b); }
; __device__ __forceinline__ float bflo(unsigned w) { return __uint_as_float(w << 16); }
; __device__ __forceinline__ float bfhi(unsigned w) { return __uint_as_float(w & 0xffff0000u); }
; __device__ __forceinline__ float fast_sigmoid(float g) { return __builtin_amdgcn_rcpf(1.0f + __expf(-g)); }
;     __device__ __forceinline__ void operator()(const f32x4 (&acc)[2][2][4][2], const Unit& u, int wr, int wc, int fr, int fq) const {
;     ...
;         for (int j = 0; j < 8; ++j) { const int ai = j >> 2, m = j & 3; const int row = row0 + ai * HALF + m * 16; const size_t off = (size_t)row * DM + col0; float ss = 0.f; f32x4 o[2];
;             if (j < 7) nxt = *(const u32x4*)(xb + (size_t)(row0 + ((j + 1) >> 2) * HALF + ((j + 1) & 3) * 16) * DM + col0);
; #pragma unroll
;             for (int n = 0; n < 2; ++n) {
;                 const f32x4 v = acc[ai][0][m][n] + (n ? bv1 : bv0), g = acc[ai][1][m][n] + (n ? bg1 : bg0);
;                 const unsigned w0 = n ? cur.z : cur.x, w1 = n ? cur.w : cur.y; o[n] = (f32x4){bflo(w0), bfhi(w0), bflo(w1), bfhi(w1)};
;                 o[n][0] += v[0] * fast_sigmoid(g[0]); o[n][1] += v[1] * fast_sigmoid(g[1]); o[n][2] += v[2] * fast_sigmoid(g[2]); o[n][3] += v[3] * fast_sigmoid(g[3]);
;                 ss += (o[n][0] * o[n][0] + o[n][1] * o[n][1]) + (o[n][2] * o[n][2] + o[n][3] * o[n][3]); }
;             { u32x4 w; w.x = pk2(o[0][0], o[0][1]); w.y = pk2(o[0][2], o[0][3]); w.z = pk2(o[1][0], o[1][1]); w.w = pk2(o[1][2], o[1][3]); *(u32x4*)(xb + off) = w; }
;             ss += __shfl_xor(ss, 16); ss += __shfl_xor(ss, 32); if (fq == 0) rsq[(size_t)row * 64 + u.pn * 4 + wc] = ss;
.LBB0_268:
	s_or_b64 exec, exec, s[16:17]
	v_or_b32_e32 v134, 32, v166
	v_ashrrev_i32_e32 v135, 31, v134
	s_waitcnt lgkmcnt(0)
	v_lshlrev_b64 v[130:131], 12, v[134:135]
	v_lshl_add_u64 v[130:131], s[12:13], 0, v[130:131]
	v_lshl_add_u64 v[136:137], v[164:165], 1, v[130:131]
	global_load_dwordx4 v[130:133], v[136:137], off
	v_pk_add_f32 v[122:123], v[122:123], v[102:103]
	v_pk_add_f32 v[114:115], v[114:115], v[84:85]
	v_mul_f32_e32 v122, 0xbfb8aa3b, v122
	v_exp_f32_e32 v138, v122
	v_mul_f32_e32 v122, 0xbfb8aa3b, v123
	v_exp_f32_e32 v139, v122
	v_pk_add_f32 v[122:123], v[124:125], v[104:105]
	v_add_f32_e32 v124, 1.0, v138
	v_rcp_f32_e32 v124, v124
	v_add_f32_e32 v125, 1.0, v139
	v_rcp_f32_e32 v125, v125
	v_pk_add_f32 v[126:127], v[126:127], v[106:107]
	v_lshlrev_b32_e32 v138, 16, v146
	v_and_b32_e32 v139, 0xffff0000, v146
	v_mul_f32_e32 v114, 0xbfb8aa3b, v114
	v_pk_fma_f32 v[124:125], v[126:127], v[124:125], v[138:139]
	v_exp_f32_e32 v138, v114
	v_mul_f32_e32 v114, 0xbfb8aa3b, v115
	v_exp_f32_e32 v139, v114
	v_pk_add_f32 v[114:115], v[116:117], v[86:87]
	v_mul_f32_e32 v122, 0xbfb8aa3b, v122
	v_mul_f32_e32 v114, 0xbfb8aa3b, v114
	v_mul_f32_e32 v115, 0xbfb8aa3b, v115
	v_mul_f32_e32 v123, 0xbfb8aa3b, v123
	v_exp_f32_e32 v114, v114
	v_exp_f32_e32 v115, v115
	v_exp_f32_e32 v122, v122
	v_exp_f32_e32 v123, v123
	v_add_f32_e32 v116, 1.0, v138
	v_add_f32_e32 v117, 1.0, v139
	v_rcp_f32_e32 v116, v116
	v_rcp_f32_e32 v117, v117
	v_add_f32_e32 v114, 1.0, v114
	v_add_f32_e32 v115, 1.0, v115
	v_add_f32_e32 v122, 1.0, v122
	v_add_f32_e32 v123, 1.0, v123
	v_rcp_f32_e32 v114, v114
	v_rcp_f32_e32 v115, v115
	v_rcp_f32_e32 v122, v122
	v_rcp_f32_e32 v123, v123
	v_pk_add_f32 v[118:119], v[118:119], v[88:89]
	v_lshlrev_b32_e32 v138, 16, v148
	v_and_b32_e32 v139, 0xffff0000, v148
	v_pk_add_f32 v[120:121], v[120:121], v[90:91]
	v_pk_fma_f32 v[118:119], v[118:119], v[116:117], v[138:139]
	v_lshlrev_b32_e32 v116, 16, v149
	v_and_b32_e32 v117, 0xffff0000, v149
	v_pk_add_f32 v[128:129], v[128:129], v[108:109]
	v_lshlrev_b32_e32 v126, 16, v147
	v_and_b32_e32 v127, 0xffff0000, v147
	v_pk_fma_f32 v[120:121], v[120:121], v[114:115], v[116:117]
	v_pk_fma_f32 v[122:123], v[128:129], v[122:123], v[126:127]
	v_pk_mul_f32 v[114:115], v[118:119], v[118:119]
	v_pk_mul_f32 v[116:117], v[120:121], v[120:121]
	v_pk_mul_f32 v[126:127], v[124:125], v[124:125]
	v_pk_mul_f32 v[128:129], v[122:123], v[122:123]
	v_add_f32_e32 v116, v116, v117
	v_add_f32_e32 v114, v114, v115
	v_add_f32_e32 v114, v114, v116
	v_add_f32_e32 v115, v128, v129
	v_add_f32_e32 v116, v126, v127
	v_add_f32_e32 v115, v116, v115
	v_add_f32_e32 v114, v115, v114
	ds_bpermute_b32 v115, v178, v114
	v_cvt_pk_bf16_f32 v116, v124, v125
	v_cvt_pk_bf16_f32 v117, v122, v123
	v_cvt_pk_bf16_f32 v118, v118, v119
	v_cvt_pk_bf16_f32 v119, v120, v121
	s_waitcnt lgkmcnt(0)
	v_add_f32_e32 v114, v114, v115
	v_mov_b32_e32 v115, v114
	v_mov_b32_e32 v245, v114
	s_nop 1
	v_permlane32_swap_b32_e32 v115, v245
	global_store_dwordx4 v[170:171], v[116:119], off
	s_and_saveexec_b64 s[16:17], s[4:5]
	s_cbranch_execz .LBB0_270
	v_lshlrev_b64 v[116:117], 8, v[168:169]
	v_lshl_add_u64 v[116:117], s[14:15], 0, v[116:117]
	v_lshl_add_u64 v[116:117], s[52:53], 2, v[116:117]
	s_lshl_b32 s18, s37, 2
	v_lshl_add_u64 v[116:117], v[116:117], 0, s[18:19]
	s_waitcnt lgkmcnt(0)
	v_add_f32_e32 v114, v115, v245
	global_store_dword v[116:117], v114, off
.LBB0_270:
	s_or_b64 exec, exec, s[16:17]
	v_or_b32_e32 v118, 48, v166
	v_ashrrev_i32_e32 v119, 31, v118
	s_waitcnt lgkmcnt(0)
	v_lshlrev_b64 v[114:115], 12, v[118:119]
	v_lshl_add_u64 v[114:115], s[12:13], 0, v[114:115]
	v_lshl_add_u64 v[120:121], v[164:165], 1, v[114:115]
	global_load_dwordx4 v[114:117], v[120:121], off
	v_pk_add_f32 v[98:99], v[98:99], v[102:103]
	v_pk_add_f32 v[80:81], v[80:81], v[84:85]
	v_mul_f32_e32 v98, 0xbfb8aa3b, v98
	v_exp_f32_e32 v122, v98
	v_mul_f32_e32 v98, 0xbfb8aa3b, v99
	v_exp_f32_e32 v123, v98
	v_pk_add_f32 v[98:99], v[100:101], v[104:105]
	v_add_f32_e32 v100, 1.0, v122
	v_rcp_f32_e32 v100, v100
	v_add_f32_e32 v101, 1.0, v123
	v_rcp_f32_e32 v101, v101
	v_pk_add_f32 v[110:111], v[110:111], v[106:107]
	s_waitcnt vmcnt(2)
	v_lshlrev_b32_e32 v122, 16, v130
	v_and_b32_e32 v123, 0xffff0000, v130
	v_mul_f32_e32 v80, 0xbfb8aa3b, v80
	v_pk_fma_f32 v[100:101], v[110:111], v[100:101], v[122:123]
	v_exp_f32_e32 v122, v80
	v_mul_f32_e32 v80, 0xbfb8aa3b, v81
	v_exp_f32_e32 v123, v80
	v_pk_add_f32 v[80:81], v[82:83], v[86:87]
	v_mul_f32_e32 v98, 0xbfb8aa3b, v98
	v_mul_f32_e32 v80, 0xbfb8aa3b, v80
	v_mul_f32_e32 v81, 0xbfb8aa3b, v81
	v_mul_f32_e32 v99, 0xbfb8aa3b, v99
	v_exp_f32_e32 v80, v80
	v_exp_f32_e32 v81, v81
	v_exp_f32_e32 v98, v98
	v_exp_f32_e32 v99, v99
	v_add_f32_e32 v82, 1.0, v122
	v_add_f32_e32 v83, 1.0, v123
	v_rcp_f32_e32 v82, v82
	v_rcp_f32_e32 v83, v83
	v_add_f32_e32 v80, 1.0, v80
	v_add_f32_e32 v81, 1.0, v81
	v_add_f32_e32 v98, 1.0, v98
	v_add_f32_e32 v99, 1.0, v99
	v_rcp_f32_e32 v80, v80
	v_rcp_f32_e32 v81, v81
	v_rcp_f32_e32 v98, v98
	v_rcp_f32_e32 v99, v99
	v_pk_add_f32 v[92:93], v[92:93], v[88:89]
	v_lshlrev_b32_e32 v122, 16, v132
	v_and_b32_e32 v123, 0xffff0000, v132
	v_pk_add_f32 v[94:95], v[94:95], v[90:91]
	v_pk_fma_f32 v[82:83], v[92:93], v[82:83], v[122:123]
	v_lshlrev_b32_e32 v92, 16, v133
	v_and_b32_e32 v93, 0xffff0000, v133
	v_pk_add_f32 v[112:113], v[112:113], v[108:109]
	v_lshlrev_b32_e32 v110, 16, v131
	v_and_b32_e32 v111, 0xffff0000, v131
	v_pk_fma_f32 v[122:123], v[94:95], v[80:81], v[92:93]
	v_pk_fma_f32 v[98:99], v[112:113], v[98:99], v[110:111]
	v_pk_mul_f32 v[80:81], v[82:83], v[82:83]
	v_pk_mul_f32 v[92:93], v[122:123], v[122:123]
	v_pk_mul_f32 v[110:111], v[100:101], v[100:101]
	v_pk_mul_f32 v[112:113], v[98:99], v[98:99]
	v_add_f32_e32 v92, v92, v93
	v_add_f32_e32 v80, v80, v81
	v_add_f32_e32 v80, v80, v92
	v_add_f32_e32 v81, v112, v113
	v_add_f32_e32 v92, v110, v111
	v_add_f32_e32 v81, v92, v81
	v_add_f32_e32 v80, v81, v80
	ds_bpermute_b32 v81, v178, v80
	v_cvt_pk_bf16_f32 v92, v100, v101
	v_cvt_pk_bf16_f32 v93, v98, v99
	v_cvt_pk_bf16_f32 v94, v82, v83
	v_cvt_pk_bf16_f32 v95, v122, v123
	s_waitcnt lgkmcnt(0)
	v_add_f32_e32 v80, v80, v81
	v_mov_b32_e32 v81, v80
	v_mov_b32_e32 v245, v80
	s_nop 1
	v_permlane32_swap_b32_e32 v81, v245
	global_store_dwordx4 v[136:137], v[92:95], off
	s_and_saveexec_b64 s[16:17], s[4:5]
	s_cbranch_execz .LBB0_272
	v_lshlrev_b64 v[82:83], 8, v[134:135]
	v_lshl_add_u64 v[82:83], s[14:15], 0, v[82:83]
	v_lshl_add_u64 v[82:83], s[52:53], 2, v[82:83]
	s_lshl_b32 s18, s37, 2
	v_lshl_add_u64 v[82:83], v[82:83], 0, s[18:19]
	s_waitcnt lgkmcnt(0)
	v_add_f32_e32 v80, v81, v245
	global_store_dword v[82:83], v80, off
; __device__ __forceinline__ unsigned pk2(float lo, float hi) { f32x2 v = {lo, hi}; bf16x2_t b = __builtin_convertvector(v, bf16x2_t); return __builtin_bit_cast(unsigned, b); }
; __device__ __forceinline__ float bflo(unsigned w) { return __uint_as_float(w << 16); }
; __device__ __forceinline__ float bfhi(unsigned w) { return __uint_as_float(w & 0xffff0000u); }
; __device__ __forceinline__ float fast_sigmoid(float g) { return __builtin_amdgcn_rcpf(1.0f + __expf(-g)); }
;     __device__ __forceinline__ void operator()(const f32x4 (&acc)[2][2][4][2], const Unit& u, int wr, int wc, int fr, int fq) const {
;     ...
;         for (int j = 0; j < 8; ++j) { const int ai = j >> 2, m = j & 3; const int row = row0 + ai * HALF + m * 16; const size_t off = (size_t)row * DM + col0; float ss = 0.f; f32x4 o[2];
;             if (j < 7) nxt = *(const u32x4*)(xb + (size_t)(row0 + ((j + 1) >> 2) * HALF + ((j + 1) & 3) * 16) * DM + col0);
; #pragma unroll
;             for (int n = 0; n < 2; ++n) {
;                 const f32x4 v = acc[ai][0][m][n] + (n ? bv1 : bv0), g = acc[ai][1][m][n] + (n ? bg1 : bg0);
;                 const unsigned w0 = n ? cur.z : cur.x, w1 = n ? cur.w : cur.y; o[n] = (f32x4){bflo(w0), bfhi(w0), bflo(w1), bfhi(w1)};
;                 o[n][0] += v[0] * fast_sigmoid(g[0]); o[n][1] += v[1] * fast_sigmoid(g[1]); o[n][2] += v[2] * fast_sigmoid(g[2]); o[n][3] += v[3] * fast_sigmoid(g[3]);
;                 ss += (o[n][0] * o[n][0] + o[n][1] * o[n][1]) + (o[n][2] * o[n][2] + o[n][3] * o[n][3]); }
;             { u32x4 w; w.x = pk2(o[0][0], o[0][1]); w.y = pk2(o[0][2], o[0][3]); w.z = pk2(o[1][0], o[1][1]); w.w = pk2(o[1][2], o[1][3]); *(u32x4*)(xb + off) = w; }
;             ss += __shfl_xor(ss, 16); ss += __shfl_xor(ss, 32); if (fq == 0) rsq[(size_t)row * 64 + u.pn * 4 + wc] = ss;
.LBB0_272:
	s_or_b64 exec, exec, s[16:17]
	v_add_u32_e32 v92, 0x80, v166
	v_ashrrev_i32_e32 v93, 31, v92
	s_waitcnt lgkmcnt(0)
	v_lshlrev_b64 v[80:81], 12, v[92:93]
	v_lshl_add_u64 v[80:81], s[12:13], 0, v[80:81]
	v_lshl_add_u64 v[94:95], v[164:165], 1, v[80:81]
	global_load_dwordx4 v[80:83], v[94:95], off
	v_pk_add_f32 v[72:73], v[72:73], v[102:103]
	v_pk_add_f32 v[64:65], v[64:65], v[84:85]
	v_mul_f32_e32 v72, 0xbfb8aa3b, v72
	v_exp_f32_e32 v98, v72
	v_mul_f32_e32 v72, 0xbfb8aa3b, v73
	v_exp_f32_e32 v99, v72
	v_pk_add_f32 v[72:73], v[74:75], v[104:105]
	v_add_f32_e32 v74, 1.0, v98
	v_rcp_f32_e32 v74, v74
	v_add_f32_e32 v75, 1.0, v99
	v_rcp_f32_e32 v75, v75
	v_pk_add_f32 v[76:77], v[76:77], v[106:107]
	s_waitcnt vmcnt(2)
	v_lshlrev_b32_e32 v98, 16, v114
	v_and_b32_e32 v99, 0xffff0000, v114
	v_mul_f32_e32 v64, 0xbfb8aa3b, v64
	v_pk_fma_f32 v[74:75], v[76:77], v[74:75], v[98:99]
	v_exp_f32_e32 v98, v64
	v_mul_f32_e32 v64, 0xbfb8aa3b, v65
	v_exp_f32_e32 v99, v64
	v_pk_add_f32 v[64:65], v[66:67], v[86:87]
	v_mul_f32_e32 v72, 0xbfb8aa3b, v72
	v_mul_f32_e32 v64, 0xbfb8aa3b, v64
	v_mul_f32_e32 v65, 0xbfb8aa3b, v65
	v_mul_f32_e32 v73, 0xbfb8aa3b, v73
	v_exp_f32_e32 v64, v64
	v_exp_f32_e32 v65, v65
	v_exp_f32_e32 v72, v72
	v_exp_f32_e32 v73, v73
	v_add_f32_e32 v66, 1.0, v98
	v_add_f32_e32 v67, 1.0, v99
	v_rcp_f32_e32 v66, v66
	v_rcp_f32_e32 v67, v67
	v_add_f32_e32 v64, 1.0, v64
	v_add_f32_e32 v65, 1.0, v65
	v_add_f32_e32 v72, 1.0, v72
	v_add_f32_e32 v73, 1.0, v73
	v_rcp_f32_e32 v64, v64
	v_rcp_f32_e32 v65, v65
	v_rcp_f32_e32 v72, v72
	v_rcp_f32_e32 v73, v73
	v_pk_add_f32 v[68:69], v[68:69], v[88:89]
	v_lshlrev_b32_e32 v98, 16, v116
	v_and_b32_e32 v99, 0xffff0000, v116
	v_pk_add_f32 v[70:71], v[70:71], v[90:91]
	v_pk_fma_f32 v[68:69], v[68:69], v[66:67], v[98:99]
	v_lshlrev_b32_e32 v66, 16, v117
	v_and_b32_e32 v67, 0xffff0000, v117
	v_pk_add_f32 v[78:79], v[78:79], v[108:109]
	v_lshlrev_b32_e32 v76, 16, v115
	v_and_b32_e32 v77, 0xffff0000, v115
	v_pk_fma_f32 v[70:71], v[70:71], v[64:65], v[66:67]
	v_pk_fma_f32 v[72:73], v[78:79], v[72:73], v[76:77]
	v_pk_mul_f32 v[64:65], v[68:69], v[68:69]
	v_pk_mul_f32 v[66:67], v[70:71], v[70:71]
	v_pk_mul_f32 v[76:77], v[74:75], v[74:75]
	v_pk_mul_f32 v[78:79], v[72:73], v[72:73]
	v_add_f32_e32 v66, v66, v67
	v_add_f32_e32 v64, v64, v65
	v_add_f32_e32 v64, v64, v66
	v_add_f32_e32 v65, v78, v79
	v_add_f32_e32 v66, v76, v77
	v_add_f32_e32 v65, v66, v65
	v_add_f32_e32 v64, v65, v64
	ds_bpermute_b32 v65, v178, v64
	v_cvt_pk_bf16_f32 v66, v74, v75
	v_cvt_pk_bf16_f32 v67, v72, v73
	v_cvt_pk_bf16_f32 v68, v68, v69
	v_cvt_pk_bf16_f32 v69, v70, v71
	s_waitcnt lgkmcnt(0)
	v_add_f32_e32 v64, v64, v65
	v_mov_b32_e32 v65, v64
	v_mov_b32_e32 v245, v64
	s_nop 1
	v_permlane32_swap_b32_e32 v65, v245
	global_store_dwordx4 v[120:121], v[66:69], off
	s_and_saveexec_b64 s[16:17], s[4:5]
	s_cbranch_execz .LBB0_274
	v_lshlrev_b64 v[66:67], 8, v[118:119]
	v_lshl_add_u64 v[66:67], s[14:15], 0, v[66:67]
	v_lshl_add_u64 v[66:67], s[52:53], 2, v[66:67]
	s_lshl_b32 s18, s37, 2
	v_lshl_add_u64 v[66:67], v[66:67], 0, s[18:19]
	s_waitcnt lgkmcnt(0)
	v_add_f32_e32 v64, v65, v245
	global_store_dword v[66:67], v64, off
.LBB0_274:
	s_or_b64 exec, exec, s[16:17]
	v_or_b32_e32 v68, 16, v92
	v_ashrrev_i32_e32 v69, 31, v68
	s_waitcnt lgkmcnt(0)
	v_lshlrev_b64 v[64:65], 12, v[68:69]
	v_lshl_add_u64 v[64:65], s[12:13], 0, v[64:65]
	v_lshl_add_u64 v[70:71], v[164:165], 1, v[64:65]
	global_load_dwordx4 v[64:67], v[70:71], off
	v_pk_add_f32 v[56:57], v[56:57], v[102:103]
	v_pk_add_f32 v[48:49], v[48:49], v[84:85]
	v_mul_f32_e32 v56, 0xbfb8aa3b, v56
	v_exp_f32_e32 v72, v56
	v_mul_f32_e32 v56, 0xbfb8aa3b, v57
	v_exp_f32_e32 v73, v56
	v_pk_add_f32 v[56:57], v[58:59], v[104:105]
	v_add_f32_e32 v58, 1.0, v72
	v_rcp_f32_e32 v58, v58
	v_add_f32_e32 v59, 1.0, v73
	v_rcp_f32_e32 v59, v59
	v_pk_add_f32 v[60:61], v[60:61], v[106:107]
	s_waitcnt vmcnt(2)
	v_lshlrev_b32_e32 v72, 16, v80
	v_and_b32_e32 v73, 0xffff0000, v80
	v_mul_f32_e32 v48, 0xbfb8aa3b, v48
	v_pk_fma_f32 v[58:59], v[60:61], v[58:59], v[72:73]
	v_exp_f32_e32 v72, v48
	v_mul_f32_e32 v48, 0xbfb8aa3b, v49
	v_exp_f32_e32 v73, v48
	v_pk_add_f32 v[48:49], v[50:51], v[86:87]
	v_mul_f32_e32 v56, 0xbfb8aa3b, v56
	v_mul_f32_e32 v48, 0xbfb8aa3b, v48
	v_mul_f32_e32 v49, 0xbfb8aa3b, v49
	v_mul_f32_e32 v57, 0xbfb8aa3b, v57
	v_exp_f32_e32 v48, v48
	v_exp_f32_e32 v49, v49
	v_exp_f32_e32 v56, v56
	v_exp_f32_e32 v57, v57
	v_add_f32_e32 v50, 1.0, v72
	v_add_f32_e32 v51, 1.0, v73
	v_rcp_f32_e32 v50, v50
	v_rcp_f32_e32 v51, v51
	v_add_f32_e32 v48, 1.0, v48
	v_add_f32_e32 v49, 1.0, v49
	v_add_f32_e32 v56, 1.0, v56
	v_add_f32_e32 v57, 1.0, v57
	v_rcp_f32_e32 v48, v48
	v_rcp_f32_e32 v49, v49
	v_rcp_f32_e32 v56, v56
	v_rcp_f32_e32 v57, v57
	v_pk_add_f32 v[52:53], v[52:53], v[88:89]
	v_lshlrev_b32_e32 v72, 16, v82
	v_and_b32_e32 v73, 0xffff0000, v82
	v_pk_add_f32 v[54:55], v[54:55], v[90:91]
	v_pk_fma_f32 v[52:53], v[52:53], v[50:51], v[72:73]
	v_lshlrev_b32_e32 v50, 16, v83
	v_and_b32_e32 v51, 0xffff0000, v83
	v_pk_add_f32 v[62:63], v[62:63], v[108:109]
	v_lshlrev_b32_e32 v60, 16, v81
	v_and_b32_e32 v61, 0xffff0000, v81
	v_pk_fma_f32 v[54:55], v[54:55], v[48:49], v[50:51]
	v_pk_fma_f32 v[56:57], v[62:63], v[56:57], v[60:61]
	v_pk_mul_f32 v[48:49], v[52:53], v[52:53]
	v_pk_mul_f32 v[50:51], v[54:55], v[54:55]
	v_pk_mul_f32 v[60:61], v[58:59], v[58:59]
	v_pk_mul_f32 v[62:63], v[56:57], v[56:57]
	v_add_f32_e32 v50, v50, v51
	v_add_f32_e32 v48, v48, v49
	v_add_f32_e32 v48, v48, v50
	v_add_f32_e32 v49, v62, v63
	v_add_f32_e32 v50, v60, v61
	v_add_f32_e32 v49, v50, v49
	v_add_f32_e32 v48, v49, v48
	ds_bpermute_b32 v49, v178, v48
	v_cvt_pk_bf16_f32 v50, v58, v59
	v_cvt_pk_bf16_f32 v51, v56, v57
	v_cvt_pk_bf16_f32 v52, v52, v53
	v_cvt_pk_bf16_f32 v53, v54, v55
	s_waitcnt lgkmcnt(0)
	v_add_f32_e32 v48, v48, v49
	v_mov_b32_e32 v49, v48
	v_mov_b32_e32 v245, v48
	s_nop 1
	v_permlane32_swap_b32_e32 v49, v245
	global_store_dwordx4 v[94:95], v[50:53], off
	s_and_saveexec_b64 s[16:17], s[4:5]
	s_cbranch_execz .LBB0_276
	v_lshlrev_b64 v[50:51], 8, v[92:93]
	v_lshl_add_u64 v[50:51], s[14:15], 0, v[50:51]
	v_lshl_add_u64 v[50:51], s[52:53], 2, v[50:51]
	s_lshl_b32 s18, s37, 2
	v_lshl_add_u64 v[50:51], v[50:51], 0, s[18:19]
	s_waitcnt lgkmcnt(0)
	v_add_f32_e32 v48, v49, v245
	global_store_dword v[50:51], v48, off
; __device__ __forceinline__ unsigned pk2(float lo, float hi) { f32x2 v = {lo, hi}; bf16x2_t b = __builtin_convertvector(v, bf16x2_t); return __builtin_bit_cast(unsigned, b); }
; __device__ __forceinline__ float bflo(unsigned w) { return __uint_as_float(w << 16); }
; __device__ __forceinline__ float bfhi(unsigned w) { return __uint_as_float(w & 0xffff0000u); }
; __device__ __forceinline__ float fast_sigmoid(float g) { return __builtin_amdgcn_rcpf(1.0f + __expf(-g)); }
;     __device__ __forceinline__ void operator()(const f32x4 (&acc)[2][2][4][2], const Unit& u, int wr, int wc, int fr, int fq) const {
;     ...
;         for (int j = 0; j < 8; ++j) { const int ai = j >> 2, m = j & 3; const int row = row0 + ai * HALF + m * 16; const size_t off = (size_t)row * DM + col0; float ss = 0.f; f32x4 o[2];
;             if (j < 7) nxt = *(const u32x4*)(xb + (size_t)(row0 + ((j + 1) >> 2) * HALF + ((j + 1) & 3) * 16) * DM + col0);
; #pragma unroll
;             for (int n = 0; n < 2; ++n) {
;                 const f32x4 v = acc[ai][0][m][n] + (n ? bv1 : bv0), g = acc[ai][1][m][n] + (n ? bg1 : bg0);
;                 const unsigned w0 = n ? cur.z : cur.x, w1 = n ? cur.w : cur.y; o[n] = (f32x4){bflo(w0), bfhi(w0), bflo(w1), bfhi(w1)};
;                 o[n][0] += v[0] * fast_sigmoid(g[0]); o[n][1] += v[1] * fast_sigmoid(g[1]); o[n][2] += v[2] * fast_sigmoid(g[2]); o[n][3] += v[3] * fast_sigmoid(g[3]);
;                 ss += (o[n][0] * o[n][0] + o[n][1] * o[n][1]) + (o[n][2] * o[n][2] + o[n][3] * o[n][3]); }
;             { u32x4 w; w.x = pk2(o[0][0], o[0][1]); w.y = pk2(o[0][2], o[0][3]); w.z = pk2(o[1][0], o[1][1]); w.w = pk2(o[1][2], o[1][3]); *(u32x4*)(xb + off) = w; }
;             ss += __shfl_xor(ss, 16); ss += __shfl_xor(ss, 32); if (fq == 0) rsq[(size_t)row * 64 + u.pn * 4 + wc] = ss;
.LBB0_276:
	s_or_b64 exec, exec, s[16:17]
	v_or_b32_e32 v52, 32, v92
	v_ashrrev_i32_e32 v53, 31, v52
	s_waitcnt lgkmcnt(0)
	v_lshlrev_b64 v[48:49], 12, v[52:53]
	v_lshl_add_u64 v[48:49], s[12:13], 0, v[48:49]
	v_lshl_add_u64 v[54:55], v[164:165], 1, v[48:49]
	global_load_dwordx4 v[48:51], v[54:55], off
	v_pk_add_f32 v[40:41], v[40:41], v[102:103]
	v_pk_add_f32 v[32:33], v[32:33], v[84:85]
	v_mul_f32_e32 v40, 0xbfb8aa3b, v40
	v_exp_f32_e32 v56, v40
	v_mul_f32_e32 v40, 0xbfb8aa3b, v41
	v_exp_f32_e32 v57, v40
	v_pk_add_f32 v[40:41], v[42:43], v[104:105]
	v_add_f32_e32 v42, 1.0, v56
	v_rcp_f32_e32 v42, v42
	v_add_f32_e32 v43, 1.0, v57
	v_rcp_f32_e32 v43, v43
	v_pk_add_f32 v[44:45], v[44:45], v[106:107]
	s_waitcnt vmcnt(2)
	v_lshlrev_b32_e32 v56, 16, v64
	v_and_b32_e32 v57, 0xffff0000, v64
	v_mul_f32_e32 v32, 0xbfb8aa3b, v32
	v_pk_fma_f32 v[42:43], v[44:45], v[42:43], v[56:57]
	v_exp_f32_e32 v56, v32
	v_mul_f32_e32 v32, 0xbfb8aa3b, v33
	v_exp_f32_e32 v57, v32
	v_pk_add_f32 v[32:33], v[34:35], v[86:87]
	v_mul_f32_e32 v40, 0xbfb8aa3b, v40
	v_mul_f32_e32 v32, 0xbfb8aa3b, v32
	v_mul_f32_e32 v33, 0xbfb8aa3b, v33
	v_mul_f32_e32 v41, 0xbfb8aa3b, v41
	v_exp_f32_e32 v32, v32
	v_exp_f32_e32 v33, v33
	v_exp_f32_e32 v40, v40
	v_exp_f32_e32 v41, v41
	v_add_f32_e32 v34, 1.0, v56
	v_add_f32_e32 v35, 1.0, v57
	v_rcp_f32_e32 v34, v34
	v_rcp_f32_e32 v35, v35
	v_add_f32_e32 v32, 1.0, v32
	v_add_f32_e32 v33, 1.0, v33
	v_add_f32_e32 v40, 1.0, v40
	v_add_f32_e32 v41, 1.0, v41
	v_rcp_f32_e32 v32, v32
	v_rcp_f32_e32 v33, v33
	v_rcp_f32_e32 v40, v40
	v_rcp_f32_e32 v41, v41
	v_pk_add_f32 v[36:37], v[36:37], v[88:89]
	v_lshlrev_b32_e32 v56, 16, v66
	v_and_b32_e32 v57, 0xffff0000, v66
	v_pk_add_f32 v[38:39], v[38:39], v[90:91]
	v_pk_fma_f32 v[36:37], v[36:37], v[34:35], v[56:57]
	v_lshlrev_b32_e32 v34, 16, v67
	v_and_b32_e32 v35, 0xffff0000, v67
	v_pk_add_f32 v[46:47], v[46:47], v[108:109]
	v_lshlrev_b32_e32 v44, 16, v65
	v_and_b32_e32 v45, 0xffff0000, v65
	v_pk_fma_f32 v[38:39], v[38:39], v[32:33], v[34:35]
	v_pk_fma_f32 v[40:41], v[46:47], v[40:41], v[44:45]
	v_pk_mul_f32 v[32:33], v[36:37], v[36:37]
	v_pk_mul_f32 v[34:35], v[38:39], v[38:39]
	v_pk_mul_f32 v[44:45], v[42:43], v[42:43]
	v_pk_mul_f32 v[46:47], v[40:41], v[40:41]
	v_add_f32_e32 v34, v34, v35
	v_add_f32_e32 v32, v32, v33
	v_add_f32_e32 v32, v32, v34
	v_add_f32_e32 v33, v46, v47
	v_add_f32_e32 v34, v44, v45
	v_add_f32_e32 v33, v34, v33
	v_add_f32_e32 v32, v33, v32
	ds_bpermute_b32 v33, v178, v32
	v_cvt_pk_bf16_f32 v34, v42, v43
	v_cvt_pk_bf16_f32 v35, v40, v41
	v_cvt_pk_bf16_f32 v36, v36, v37
	v_cvt_pk_bf16_f32 v37, v38, v39
	s_waitcnt lgkmcnt(0)
	v_add_f32_e32 v32, v32, v33
	v_mov_b32_e32 v33, v32
	v_mov_b32_e32 v245, v32
	s_nop 1
	v_permlane32_swap_b32_e32 v33, v245
	global_store_dwordx4 v[70:71], v[34:37], off
	s_and_saveexec_b64 s[16:17], s[4:5]
	s_cbranch_execz .LBB0_278
	v_lshlrev_b64 v[34:35], 8, v[68:69]
	v_lshl_add_u64 v[34:35], s[14:15], 0, v[34:35]
	v_lshl_add_u64 v[34:35], s[52:53], 2, v[34:35]
	s_lshl_b32 s18, s37, 2
	v_lshl_add_u64 v[34:35], v[34:35], 0, s[18:19]
	s_waitcnt lgkmcnt(0)
	v_add_f32_e32 v32, v33, v245
	global_store_dword v[34:35], v32, off
; __device__ __forceinline__ unsigned pk2(float lo, float hi) { f32x2 v = {lo, hi}; bf16x2_t b = __builtin_convertvector(v, bf16x2_t); return __builtin_bit_cast(unsigned, b); }
; __device__ __forceinline__ float bflo(unsigned w) { return __uint_as_float(w << 16); }
; __device__ __forceinline__ float bfhi(unsigned w) { return __uint_as_float(w & 0xffff0000u); }
; __device__ __forceinline__ float fast_sigmoid(float g) { return __builtin_amdgcn_rcpf(1.0f + __expf(-g)); }
;     __device__ __forceinline__ void operator()(const f32x4 (&acc)[2][2][4][2], const Unit& u, int wr, int wc, int fr, int fq) const {
;     ...
;         for (int j = 0; j < 8; ++j) { const int ai = j >> 2, m = j & 3; const int row = row0 + ai * HALF + m * 16; const size_t off = (size_t)row * DM + col0; float ss = 0.f; f32x4 o[2];
;             if (j < 7) nxt = *(const u32x4*)(xb + (size_t)(row0 + ((j + 1) >> 2) * HALF + ((j + 1) & 3) * 16) * DM + col0);
; #pragma unroll
;             for (int n = 0; n < 2; ++n) {
;                 const f32x4 v = acc[ai][0][m][n] + (n ? bv1 : bv0), g = acc[ai][1][m][n] + (n ? bg1 : bg0);
;                 const unsigned w0 = n ? cur.z : cur.x, w1 = n ? cur.w : cur.y; o[n] = (f32x4){bflo(w0), bfhi(w0), bflo(w1), bfhi(w1)};
;                 o[n][0] += v[0] * fast_sigmoid(g[0]); o[n][1] += v[1] * fast_sigmoid(g[1]); o[n][2] += v[2] * fast_sigmoid(g[2]); o[n][3] += v[3] * fast_sigmoid(g[3]);
;                 ss += (o[n][0] * o[n][0] + o[n][1] * o[n][1]) + (o[n][2] * o[n][2] + o[n][3] * o[n][3]); }
;             { u32x4 w; w.x = pk2(o[0][0], o[0][1]); w.y = pk2(o[0][2], o[0][3]); w.z = pk2(o[1][0], o[1][1]); w.w = pk2(o[1][2], o[1][3]); *(u32x4*)(xb + off) = w; }
;             ss += __shfl_xor(ss, 16); ss += __shfl_xor(ss, 32); if (fq == 0) rsq[(size_t)row * 64 + u.pn * 4 + wc] = ss;
.LBB0_278:
	s_or_b64 exec, exec, s[16:17]
	v_or_b32_e32 v36, 48, v92
	v_ashrrev_i32_e32 v37, 31, v36
	s_waitcnt lgkmcnt(0)
	v_lshlrev_b64 v[32:33], 12, v[36:37]
	v_lshl_add_u64 v[32:33], s[12:13], 0, v[32:33]
	v_lshl_add_u64 v[38:39], v[164:165], 1, v[32:33]
	global_load_dwordx4 v[32:35], v[38:39], off
	v_pk_add_f32 v[24:25], v[24:25], v[102:103]
	v_pk_add_f32 v[16:17], v[16:17], v[84:85]
	v_mul_f32_e32 v24, 0xbfb8aa3b, v24
	v_exp_f32_e32 v40, v24
	v_mul_f32_e32 v24, 0xbfb8aa3b, v25
	v_exp_f32_e32 v41, v24
	v_pk_add_f32 v[24:25], v[26:27], v[104:105]
	v_add_f32_e32 v26, 1.0, v40
	v_rcp_f32_e32 v26, v26
	v_add_f32_e32 v27, 1.0, v41
	v_rcp_f32_e32 v27, v27
	v_pk_add_f32 v[28:29], v[28:29], v[106:107]
	s_waitcnt vmcnt(2)
	v_lshlrev_b32_e32 v40, 16, v48
	v_and_b32_e32 v41, 0xffff0000, v48
	v_mul_f32_e32 v16, 0xbfb8aa3b, v16
	v_pk_fma_f32 v[26:27], v[28:29], v[26:27], v[40:41]
	v_exp_f32_e32 v40, v16
	v_mul_f32_e32 v16, 0xbfb8aa3b, v17
	v_exp_f32_e32 v41, v16
	v_pk_add_f32 v[16:17], v[18:19], v[86:87]
	v_mul_f32_e32 v24, 0xbfb8aa3b, v24
	v_mul_f32_e32 v16, 0xbfb8aa3b, v16
	v_mul_f32_e32 v17, 0xbfb8aa3b, v17
	v_mul_f32_e32 v25, 0xbfb8aa3b, v25
	v_exp_f32_e32 v16, v16
	v_exp_f32_e32 v17, v17
	v_exp_f32_e32 v24, v24
	v_exp_f32_e32 v25, v25
	v_add_f32_e32 v18, 1.0, v40
	v_add_f32_e32 v19, 1.0, v41
	v_rcp_f32_e32 v18, v18
	v_rcp_f32_e32 v19, v19
	v_add_f32_e32 v16, 1.0, v16
	v_add_f32_e32 v17, 1.0, v17
	v_add_f32_e32 v24, 1.0, v24
	v_add_f32_e32 v25, 1.0, v25
	v_rcp_f32_e32 v16, v16
	v_rcp_f32_e32 v17, v17
	v_rcp_f32_e32 v24, v24
	v_rcp_f32_e32 v25, v25
	v_pk_add_f32 v[20:21], v[20:21], v[88:89]
	v_lshlrev_b32_e32 v40, 16, v50
	v_and_b32_e32 v41, 0xffff0000, v50
	v_pk_add_f32 v[22:23], v[22:23], v[90:91]
	v_pk_fma_f32 v[20:21], v[20:21], v[18:19], v[40:41]
	v_lshlrev_b32_e32 v18, 16, v51
	v_and_b32_e32 v19, 0xffff0000, v51
	v_pk_add_f32 v[30:31], v[30:31], v[108:109]
	v_lshlrev_b32_e32 v28, 16, v49
	v_and_b32_e32 v29, 0xffff0000, v49
	v_pk_fma_f32 v[22:23], v[22:23], v[16:17], v[18:19]
	v_pk_fma_f32 v[24:25], v[30:31], v[24:25], v[28:29]
	v_pk_mul_f32 v[16:17], v[20:21], v[20:21]
	v_pk_mul_f32 v[18:19], v[22:23], v[22:23]
	v_pk_mul_f32 v[28:29], v[26:27], v[26:27]
	v_pk_mul_f32 v[30:31], v[24:25], v[24:25]
	v_add_f32_e32 v18, v18, v19
	v_add_f32_e32 v16, v16, v17
	v_add_f32_e32 v16, v16, v18
	v_add_f32_e32 v17, v30, v31
	v_add_f32_e32 v18, v28, v29
	v_add_f32_e32 v17, v18, v17
	v_add_f32_e32 v16, v17, v16
	ds_bpermute_b32 v17, v178, v16
	v_cvt_pk_bf16_f32 v18, v26, v27
	v_cvt_pk_bf16_f32 v19, v24, v25
	v_cvt_pk_bf16_f32 v20, v20, v21
	v_cvt_pk_bf16_f32 v21, v22, v23
	s_waitcnt lgkmcnt(0)
	v_add_f32_e32 v16, v16, v17
	v_mov_b32_e32 v17, v16
	v_mov_b32_e32 v245, v16
	s_nop 1
	v_permlane32_swap_b32_e32 v17, v245
	global_store_dwordx4 v[54:55], v[18:21], off
	s_and_saveexec_b64 s[16:17], s[4:5]
	s_cbranch_execz .LBB0_280
	v_lshlrev_b64 v[18:19], 8, v[52:53]
	v_lshl_add_u64 v[18:19], s[14:15], 0, v[18:19]
	v_lshl_add_u64 v[18:19], s[52:53], 2, v[18:19]
	s_lshl_b32 s18, s37, 2
	v_lshl_add_u64 v[18:19], v[18:19], 0, s[18:19]
	s_waitcnt lgkmcnt(0)
	v_add_f32_e32 v16, v17, v245
	global_store_dword v[18:19], v16, off
.LBB0_280:
	s_or_b64 exec, exec, s[16:17]
	v_pk_add_f32 v[8:9], v[8:9], v[102:103]
	v_pk_add_f32 v[0:1], v[0:1], v[84:85]
	v_mul_f32_e32 v8, 0xbfb8aa3b, v8
	v_exp_f32_e32 v16, v8
	v_mul_f32_e32 v8, 0xbfb8aa3b, v9
	s_waitcnt lgkmcnt(0)
	v_exp_f32_e32 v17, v8
	v_pk_add_f32 v[8:9], v[10:11], v[104:105]
	v_add_f32_e32 v10, 1.0, v16
	v_rcp_f32_e32 v10, v10
	v_add_f32_e32 v11, 1.0, v17
	v_rcp_f32_e32 v11, v11
	v_pk_add_f32 v[12:13], v[12:13], v[106:107]
	s_waitcnt vmcnt(1)
	v_lshlrev_b32_e32 v16, 16, v32
	v_and_b32_e32 v17, 0xffff0000, v32
	v_mul_f32_e32 v0, 0xbfb8aa3b, v0
	v_pk_fma_f32 v[10:11], v[12:13], v[10:11], v[16:17]
	v_exp_f32_e32 v16, v0
	v_mul_f32_e32 v0, 0xbfb8aa3b, v1
	v_exp_f32_e32 v17, v0
	v_pk_add_f32 v[0:1], v[2:3], v[86:87]
	v_mul_f32_e32 v8, 0xbfb8aa3b, v8
	v_mul_f32_e32 v0, 0xbfb8aa3b, v0
	v_mul_f32_e32 v1, 0xbfb8aa3b, v1
	v_mul_f32_e32 v9, 0xbfb8aa3b, v9
	v_exp_f32_e32 v0, v0
	v_exp_f32_e32 v1, v1
	v_exp_f32_e32 v8, v8
	v_exp_f32_e32 v9, v9
	v_add_f32_e32 v2, 1.0, v16
	v_add_f32_e32 v3, 1.0, v17
	v_rcp_f32_e32 v2, v2
	v_rcp_f32_e32 v3, v3
	v_add_f32_e32 v0, 1.0, v0
	v_add_f32_e32 v1, 1.0, v1
	v_add_f32_e32 v8, 1.0, v8
	v_add_f32_e32 v9, 1.0, v9
	v_rcp_f32_e32 v0, v0
	v_rcp_f32_e32 v1, v1
	v_rcp_f32_e32 v8, v8
	v_rcp_f32_e32 v9, v9
	v_pk_add_f32 v[4:5], v[4:5], v[88:89]
	v_lshlrev_b32_e32 v16, 16, v34
	v_and_b32_e32 v17, 0xffff0000, v34
	v_pk_add_f32 v[6:7], v[6:7], v[90:91]
	v_pk_fma_f32 v[4:5], v[4:5], v[2:3], v[16:17]
	v_lshlrev_b32_e32 v2, 16, v35
	v_and_b32_e32 v3, 0xffff0000, v35
	v_pk_add_f32 v[14:15], v[14:15], v[108:109]
	v_lshlrev_b32_e32 v12, 16, v33
	v_and_b32_e32 v13, 0xffff0000, v33
	v_pk_fma_f32 v[6:7], v[6:7], v[0:1], v[2:3]
	v_pk_fma_f32 v[8:9], v[14:15], v[8:9], v[12:13]
	v_pk_mul_f32 v[0:1], v[4:5], v[4:5]
	v_pk_mul_f32 v[2:3], v[6:7], v[6:7]
	v_pk_mul_f32 v[12:13], v[10:11], v[10:11]
	v_pk_mul_f32 v[14:15], v[8:9], v[8:9]
	v_add_f32_e32 v2, v2, v3
	v_add_f32_e32 v0, v0, v1
	v_add_f32_e32 v0, v0, v2
	v_add_f32_e32 v1, v14, v15
	v_add_f32_e32 v2, v12, v13
	v_add_f32_e32 v1, v2, v1
	v_add_f32_e32 v0, v1, v0
	ds_bpermute_b32 v1, v178, v0
	v_cvt_pk_bf16_f32 v2, v10, v11
	v_cvt_pk_bf16_f32 v3, v8, v9
	v_cvt_pk_bf16_f32 v4, v4, v5
	s_waitcnt lgkmcnt(0)
	v_add_f32_e32 v0, v0, v1
	v_mov_b32_e32 v1, v0
	v_mov_b32_e32 v245, v0
	s_nop 1
	v_permlane32_swap_b32_e32 v1, v245
	v_cvt_pk_bf16_f32 v5, v6, v7
	global_store_dwordx4 v[38:39], v[2:5], off
	s_and_saveexec_b64 s[16:17], s[4:5]
	s_cbranch_execz .LBB0_282
	v_lshlrev_b64 v[2:3], 8, v[36:37]
	v_lshl_add_u64 v[2:3], s[14:15], 0, v[2:3]
	v_lshl_add_u64 v[2:3], s[52:53], 2, v[2:3]
	s_lshl_b32 s18, s37, 2
	v_lshl_add_u64 v[2:3], v[2:3], 0, s[18:19]
	s_waitcnt lgkmcnt(0)
	v_add_f32_e32 v0, v1, v245
	global_store_dword v[2:3], v0, off

; __device__ __forceinline__ unsigned pk2(float lo, float hi) { f32x2 v = {lo, hi}; bf16x2_t b = __builtin_convertvector(v, bf16x2_t); return __builtin_bit_cast(unsigned, b); }
; __device__ __forceinline__ float bflo(unsigned w) { return __uint_as_float(w << 16); }
; __device__ __forceinline__ float bfhi(unsigned w) { return __uint_as_float(w & 0xffff0000u); }
;     __device__ __forceinline__ void operator()(const f32x4 (&acc)[2][2][4][2], const Unit& u, int wr, int wc, int fr, int fq) const {
;     ...
;         for (int j = 0; j < 8; ++j) { const int ai = j >> 2, m = j & 3; const int row = row0 + ai * HALF + m * 16; const size_t off = (size_t)row * DM + col0; float ss = 0.f;
;             if (MODE < 3 && j < 6) ldgrp(nx2, (size_t)(row0 + ((j + 2) >> 2) * HALF + ((j + 2) & 3) * 16) * DM + col0);
; #pragma unroll
;             for (int bj = 0; bj < 2; ++bj) { f32x4 o[2];
; #pragma unroll
;                 for (int n = 0; n < 2; ++n) { const int cc = bj * HALF + 4 * n;
;                     f32x4 v = acc[ai][bj][m][n];
;                     if (bias) { v = (v + *(const f32x4*)(bias + col0 + cc)) * *(const f32x4*)(scale + col0 + cc); }
;                     f32x4 b;
;                     if (MODE >= 3) b = (f32x4){0.f, 0.f, 0.f, 0.f};
;                     else if (MODE == 0) b = __builtin_bit_cast(f32x4, cur[bj][n]);
;                     else { const unsigned w0 = n ? cur[bj][0].z : cur[bj][0].x, w1 = n ? cur[bj][0].w : cur[bj][0].y; b = (f32x4){bflo(w0), bfhi(w0), bflo(w1), bfhi(w1)}; }
;                     o[n] = b + v;
;                     if (MODE == 2 || MODE == 4) *(f32x4*)(out + off + cc) = o[n];
;                     ss += (o[n][0] * o[n][0] + o[n][1] * o[n][1]) + (o[n][2] * o[n][2] + o[n][3] * o[n][3]); }
;                 if (MODE != 2 && MODE != 4) { u32x4 w; w.x = pk2(o[0][0], o[0][1]); w.y = pk2(o[0][2], o[0][3]); w.z = pk2(o[1][0], o[1][1]); w.w = pk2(o[1][2], o[1][3]); *(u32x4*)(xb + off + bj * HALF) = w; } }
;             if (MODE != 2 && MODE != 4 && rsq) { ss += __shfl_xor(ss, 16); ss += __shfl_xor(ss, 32); if (fq == 0) rsq[(size_t)row * 64 + u.pn * 4 + wc] = ss; }
.LBB0_569:
	v_lshl_add_u32 v142, s68, 8, v148
	v_ashrrev_i32_e32 v143, 31, v142
	v_lshl_or_b32 v140, s8, 8, v150
	v_lshlrev_b64 v[146:147], 12, v[142:143]
	v_ashrrev_i32_e32 v141, 31, v140
	v_pk_add_f32 v[116:117], v[116:117], 0 op_sel_hi:[1,0]
	v_pk_add_f32 v[144:145], v[114:115], 0 op_sel_hi:[1,0]
	v_pk_add_f32 v[114:115], v[120:121], 0 op_sel_hi:[1,0]
	v_pk_add_f32 v[120:121], v[118:119], 0 op_sel_hi:[1,0]
	v_lshl_add_u64 v[118:119], s[10:11], 0, v[146:147]
	v_cvt_pk_bf16_f32 v152, v144, v145
	v_cvt_pk_bf16_f32 v153, v116, v117
	v_cvt_pk_bf16_f32 v154, v120, v121
	v_cvt_pk_bf16_f32 v155, v114, v115
	v_lshl_add_u64 v[156:157], v[140:141], 1, v[118:119]
	s_lshl_b32 s16, s8, 2
	global_store_dwordx4 v[156:157], v[152:155], off
	v_pk_add_f32 v[124:125], v[124:125], 0 op_sel_hi:[1,0]
	v_pk_add_f32 v[146:147], v[122:123], 0 op_sel_hi:[1,0]
	v_pk_add_f32 v[118:119], v[128:129], 0 op_sel_hi:[1,0]
	v_pk_add_f32 v[122:123], v[126:127], 0 op_sel_hi:[1,0]
	v_cndmask_b32_e64 v152, 0, 1, s[60:61]
	s_ashr_i32 s17, s16, 31
	v_cvt_pk_bf16_f32 v126, v146, v147
	v_cvt_pk_bf16_f32 v127, v124, v125
	v_cvt_pk_bf16_f32 v128, v122, v123
	v_cvt_pk_bf16_f32 v129, v118, v119
	v_cmp_ne_u32_e64 s[8:9], 1, v152
	s_andn2_b64 vcc, exec, s[60:61]
	global_store_dwordx4 v[156:157], v[126:129], off offset:256
	s_cbranch_vccnz .LBB0_573
	s_nop 0
	v_mul_f32_e32 v126, v145, v145
	v_mul_f32_e32 v117, v117, v117
	v_fmac_f32_e32 v126, v144, v144
	v_fmac_f32_e32 v117, v116, v116
	v_add_f32_e32 v116, v126, v117
	v_mul_f32_e32 v117, v121, v121
	v_mul_f32_e32 v115, v115, v115
	v_fmac_f32_e32 v117, v120, v120
	v_fmac_f32_e32 v115, v114, v114
	v_add_f32_e32 v114, v117, v115
	v_add_f32_e32 v114, v116, v114
	v_mul_f32_e32 v115, v147, v147
	v_mul_f32_e32 v116, v125, v125
	v_fmac_f32_e32 v115, v146, v146
	v_fmac_f32_e32 v116, v124, v124
	v_add_f32_e32 v115, v115, v116
	v_add_f32_e32 v114, v114, v115
	v_mul_f32_e32 v115, v123, v123
	v_mul_f32_e32 v116, v119, v119
	v_fmac_f32_e32 v115, v122, v122
	v_fmac_f32_e32 v116, v118, v118
	v_add_f32_e32 v115, v115, v116
	v_and_b32_e32 v116, 64, v251
	v_add_f32_e32 v114, v114, v115
	v_xor_b32_e32 v115, 16, v251
	v_add_u32_e32 v116, 64, v116
	v_cmp_lt_i32_e32 vcc, v115, v116
	s_nop 1
	v_cndmask_b32_e32 v115, v251, v115, vcc
	v_lshlrev_b32_e32 v115, 2, v115
	ds_bpermute_b32 v115, v115, v114
	s_waitcnt lgkmcnt(0)
	v_add_f32_e32 v114, v114, v115
	v_xor_b32_e32 v115, 32, v251
	v_cmp_lt_i32_e32 vcc, v115, v116
	s_nop 1
	v_cndmask_b32_e32 v115, v251, v115, vcc
	v_lshlrev_b32_e32 v115, 2, v115
	v_mov_b32_e32 v115, v114
	v_mov_b32_e32 v245, v114
	s_nop 1
	v_permlane32_swap_b32_e32 v115, v245
	s_and_saveexec_b64 s[54:55], s[4:5]
	s_cbranch_execz .LBB0_572
	v_lshlrev_b64 v[116:117], 8, v[142:143]
	v_lshl_add_u64 v[116:117], s[14:15], 0, v[116:117]
	v_lshl_add_u64 v[116:117], s[16:17], 2, v[116:117]
	s_lshl_b32 s18, s27, 2
	v_lshl_add_u64 v[116:117], v[116:117], 0, s[18:19]
	s_waitcnt lgkmcnt(0)
	v_add_f32_e32 v114, v115, v245
	global_store_dword v[116:117], v114, off

; __device__ __forceinline__ unsigned pk2(float lo, float hi) { f32x2 v = {lo, hi}; bf16x2_t b = __builtin_convertvector(v, bf16x2_t); return __builtin_bit_cast(unsigned, b); }
; __device__ __forceinline__ float bflo(unsigned w) { return __uint_as_float(w << 16); }
; __device__ __forceinline__ float bfhi(unsigned w) { return __uint_as_float(w & 0xffff0000u); }
;     __device__ __forceinline__ void operator()(const f32x4 (&acc)[2][2][4][2], const Unit& u, int wr, int wc, int fr, int fq) const {
;     ...
;         for (int j = 0; j < 8; ++j) { const int ai = j >> 2, m = j & 3; const int row = row0 + ai * HALF + m * 16; const size_t off = (size_t)row * DM + col0; float ss = 0.f;
;             if (MODE < 3 && j < 6) ldgrp(nx2, (size_t)(row0 + ((j + 2) >> 2) * HALF + ((j + 2) & 3) * 16) * DM + col0);
; #pragma unroll
;             for (int bj = 0; bj < 2; ++bj) { f32x4 o[2];
; #pragma unroll
;                 for (int n = 0; n < 2; ++n) { const int cc = bj * HALF + 4 * n;
;                     f32x4 v = acc[ai][bj][m][n];
;                     if (bias) { v = (v + *(const f32x4*)(bias + col0 + cc)) * *(const f32x4*)(scale + col0 + cc); }
;                     f32x4 b;
;                     if (MODE >= 3) b = (f32x4){0.f, 0.f, 0.f, 0.f};
;                     else if (MODE == 0) b = __builtin_bit_cast(f32x4, cur[bj][n]);
;                     else { const unsigned w0 = n ? cur[bj][0].z : cur[bj][0].x, w1 = n ? cur[bj][0].w : cur[bj][0].y; b = (f32x4){bflo(w0), bfhi(w0), bflo(w1), bfhi(w1)}; }
;                     o[n] = b + v;
;                     if (MODE == 2 || MODE == 4) *(f32x4*)(out + off + cc) = o[n];
;                     ss += (o[n][0] * o[n][0] + o[n][1] * o[n][1]) + (o[n][2] * o[n][2] + o[n][3] * o[n][3]); }
;                 if (MODE != 2 && MODE != 4) { u32x4 w; w.x = pk2(o[0][0], o[0][1]); w.y = pk2(o[0][2], o[0][3]); w.z = pk2(o[1][0], o[1][1]); w.w = pk2(o[1][2], o[1][3]); *(u32x4*)(xb + off + bj * HALF) = w; } }
;             if (MODE != 2 && MODE != 4 && rsq) { ss += __shfl_xor(ss, 16); ss += __shfl_xor(ss, 32); if (fq == 0) rsq[(size_t)row * 64 + u.pn * 4 + wc] = ss; }
.LBB0_573:
	v_or_b32_e32 v114, 16, v142
	s_waitcnt lgkmcnt(0)
	v_ashrrev_i32_e32 v115, 31, v114
	v_lshlrev_b64 v[122:123], 12, v[114:115]
	v_pk_add_f32 v[100:101], v[100:101], 0 op_sel_hi:[1,0]
	v_pk_add_f32 v[116:117], v[98:99], 0 op_sel_hi:[1,0]
	v_pk_add_f32 v[98:99], v[104:105], 0 op_sel_hi:[1,0]
	v_pk_add_f32 v[104:105], v[102:103], 0 op_sel_hi:[1,0]
	v_lshl_add_u64 v[102:103], s[10:11], 0, v[122:123]
	v_cvt_pk_bf16_f32 v118, v116, v117
	v_cvt_pk_bf16_f32 v119, v100, v101
	v_cvt_pk_bf16_f32 v120, v104, v105
	v_cvt_pk_bf16_f32 v121, v98, v99
	v_lshl_add_u64 v[122:123], v[140:141], 1, v[102:103]
	global_store_dwordx4 v[122:123], v[118:121], off
	v_pk_add_f32 v[108:109], v[108:109], 0 op_sel_hi:[1,0]
	v_pk_add_f32 v[102:103], v[112:113], 0 op_sel_hi:[1,0]
	v_pk_add_f32 v[118:119], v[106:107], 0 op_sel_hi:[1,0]
	v_pk_add_f32 v[106:107], v[110:111], 0 op_sel_hi:[1,0]
	v_cvt_pk_bf16_f32 v110, v118, v119
	v_cvt_pk_bf16_f32 v111, v108, v109
	v_cvt_pk_bf16_f32 v112, v106, v107
	v_cvt_pk_bf16_f32 v113, v102, v103
	s_and_b64 vcc, exec, s[8:9]
	global_store_dwordx4 v[122:123], v[110:113], off offset:256
	s_cbranch_vccnz .LBB0_577
	s_nop 0
	v_mul_f32_e32 v110, v117, v117
	v_mul_f32_e32 v101, v101, v101
	v_fmac_f32_e32 v110, v116, v116
	v_fmac_f32_e32 v101, v100, v100
	v_add_f32_e32 v100, v110, v101
	v_mul_f32_e32 v101, v105, v105
	v_mul_f32_e32 v99, v99, v99
	v_fmac_f32_e32 v101, v104, v104
	v_fmac_f32_e32 v99, v98, v98
	v_add_f32_e32 v98, v101, v99
	v_add_f32_e32 v98, v100, v98
	v_mul_f32_e32 v99, v119, v119
	v_mul_f32_e32 v100, v109, v109
	v_fmac_f32_e32 v99, v118, v118
	v_fmac_f32_e32 v100, v108, v108
	v_add_f32_e32 v99, v99, v100
	v_add_f32_e32 v98, v98, v99
	v_mul_f32_e32 v99, v107, v107
	v_mul_f32_e32 v100, v103, v103
	v_fmac_f32_e32 v99, v106, v106
	v_fmac_f32_e32 v100, v102, v102
	v_add_f32_e32 v99, v99, v100
	v_and_b32_e32 v100, 64, v251
	v_add_f32_e32 v98, v98, v99
	v_xor_b32_e32 v99, 16, v251
	v_add_u32_e32 v100, 64, v100
	v_cmp_lt_i32_e32 vcc, v99, v100
	s_nop 1
	v_cndmask_b32_e32 v99, v251, v99, vcc
	v_lshlrev_b32_e32 v99, 2, v99
	ds_bpermute_b32 v99, v99, v98
	s_waitcnt lgkmcnt(0)
	v_add_f32_e32 v98, v98, v99
	v_xor_b32_e32 v99, 32, v251
	v_cmp_lt_i32_e32 vcc, v99, v100
	s_nop 1
	v_cndmask_b32_e32 v99, v251, v99, vcc
	v_lshlrev_b32_e32 v99, 2, v99
	v_mov_b32_e32 v99, v98
	v_mov_b32_e32 v245, v98
	s_nop 1
	v_permlane32_swap_b32_e32 v99, v245
	s_and_saveexec_b64 s[54:55], s[4:5]
	s_cbranch_execz .LBB0_576
	v_lshlrev_b64 v[100:101], 8, v[114:115]
	v_lshl_add_u64 v[100:101], s[14:15], 0, v[100:101]
	v_lshl_add_u64 v[100:101], s[16:17], 2, v[100:101]
	s_lshl_b32 s18, s27, 2
	v_lshl_add_u64 v[100:101], v[100:101], 0, s[18:19]
	s_waitcnt lgkmcnt(0)
	v_add_f32_e32 v98, v99, v245
	global_store_dword v[100:101], v98, off

; __device__ __forceinline__ unsigned pk2(float lo, float hi) { f32x2 v = {lo, hi}; bf16x2_t b = __builtin_convertvector(v, bf16x2_t); return __builtin_bit_cast(unsigned, b); }
; __device__ __forceinline__ float bflo(unsigned w) { return __uint_as_float(w << 16); }
; __device__ __forceinline__ float bfhi(unsigned w) { return __uint_as_float(w & 0xffff0000u); }
;     __device__ __forceinline__ void operator()(const f32x4 (&acc)[2][2][4][2], const Unit& u, int wr, int wc, int fr, int fq) const {
;     ...
;         for (int j = 0; j < 8; ++j) { const int ai = j >> 2, m = j & 3; const int row = row0 + ai * HALF + m * 16; const size_t off = (size_t)row * DM + col0; float ss = 0.f;
;             if (MODE < 3 && j < 6) ldgrp(nx2, (size_t)(row0 + ((j + 2) >> 2) * HALF + ((j + 2) & 3) * 16) * DM + col0);
; #pragma unroll
;             for (int bj = 0; bj < 2; ++bj) { f32x4 o[2];
; #pragma unroll
;                 for (int n = 0; n < 2; ++n) { const int cc = bj * HALF + 4 * n;
;                     f32x4 v = acc[ai][bj][m][n];
;                     if (bias) { v = (v + *(const f32x4*)(bias + col0 + cc)) * *(const f32x4*)(scale + col0 + cc); }
;                     f32x4 b;
;                     if (MODE >= 3) b = (f32x4){0.f, 0.f, 0.f, 0.f};
;                     else if (MODE == 0) b = __builtin_bit_cast(f32x4, cur[bj][n]);
;                     else { const unsigned w0 = n ? cur[bj][0].z : cur[bj][0].x, w1 = n ? cur[bj][0].w : cur[bj][0].y; b = (f32x4){bflo(w0), bfhi(w0), bflo(w1), bfhi(w1)}; }
;                     o[n] = b + v;
;                     if (MODE == 2 || MODE == 4) *(f32x4*)(out + off + cc) = o[n];
;                     ss += (o[n][0] * o[n][0] + o[n][1] * o[n][1]) + (o[n][2] * o[n][2] + o[n][3] * o[n][3]); }
;                 if (MODE != 2 && MODE != 4) { u32x4 w; w.x = pk2(o[0][0], o[0][1]); w.y = pk2(o[0][2], o[0][3]); w.z = pk2(o[1][0], o[1][1]); w.w = pk2(o[1][2], o[1][3]); *(u32x4*)(xb + off + bj * HALF) = w; } }
;             if (MODE != 2 && MODE != 4 && rsq) { ss += __shfl_xor(ss, 16); ss += __shfl_xor(ss, 32); if (fq == 0) rsq[(size_t)row * 64 + u.pn * 4 + wc] = ss; }
.LBB0_577:
	v_or_b32_e32 v98, 32, v142
	s_waitcnt lgkmcnt(0)
	v_ashrrev_i32_e32 v99, 31, v98
	v_lshlrev_b64 v[106:107], 12, v[98:99]
	v_pk_add_f32 v[82:83], v[82:83], 0 op_sel_hi:[1,0]
	v_pk_add_f32 v[100:101], v[80:81], 0 op_sel_hi:[1,0]
	v_pk_add_f32 v[80:81], v[86:87], 0 op_sel_hi:[1,0]
	v_pk_add_f32 v[86:87], v[84:85], 0 op_sel_hi:[1,0]
	v_lshl_add_u64 v[84:85], s[10:11], 0, v[106:107]
	v_cvt_pk_bf16_f32 v102, v100, v101
	v_cvt_pk_bf16_f32 v103, v82, v83
	v_cvt_pk_bf16_f32 v104, v86, v87
	v_cvt_pk_bf16_f32 v105, v80, v81
	v_lshl_add_u64 v[106:107], v[140:141], 1, v[84:85]
	global_store_dwordx4 v[106:107], v[102:105], off
	v_pk_add_f32 v[90:91], v[90:91], 0 op_sel_hi:[1,0]
	v_pk_add_f32 v[84:85], v[94:95], 0 op_sel_hi:[1,0]
	v_pk_add_f32 v[102:103], v[88:89], 0 op_sel_hi:[1,0]
	v_pk_add_f32 v[88:89], v[92:93], 0 op_sel_hi:[1,0]
	v_cvt_pk_bf16_f32 v92, v102, v103
	v_cvt_pk_bf16_f32 v93, v90, v91
	v_cvt_pk_bf16_f32 v94, v88, v89
	v_cvt_pk_bf16_f32 v95, v84, v85
	s_and_b64 vcc, exec, s[8:9]
	global_store_dwordx4 v[106:107], v[92:95], off offset:256
	s_cbranch_vccnz .LBB0_581
	s_nop 0
	v_mul_f32_e32 v92, v101, v101
	v_mul_f32_e32 v83, v83, v83
	v_fmac_f32_e32 v92, v100, v100
	v_fmac_f32_e32 v83, v82, v82
	v_add_f32_e32 v82, v92, v83
	v_mul_f32_e32 v83, v87, v87
	v_mul_f32_e32 v81, v81, v81
	v_fmac_f32_e32 v83, v86, v86
	v_fmac_f32_e32 v81, v80, v80
	v_add_f32_e32 v80, v83, v81
	v_add_f32_e32 v80, v82, v80
	v_mul_f32_e32 v81, v103, v103
	v_mul_f32_e32 v82, v91, v91
	v_fmac_f32_e32 v81, v102, v102
	v_fmac_f32_e32 v82, v90, v90
	v_add_f32_e32 v81, v81, v82
	v_add_f32_e32 v80, v80, v81
	v_mul_f32_e32 v81, v89, v89
	v_mul_f32_e32 v82, v85, v85
	v_fmac_f32_e32 v81, v88, v88
	v_fmac_f32_e32 v82, v84, v84
	v_add_f32_e32 v81, v81, v82
	v_and_b32_e32 v82, 64, v251
	v_add_f32_e32 v80, v80, v81
	v_xor_b32_e32 v81, 16, v251
	v_add_u32_e32 v82, 64, v82
	v_cmp_lt_i32_e32 vcc, v81, v82
	s_nop 1
	v_cndmask_b32_e32 v81, v251, v81, vcc
	v_lshlrev_b32_e32 v81, 2, v81
	ds_bpermute_b32 v81, v81, v80
	s_waitcnt lgkmcnt(0)
	v_add_f32_e32 v80, v80, v81
	v_xor_b32_e32 v81, 32, v251
	v_cmp_lt_i32_e32 vcc, v81, v82
	s_nop 1
	v_cndmask_b32_e32 v81, v251, v81, vcc
	v_lshlrev_b32_e32 v81, 2, v81
	v_mov_b32_e32 v81, v80
	v_mov_b32_e32 v245, v80
	s_nop 1
	v_permlane32_swap_b32_e32 v81, v245
	s_and_saveexec_b64 s[54:55], s[4:5]
	s_cbranch_execz .LBB0_580
	v_lshlrev_b64 v[82:83], 8, v[98:99]
	v_lshl_add_u64 v[82:83], s[14:15], 0, v[82:83]
	v_lshl_add_u64 v[82:83], s[16:17], 2, v[82:83]
	s_lshl_b32 s18, s27, 2
	v_lshl_add_u64 v[82:83], v[82:83], 0, s[18:19]
	s_waitcnt lgkmcnt(0)
	v_add_f32_e32 v80, v81, v245
	global_store_dword v[82:83], v80, off

; __device__ __forceinline__ unsigned pk2(float lo, float hi) { f32x2 v = {lo, hi}; bf16x2_t b = __builtin_convertvector(v, bf16x2_t); return __builtin_bit_cast(unsigned, b); }
; __device__ __forceinline__ float bflo(unsigned w) { return __uint_as_float(w << 16); }
; __device__ __forceinline__ float bfhi(unsigned w) { return __uint_as_float(w & 0xffff0000u); }
;     __device__ __forceinline__ void operator()(const f32x4 (&acc)[2][2][4][2], const Unit& u, int wr, int wc, int fr, int fq) const {
;     ...
;         for (int j = 0; j < 8; ++j) { const int ai = j >> 2, m = j & 3; const int row = row0 + ai * HALF + m * 16; const size_t off = (size_t)row * DM + col0; float ss = 0.f;
;             if (MODE < 3 && j < 6) ldgrp(nx2, (size_t)(row0 + ((j + 2) >> 2) * HALF + ((j + 2) & 3) * 16) * DM + col0);
; #pragma unroll
;             for (int bj = 0; bj < 2; ++bj) { f32x4 o[2];
; #pragma unroll
;                 for (int n = 0; n < 2; ++n) { const int cc = bj * HALF + 4 * n;
;                     f32x4 v = acc[ai][bj][m][n];
;                     if (bias) { v = (v + *(const f32x4*)(bias + col0 + cc)) * *(const f32x4*)(scale + col0 + cc); }
;                     f32x4 b;
;                     if (MODE >= 3) b = (f32x4){0.f, 0.f, 0.f, 0.f};
;                     else if (MODE == 0) b = __builtin_bit_cast(f32x4, cur[bj][n]);
;                     else { const unsigned w0 = n ? cur[bj][0].z : cur[bj][0].x, w1 = n ? cur[bj][0].w : cur[bj][0].y; b = (f32x4){bflo(w0), bfhi(w0), bflo(w1), bfhi(w1)}; }
;                     o[n] = b + v;
;                     if (MODE == 2 || MODE == 4) *(f32x4*)(out + off + cc) = o[n];
;                     ss += (o[n][0] * o[n][0] + o[n][1] * o[n][1]) + (o[n][2] * o[n][2] + o[n][3] * o[n][3]); }
;                 if (MODE != 2 && MODE != 4) { u32x4 w; w.x = pk2(o[0][0], o[0][1]); w.y = pk2(o[0][2], o[0][3]); w.z = pk2(o[1][0], o[1][1]); w.w = pk2(o[1][2], o[1][3]); *(u32x4*)(xb + off + bj * HALF) = w; } }
;             if (MODE != 2 && MODE != 4 && rsq) { ss += __shfl_xor(ss, 16); ss += __shfl_xor(ss, 32); if (fq == 0) rsq[(size_t)row * 64 + u.pn * 4 + wc] = ss; }
.LBB0_581:
	v_or_b32_e32 v80, 48, v142
	s_waitcnt lgkmcnt(0)
	v_ashrrev_i32_e32 v81, 31, v80
	v_lshlrev_b64 v[88:89], 12, v[80:81]
	v_pk_add_f32 v[50:51], v[50:51], 0 op_sel_hi:[1,0]
	v_pk_add_f32 v[82:83], v[48:49], 0 op_sel_hi:[1,0]
	v_pk_add_f32 v[48:49], v[54:55], 0 op_sel_hi:[1,0]
	v_pk_add_f32 v[54:55], v[52:53], 0 op_sel_hi:[1,0]
	v_lshl_add_u64 v[52:53], s[10:11], 0, v[88:89]
	v_cvt_pk_bf16_f32 v84, v82, v83
	v_cvt_pk_bf16_f32 v85, v50, v51
	v_cvt_pk_bf16_f32 v86, v54, v55
	v_cvt_pk_bf16_f32 v87, v48, v49
	v_lshl_add_u64 v[88:89], v[140:141], 1, v[52:53]
	global_store_dwordx4 v[88:89], v[84:87], off
	v_pk_add_f32 v[70:71], v[70:71], 0 op_sel_hi:[1,0]
	v_pk_add_f32 v[52:53], v[78:79], 0 op_sel_hi:[1,0]
	v_pk_add_f32 v[84:85], v[68:69], 0 op_sel_hi:[1,0]
	v_pk_add_f32 v[68:69], v[76:77], 0 op_sel_hi:[1,0]
	v_cvt_pk_bf16_f32 v76, v84, v85
	v_cvt_pk_bf16_f32 v77, v70, v71
	v_cvt_pk_bf16_f32 v78, v68, v69
	v_cvt_pk_bf16_f32 v79, v52, v53
	s_and_b64 vcc, exec, s[8:9]
	global_store_dwordx4 v[88:89], v[76:79], off offset:256
	s_cbranch_vccnz .LBB0_585
	s_nop 0
	v_mul_f32_e32 v76, v83, v83
	v_mul_f32_e32 v51, v51, v51
	v_fmac_f32_e32 v76, v82, v82
	v_fmac_f32_e32 v51, v50, v50
	v_add_f32_e32 v50, v76, v51
	v_mul_f32_e32 v51, v55, v55
	v_mul_f32_e32 v49, v49, v49
	v_fmac_f32_e32 v51, v54, v54
	v_fmac_f32_e32 v49, v48, v48
	v_add_f32_e32 v48, v51, v49
	v_add_f32_e32 v48, v50, v48
	v_mul_f32_e32 v49, v85, v85
	v_mul_f32_e32 v50, v71, v71
	v_fmac_f32_e32 v49, v84, v84
	v_fmac_f32_e32 v50, v70, v70
	v_add_f32_e32 v49, v49, v50
	v_add_f32_e32 v48, v48, v49
	v_mul_f32_e32 v49, v69, v69
	v_mul_f32_e32 v50, v53, v53
	v_fmac_f32_e32 v49, v68, v68
	v_fmac_f32_e32 v50, v52, v52
	v_add_f32_e32 v49, v49, v50
	v_and_b32_e32 v50, 64, v251
	v_add_f32_e32 v48, v48, v49
	v_xor_b32_e32 v49, 16, v251
	v_add_u32_e32 v50, 64, v50
	v_cmp_lt_i32_e32 vcc, v49, v50
	s_nop 1
	v_cndmask_b32_e32 v49, v251, v49, vcc
	v_lshlrev_b32_e32 v49, 2, v49
	ds_bpermute_b32 v49, v49, v48
	s_waitcnt lgkmcnt(0)
	v_add_f32_e32 v48, v48, v49
	v_xor_b32_e32 v49, 32, v251
	v_cmp_lt_i32_e32 vcc, v49, v50
	s_nop 1
	v_cndmask_b32_e32 v49, v251, v49, vcc
	v_lshlrev_b32_e32 v49, 2, v49
	v_mov_b32_e32 v49, v48
	v_mov_b32_e32 v245, v48
	s_nop 1
	v_permlane32_swap_b32_e32 v49, v245
	s_and_saveexec_b64 s[54:55], s[4:5]
	s_cbranch_execz .LBB0_584
	v_lshlrev_b64 v[50:51], 8, v[80:81]
	v_lshl_add_u64 v[50:51], s[14:15], 0, v[50:51]
	v_lshl_add_u64 v[50:51], s[16:17], 2, v[50:51]
	s_lshl_b32 s18, s27, 2
	v_lshl_add_u64 v[50:51], v[50:51], 0, s[18:19]
	s_waitcnt lgkmcnt(0)
	v_add_f32_e32 v48, v49, v245
	global_store_dword v[50:51], v48, off

; __device__ __forceinline__ unsigned pk2(float lo, float hi) { f32x2 v = {lo, hi}; bf16x2_t b = __builtin_convertvector(v, bf16x2_t); return __builtin_bit_cast(unsigned, b); }
; __device__ __forceinline__ float bflo(unsigned w) { return __uint_as_float(w << 16); }
; __device__ __forceinline__ float bfhi(unsigned w) { return __uint_as_float(w & 0xffff0000u); }
;     __device__ __forceinline__ void operator()(const f32x4 (&acc)[2][2][4][2], const Unit& u, int wr, int wc, int fr, int fq) const {
;     ...
;         for (int j = 0; j < 8; ++j) { const int ai = j >> 2, m = j & 3; const int row = row0 + ai * HALF + m * 16; const size_t off = (size_t)row * DM + col0; float ss = 0.f;
;             if (MODE < 3 && j < 6) ldgrp(nx2, (size_t)(row0 + ((j + 2) >> 2) * HALF + ((j + 2) & 3) * 16) * DM + col0);
; #pragma unroll
;             for (int bj = 0; bj < 2; ++bj) { f32x4 o[2];
; #pragma unroll
;                 for (int n = 0; n < 2; ++n) { const int cc = bj * HALF + 4 * n;
;                     f32x4 v = acc[ai][bj][m][n];
;                     if (bias) { v = (v + *(const f32x4*)(bias + col0 + cc)) * *(const f32x4*)(scale + col0 + cc); }
;                     f32x4 b;
;                     if (MODE >= 3) b = (f32x4){0.f, 0.f, 0.f, 0.f};
;                     else if (MODE == 0) b = __builtin_bit_cast(f32x4, cur[bj][n]);
;                     else { const unsigned w0 = n ? cur[bj][0].z : cur[bj][0].x, w1 = n ? cur[bj][0].w : cur[bj][0].y; b = (f32x4){bflo(w0), bfhi(w0), bflo(w1), bfhi(w1)}; }
;                     o[n] = b + v;
;                     if (MODE == 2 || MODE == 4) *(f32x4*)(out + off + cc) = o[n];
;                     ss += (o[n][0] * o[n][0] + o[n][1] * o[n][1]) + (o[n][2] * o[n][2] + o[n][3] * o[n][3]); }
;                 if (MODE != 2 && MODE != 4) { u32x4 w; w.x = pk2(o[0][0], o[0][1]); w.y = pk2(o[0][2], o[0][3]); w.z = pk2(o[1][0], o[1][1]); w.w = pk2(o[1][2], o[1][3]); *(u32x4*)(xb + off + bj * HALF) = w; } }
;             if (MODE != 2 && MODE != 4 && rsq) { ss += __shfl_xor(ss, 16); ss += __shfl_xor(ss, 32); if (fq == 0) rsq[(size_t)row * 64 + u.pn * 4 + wc] = ss; }
.LBB0_585:
	v_add_u32_e32 v48, 0x80, v142
	s_waitcnt lgkmcnt(0)
	v_ashrrev_i32_e32 v49, 31, v48
	v_lshlrev_b64 v[68:69], 12, v[48:49]
	v_pk_add_f32 v[38:39], v[38:39], 0 op_sel_hi:[1,0]
	v_pk_add_f32 v[50:51], v[36:37], 0 op_sel_hi:[1,0]
	v_pk_add_f32 v[36:37], v[46:47], 0 op_sel_hi:[1,0]
	v_pk_add_f32 v[46:47], v[44:45], 0 op_sel_hi:[1,0]
	v_lshl_add_u64 v[44:45], s[10:11], 0, v[68:69]
	v_cvt_pk_bf16_f32 v52, v50, v51
	v_cvt_pk_bf16_f32 v53, v38, v39
	v_cvt_pk_bf16_f32 v54, v46, v47
	v_cvt_pk_bf16_f32 v55, v36, v37
	v_lshl_add_u64 v[68:69], v[140:141], 1, v[44:45]
	global_store_dwordx4 v[68:69], v[52:55], off
	v_pk_add_f32 v[56:57], v[56:57], 0 op_sel_hi:[1,0]
	v_pk_add_f32 v[44:45], v[62:63], 0 op_sel_hi:[1,0]
	v_pk_add_f32 v[52:53], v[58:59], 0 op_sel_hi:[1,0]
	v_pk_add_f32 v[54:55], v[60:61], 0 op_sel_hi:[1,0]
	v_cvt_pk_bf16_f32 v58, v56, v57
	v_cvt_pk_bf16_f32 v59, v52, v53
	v_cvt_pk_bf16_f32 v60, v54, v55
	v_cvt_pk_bf16_f32 v61, v44, v45
	s_and_b64 vcc, exec, s[8:9]
	global_store_dwordx4 v[68:69], v[58:61], off offset:256
	s_cbranch_vccnz .LBB0_589
	v_mul_f32_e32 v51, v51, v51
	v_mul_f32_e32 v39, v39, v39
	v_fmac_f32_e32 v51, v50, v50
	v_fmac_f32_e32 v39, v38, v38
	v_add_f32_e32 v38, v51, v39
	v_mul_f32_e32 v39, v47, v47
	v_mul_f32_e32 v37, v37, v37
	v_fmac_f32_e32 v39, v46, v46
	v_fmac_f32_e32 v37, v36, v36
	v_add_f32_e32 v36, v39, v37
	v_add_f32_e32 v36, v38, v36
	v_mul_f32_e32 v37, v57, v57
	v_mul_f32_e32 v38, v53, v53
	v_fmac_f32_e32 v37, v56, v56
	v_fmac_f32_e32 v38, v52, v52
	v_add_f32_e32 v37, v37, v38
	v_add_f32_e32 v36, v36, v37
	v_mul_f32_e32 v37, v55, v55
	v_mul_f32_e32 v38, v45, v45
	v_fmac_f32_e32 v37, v54, v54
	v_fmac_f32_e32 v38, v44, v44
	v_add_f32_e32 v37, v37, v38
	v_and_b32_e32 v38, 64, v251
	v_add_f32_e32 v36, v36, v37
	v_xor_b32_e32 v37, 16, v251
	v_add_u32_e32 v38, 64, v38
	v_cmp_lt_i32_e32 vcc, v37, v38
	s_nop 1
	v_cndmask_b32_e32 v37, v251, v37, vcc
	v_lshlrev_b32_e32 v37, 2, v37
	ds_bpermute_b32 v37, v37, v36
	s_waitcnt lgkmcnt(0)
	v_add_f32_e32 v36, v36, v37
	v_xor_b32_e32 v37, 32, v251
	v_cmp_lt_i32_e32 vcc, v37, v38
	s_nop 1
	v_cndmask_b32_e32 v37, v251, v37, vcc
	v_lshlrev_b32_e32 v37, 2, v37
	v_mov_b32_e32 v37, v36
	v_mov_b32_e32 v245, v36
	s_nop 1
	v_permlane32_swap_b32_e32 v37, v245
	s_and_saveexec_b64 s[54:55], s[4:5]
	s_cbranch_execz .LBB0_588
	v_lshlrev_b64 v[38:39], 8, v[48:49]
	v_lshl_add_u64 v[38:39], s[14:15], 0, v[38:39]
	v_lshl_add_u64 v[38:39], s[16:17], 2, v[38:39]
	s_lshl_b32 s18, s27, 2
	v_lshl_add_u64 v[38:39], v[38:39], 0, s[18:19]
	s_waitcnt lgkmcnt(0)
	v_add_f32_e32 v36, v37, v245
	global_store_dword v[38:39], v36, off

; __device__ __forceinline__ unsigned pk2(float lo, float hi) { f32x2 v = {lo, hi}; bf16x2_t b = __builtin_convertvector(v, bf16x2_t); return __builtin_bit_cast(unsigned, b); }
; __device__ __forceinline__ float bflo(unsigned w) { return __uint_as_float(w << 16); }
; __device__ __forceinline__ float bfhi(unsigned w) { return __uint_as_float(w & 0xffff0000u); }
;     __device__ __forceinline__ void operator()(const f32x4 (&acc)[2][2][4][2], const Unit& u, int wr, int wc, int fr, int fq) const {
;     ...
;         for (int j = 0; j < 8; ++j) { const int ai = j >> 2, m = j & 3; const int row = row0 + ai * HALF + m * 16; const size_t off = (size_t)row * DM + col0; float ss = 0.f;
;             if (MODE < 3 && j < 6) ldgrp(nx2, (size_t)(row0 + ((j + 2) >> 2) * HALF + ((j + 2) & 3) * 16) * DM + col0);
; #pragma unroll
;             for (int bj = 0; bj < 2; ++bj) { f32x4 o[2];
; #pragma unroll
;                 for (int n = 0; n < 2; ++n) { const int cc = bj * HALF + 4 * n;
;                     f32x4 v = acc[ai][bj][m][n];
;                     if (bias) { v = (v + *(const f32x4*)(bias + col0 + cc)) * *(const f32x4*)(scale + col0 + cc); }
;                     f32x4 b;
;                     if (MODE >= 3) b = (f32x4){0.f, 0.f, 0.f, 0.f};
;                     else if (MODE == 0) b = __builtin_bit_cast(f32x4, cur[bj][n]);
;                     else { const unsigned w0 = n ? cur[bj][0].z : cur[bj][0].x, w1 = n ? cur[bj][0].w : cur[bj][0].y; b = (f32x4){bflo(w0), bfhi(w0), bflo(w1), bfhi(w1)}; }
;                     o[n] = b + v;
;                     if (MODE == 2 || MODE == 4) *(f32x4*)(out + off + cc) = o[n];
;                     ss += (o[n][0] * o[n][0] + o[n][1] * o[n][1]) + (o[n][2] * o[n][2] + o[n][3] * o[n][3]); }
;                 if (MODE != 2 && MODE != 4) { u32x4 w; w.x = pk2(o[0][0], o[0][1]); w.y = pk2(o[0][2], o[0][3]); w.z = pk2(o[1][0], o[1][1]); w.w = pk2(o[1][2], o[1][3]); *(u32x4*)(xb + off + bj * HALF) = w; } }
;             if (MODE != 2 && MODE != 4 && rsq) { ss += __shfl_xor(ss, 16); ss += __shfl_xor(ss, 32); if (fq == 0) rsq[(size_t)row * 64 + u.pn * 4 + wc] = ss; }
.LBB0_589:
	v_or_b32_e32 v36, 16, v48
	s_waitcnt lgkmcnt(0)
	v_ashrrev_i32_e32 v37, 31, v36
	v_lshlrev_b64 v[50:51], 12, v[36:37]
	v_pk_add_f32 v[14:15], v[14:15], 0 op_sel_hi:[1,0]
	v_pk_add_f32 v[38:39], v[12:13], 0 op_sel_hi:[1,0]
	v_pk_add_f32 v[12:13], v[22:23], 0 op_sel_hi:[1,0]
	v_pk_add_f32 v[22:23], v[20:21], 0 op_sel_hi:[1,0]
	v_lshl_add_u64 v[20:21], s[10:11], 0, v[50:51]
	v_cvt_pk_bf16_f32 v44, v38, v39
	v_cvt_pk_bf16_f32 v45, v14, v15
	v_cvt_pk_bf16_f32 v46, v22, v23
	v_cvt_pk_bf16_f32 v47, v12, v13
	v_lshl_add_u64 v[56:57], v[140:141], 1, v[20:21]
	global_store_dwordx4 v[56:57], v[44:47], off
	v_pk_add_f32 v[50:51], v[64:65], 0 op_sel_hi:[1,0]
	v_pk_add_f32 v[20:21], v[74:75], 0 op_sel_hi:[1,0]
	v_pk_add_f32 v[44:45], v[66:67], 0 op_sel_hi:[1,0]
	v_pk_add_f32 v[46:47], v[72:73], 0 op_sel_hi:[1,0]
	v_cvt_pk_bf16_f32 v52, v50, v51
	v_cvt_pk_bf16_f32 v53, v44, v45
	v_cvt_pk_bf16_f32 v54, v46, v47
	v_cvt_pk_bf16_f32 v55, v20, v21
	s_and_b64 vcc, exec, s[8:9]
	global_store_dwordx4 v[56:57], v[52:55], off offset:256
	s_cbranch_vccnz .LBB0_593
	v_mul_f32_e32 v39, v39, v39
	v_mul_f32_e32 v15, v15, v15
	v_fmac_f32_e32 v39, v38, v38
	v_fmac_f32_e32 v15, v14, v14
	v_add_f32_e32 v14, v39, v15
	v_mul_f32_e32 v15, v23, v23
	v_mul_f32_e32 v13, v13, v13
	v_fmac_f32_e32 v15, v22, v22
	v_fmac_f32_e32 v13, v12, v12
	v_add_f32_e32 v12, v15, v13
	v_add_f32_e32 v12, v14, v12
	v_mul_f32_e32 v13, v51, v51
	v_mul_f32_e32 v14, v45, v45
	v_fmac_f32_e32 v13, v50, v50
	v_fmac_f32_e32 v14, v44, v44
	v_add_f32_e32 v13, v13, v14
	v_add_f32_e32 v12, v12, v13
	v_mul_f32_e32 v13, v47, v47
	v_mul_f32_e32 v14, v21, v21
	v_fmac_f32_e32 v13, v46, v46
	v_fmac_f32_e32 v14, v20, v20
	v_add_f32_e32 v13, v13, v14
	v_and_b32_e32 v14, 64, v251
	v_add_f32_e32 v12, v12, v13
	v_xor_b32_e32 v13, 16, v251
	v_add_u32_e32 v14, 64, v14
	v_cmp_lt_i32_e32 vcc, v13, v14
	s_nop 1
	v_cndmask_b32_e32 v13, v251, v13, vcc
	v_lshlrev_b32_e32 v13, 2, v13
	ds_bpermute_b32 v13, v13, v12
	s_waitcnt lgkmcnt(0)
	v_add_f32_e32 v12, v12, v13
	v_xor_b32_e32 v13, 32, v251
	v_cmp_lt_i32_e32 vcc, v13, v14
	s_nop 1
	v_cndmask_b32_e32 v13, v251, v13, vcc
	v_lshlrev_b32_e32 v13, 2, v13
	v_mov_b32_e32 v13, v12
	v_mov_b32_e32 v245, v12
	s_nop 1
	v_permlane32_swap_b32_e32 v13, v245
	s_and_saveexec_b64 s[54:55], s[4:5]
	s_cbranch_execz .LBB0_592
	v_lshlrev_b64 v[14:15], 8, v[36:37]
	v_lshl_add_u64 v[14:15], s[14:15], 0, v[14:15]
	v_lshl_add_u64 v[14:15], s[16:17], 2, v[14:15]
	s_lshl_b32 s18, s27, 2
	v_lshl_add_u64 v[14:15], v[14:15], 0, s[18:19]
	s_waitcnt lgkmcnt(0)
	v_add_f32_e32 v12, v13, v245
	global_store_dword v[14:15], v12, off

; __device__ __forceinline__ unsigned pk2(float lo, float hi) { f32x2 v = {lo, hi}; bf16x2_t b = __builtin_convertvector(v, bf16x2_t); return __builtin_bit_cast(unsigned, b); }
; __device__ __forceinline__ float bflo(unsigned w) { return __uint_as_float(w << 16); }
; __device__ __forceinline__ float bfhi(unsigned w) { return __uint_as_float(w & 0xffff0000u); }
;     __device__ __forceinline__ void operator()(const f32x4 (&acc)[2][2][4][2], const Unit& u, int wr, int wc, int fr, int fq) const {
;     ...
;                 for (int n = 0; n < 2; ++n) { const int cc = bj * HALF + 4 * n;
;                     f32x4 v = acc[ai][bj][m][n];
;                     if (bias) { v = (v + *(const f32x4*)(bias + col0 + cc)) * *(const f32x4*)(scale + col0 + cc); }
;                     f32x4 b;
;                     if (MODE >= 3) b = (f32x4){0.f, 0.f, 0.f, 0.f};
;                     else if (MODE == 0) b = __builtin_bit_cast(f32x4, cur[bj][n]);
;                     else { const unsigned w0 = n ? cur[bj][0].z : cur[bj][0].x, w1 = n ? cur[bj][0].w : cur[bj][0].y; b = (f32x4){bflo(w0), bfhi(w0), bflo(w1), bfhi(w1)}; }
;                     o[n] = b + v;
;                     if (MODE == 2 || MODE == 4) *(f32x4*)(out + off + cc) = o[n];
;                     ss += (o[n][0] * o[n][0] + o[n][1] * o[n][1]) + (o[n][2] * o[n][2] + o[n][3] * o[n][3]); }
;                 if (MODE != 2 && MODE != 4) { u32x4 w; w.x = pk2(o[0][0], o[0][1]); w.y = pk2(o[0][2], o[0][3]); w.z = pk2(o[1][0], o[1][1]); w.w = pk2(o[1][2], o[1][3]); *(u32x4*)(xb + off + bj * HALF) = w; } }
;             if (MODE != 2 && MODE != 4 && rsq) { ss += __shfl_xor(ss, 16); ss += __shfl_xor(ss, 32); if (fq == 0) rsq[(size_t)row * 64 + u.pn * 4 + wc] = ss; }
.LBB0_593:
	v_or_b32_e32 v12, 32, v48
	s_waitcnt lgkmcnt(0)
	v_ashrrev_i32_e32 v13, 31, v12
	v_lshlrev_b64 v[22:23], 12, v[12:13]
	v_pk_add_f32 v[20:21], v[26:27], 0 op_sel_hi:[1,0]
	v_pk_add_f32 v[26:27], v[24:25], 0 op_sel_hi:[1,0]
	v_pk_add_f32 v[14:15], v[30:31], 0 op_sel_hi:[1,0]
	v_pk_add_f32 v[24:25], v[28:29], 0 op_sel_hi:[1,0]
	v_lshl_add_u64 v[22:23], s[10:11], 0, v[22:23]
	v_cvt_pk_bf16_f32 v28, v26, v27
	v_cvt_pk_bf16_f32 v29, v20, v21
	v_cvt_pk_bf16_f32 v30, v24, v25
	v_cvt_pk_bf16_f32 v31, v14, v15
	v_lshl_add_u64 v[38:39], v[140:141], 1, v[22:23]
	global_store_dwordx4 v[38:39], v[28:31], off
	v_pk_add_f32 v[32:33], v[32:33], 0 op_sel_hi:[1,0]
	v_pk_add_f32 v[22:23], v[42:43], 0 op_sel_hi:[1,0]
	v_pk_add_f32 v[28:29], v[34:35], 0 op_sel_hi:[1,0]
	v_pk_add_f32 v[30:31], v[40:41], 0 op_sel_hi:[1,0]
	v_cvt_pk_bf16_f32 v34, v32, v33
	v_cvt_pk_bf16_f32 v35, v28, v29
	v_cvt_pk_bf16_f32 v36, v30, v31
	v_cvt_pk_bf16_f32 v37, v22, v23
	s_and_b64 vcc, exec, s[8:9]
	global_store_dwordx4 v[38:39], v[34:37], off offset:256
	s_cbranch_vccnz .LBB0_597
	v_mul_f32_e32 v27, v27, v27
	v_mul_f32_e32 v21, v21, v21
	v_fmac_f32_e32 v27, v26, v26
	v_fmac_f32_e32 v21, v20, v20
	v_add_f32_e32 v20, v27, v21
	v_mul_f32_e32 v21, v25, v25
	v_mul_f32_e32 v15, v15, v15
	v_fmac_f32_e32 v21, v24, v24
	v_fmac_f32_e32 v15, v14, v14
	v_add_f32_e32 v14, v21, v15
	v_add_f32_e32 v14, v20, v14
	v_mul_f32_e32 v15, v33, v33
	v_mul_f32_e32 v20, v29, v29
	v_fmac_f32_e32 v15, v32, v32
	v_fmac_f32_e32 v20, v28, v28
	v_add_f32_e32 v15, v15, v20
	v_add_f32_e32 v14, v14, v15
	v_mul_f32_e32 v15, v31, v31
	v_mul_f32_e32 v20, v23, v23
	v_fmac_f32_e32 v15, v30, v30
	v_fmac_f32_e32 v20, v22, v22
	v_add_f32_e32 v15, v15, v20
	v_and_b32_e32 v20, 64, v251
	v_add_f32_e32 v14, v14, v15
	v_xor_b32_e32 v15, 16, v251
	v_add_u32_e32 v20, 64, v20
	v_cmp_lt_i32_e32 vcc, v15, v20
	s_nop 1
	v_cndmask_b32_e32 v15, v251, v15, vcc
	v_lshlrev_b32_e32 v15, 2, v15
	ds_bpermute_b32 v15, v15, v14
	s_waitcnt lgkmcnt(0)
	v_add_f32_e32 v14, v14, v15
	v_xor_b32_e32 v15, 32, v251
	v_cmp_lt_i32_e32 vcc, v15, v20
	s_nop 1
	v_cndmask_b32_e32 v15, v251, v15, vcc
	v_lshlrev_b32_e32 v15, 2, v15
	v_mov_b32_e32 v15, v14
	v_mov_b32_e32 v245, v14
	s_nop 1
	v_permlane32_swap_b32_e32 v15, v245
	s_and_saveexec_b64 s[54:55], s[4:5]
	s_cbranch_execz .LBB0_596
	v_lshlrev_b64 v[12:13], 8, v[12:13]
	v_lshl_add_u64 v[12:13], s[14:15], 0, v[12:13]
	v_lshl_add_u64 v[12:13], s[16:17], 2, v[12:13]
	s_lshl_b32 s18, s27, 2
	v_lshl_add_u64 v[12:13], v[12:13], 0, s[18:19]
	s_waitcnt lgkmcnt(0)
	v_add_f32_e32 v14, v15, v245
	global_store_dword v[12:13], v14, off

; __device__ __forceinline__ unsigned pk2(float lo, float hi) { f32x2 v = {lo, hi}; bf16x2_t b = __builtin_convertvector(v, bf16x2_t); return __builtin_bit_cast(unsigned, b); }
; __device__ __forceinline__ float bflo(unsigned w) { return __uint_as_float(w << 16); }
; __device__ __forceinline__ float bfhi(unsigned w) { return __uint_as_float(w & 0xffff0000u); }
;     __device__ __forceinline__ void operator()(const f32x4 (&acc)[2][2][4][2], const Unit& u, int wr, int wc, int fr, int fq) const {
;     ...
;                 for (int n = 0; n < 2; ++n) { const int cc = bj * HALF + 4 * n;
;                     f32x4 v = acc[ai][bj][m][n];
;                     if (bias) { v = (v + *(const f32x4*)(bias + col0 + cc)) * *(const f32x4*)(scale + col0 + cc); }
;                     f32x4 b;
;                     if (MODE >= 3) b = (f32x4){0.f, 0.f, 0.f, 0.f};
;                     else if (MODE == 0) b = __builtin_bit_cast(f32x4, cur[bj][n]);
;                     else { const unsigned w0 = n ? cur[bj][0].z : cur[bj][0].x, w1 = n ? cur[bj][0].w : cur[bj][0].y; b = (f32x4){bflo(w0), bfhi(w0), bflo(w1), bfhi(w1)}; }
;                     o[n] = b + v;
;                     if (MODE == 2 || MODE == 4) *(f32x4*)(out + off + cc) = o[n];
;                     ss += (o[n][0] * o[n][0] + o[n][1] * o[n][1]) + (o[n][2] * o[n][2] + o[n][3] * o[n][3]); }
;                 if (MODE != 2 && MODE != 4) { u32x4 w; w.x = pk2(o[0][0], o[0][1]); w.y = pk2(o[0][2], o[0][3]); w.z = pk2(o[1][0], o[1][1]); w.w = pk2(o[1][2], o[1][3]); *(u32x4*)(xb + off + bj * HALF) = w; } }
;             if (MODE != 2 && MODE != 4 && rsq) { ss += __shfl_xor(ss, 16); ss += __shfl_xor(ss, 32); if (fq == 0) rsq[(size_t)row * 64 + u.pn * 4 + wc] = ss; }
.LBB0_597:
	v_or_b32_e32 v12, 48, v48
	v_ashrrev_i32_e32 v13, 31, v12
	v_lshlrev_b64 v[24:25], 12, v[12:13]
	v_pk_add_f32 v[2:3], v[2:3], 0 op_sel_hi:[1,0]
	s_waitcnt lgkmcnt(0)
	v_pk_add_f32 v[14:15], v[0:1], 0 op_sel_hi:[1,0]
	v_pk_add_f32 v[0:1], v[6:7], 0 op_sel_hi:[1,0]
	v_pk_add_f32 v[6:7], v[4:5], 0 op_sel_hi:[1,0]
	v_lshl_add_u64 v[4:5], s[10:11], 0, v[24:25]
	v_cvt_pk_bf16_f32 v20, v14, v15
	v_cvt_pk_bf16_f32 v21, v2, v3
	v_cvt_pk_bf16_f32 v22, v6, v7
	v_cvt_pk_bf16_f32 v23, v0, v1
	v_lshl_add_u64 v[24:25], v[140:141], 1, v[4:5]
	global_store_dwordx4 v[24:25], v[20:23], off
	v_pk_add_f32 v[10:11], v[10:11], 0 op_sel_hi:[1,0]
	v_pk_add_f32 v[4:5], v[18:19], 0 op_sel_hi:[1,0]
	v_pk_add_f32 v[20:21], v[8:9], 0 op_sel_hi:[1,0]
	v_pk_add_f32 v[8:9], v[16:17], 0 op_sel_hi:[1,0]
	v_cvt_pk_bf16_f32 v16, v20, v21
	v_cvt_pk_bf16_f32 v17, v10, v11
	v_cvt_pk_bf16_f32 v18, v8, v9
	v_cvt_pk_bf16_f32 v19, v4, v5
	s_and_b64 vcc, exec, s[8:9]
	global_store_dwordx4 v[24:25], v[16:19], off offset:256
	s_cbranch_vccnz .LBB0_601
	v_mul_f32_e32 v15, v15, v15
	v_mul_f32_e32 v3, v3, v3
	v_fmac_f32_e32 v15, v14, v14
	v_fmac_f32_e32 v3, v2, v2
	v_add_f32_e32 v2, v15, v3
	v_mul_f32_e32 v3, v7, v7
	v_mul_f32_e32 v1, v1, v1
	v_fmac_f32_e32 v3, v6, v6
	v_fmac_f32_e32 v1, v0, v0
	v_add_f32_e32 v0, v3, v1
	v_add_f32_e32 v0, v2, v0
	v_mul_f32_e32 v1, v21, v21
	v_mul_f32_e32 v2, v11, v11
	v_fmac_f32_e32 v1, v20, v20
	v_fmac_f32_e32 v2, v10, v10
	v_add_f32_e32 v1, v1, v2
	v_add_f32_e32 v0, v0, v1
	v_mul_f32_e32 v1, v9, v9
	v_mul_f32_e32 v2, v5, v5
	v_fmac_f32_e32 v1, v8, v8
	v_fmac_f32_e32 v2, v4, v4
	v_add_f32_e32 v1, v1, v2
	v_and_b32_e32 v2, 64, v251
	v_add_f32_e32 v0, v0, v1
	v_xor_b32_e32 v1, 16, v251
	v_add_u32_e32 v2, 64, v2
	v_cmp_lt_i32_e32 vcc, v1, v2
	s_nop 1
	v_cndmask_b32_e32 v1, v251, v1, vcc
	v_lshlrev_b32_e32 v1, 2, v1
	ds_bpermute_b32 v1, v1, v0
	s_waitcnt lgkmcnt(0)
	v_add_f32_e32 v0, v0, v1
	v_xor_b32_e32 v1, 32, v251
	v_cmp_lt_i32_e32 vcc, v1, v2
	s_nop 1
	v_cndmask_b32_e32 v1, v251, v1, vcc
	v_lshlrev_b32_e32 v1, 2, v1
	v_mov_b32_e32 v1, v0
	v_mov_b32_e32 v245, v0
	s_nop 1
	v_permlane32_swap_b32_e32 v1, v245
	s_and_saveexec_b64 s[8:9], s[4:5]
	s_cbranch_execz .LBB0_600
	v_lshlrev_b64 v[2:3], 8, v[12:13]
	v_lshl_add_u64 v[2:3], s[14:15], 0, v[2:3]
	v_lshl_add_u64 v[2:3], s[16:17], 2, v[2:3]
	s_lshl_b32 s18, s27, 2
	v_lshl_add_u64 v[2:3], v[2:3], 0, s[18:19]
	s_waitcnt lgkmcnt(0)
	v_add_f32_e32 v0, v1, v245
	global_store_dword v[2:3], v0, off

; __device__ __forceinline__ unsigned pk2(float lo, float hi) { f32x2 v = {lo, hi}; bf16x2_t b = __builtin_convertvector(v, bf16x2_t); return __builtin_bit_cast(unsigned, b); }
; __device__ __forceinline__ float bflo(unsigned w) { return __uint_as_float(w << 16); }
; __device__ __forceinline__ float bfhi(unsigned w) { return __uint_as_float(w & 0xffff0000u); }
;     __device__ __forceinline__ void operator()(const f32x4 (&acc)[2][2][4][2], const Unit& u, int wr, int wc, int fr, int fq) const {
;     ...
;                 for (int n = 0; n < 2; ++n) { const int cc = bj * HALF + 4 * n;
;                     f32x4 v = acc[ai][bj][m][n];
;                     if (bias) { v = (v + *(const f32x4*)(bias + col0 + cc)) * *(const f32x4*)(scale + col0 + cc); }
;                     f32x4 b;
;                     if (MODE >= 3) b = (f32x4){0.f, 0.f, 0.f, 0.f};
;                     else if (MODE == 0) b = __builtin_bit_cast(f32x4, cur[bj][n]);
;                     else { const unsigned w0 = n ? cur[bj][0].z : cur[bj][0].x, w1 = n ? cur[bj][0].w : cur[bj][0].y; b = (f32x4){bflo(w0), bfhi(w0), bflo(w1), bfhi(w1)}; }
;                     o[n] = b + v;
;                     if (MODE == 2 || MODE == 4) *(f32x4*)(out + off + cc) = o[n];
;                     ss += (o[n][0] * o[n][0] + o[n][1] * o[n][1]) + (o[n][2] * o[n][2] + o[n][3] * o[n][3]); }
;                 if (MODE != 2 && MODE != 4) { u32x4 w; w.x = pk2(o[0][0], o[0][1]); w.y = pk2(o[0][2], o[0][3]); w.z = pk2(o[1][0], o[1][1]); w.w = pk2(o[1][2], o[1][3]); *(u32x4*)(xb + off + bj * HALF) = w; } }
;             if (MODE != 2 && MODE != 4 && rsq) { ss += __shfl_xor(ss, 16); ss += __shfl_xor(ss, 32); if (fq == 0) rsq[(size_t)row * 64 + u.pn * 4 + wc] = ss; }
.LBB0_778:
	v_lshlrev_b32_e32 v150, 16, v146
	v_and_b32_e32 v151, 0xffff0000, v146
	v_lshlrev_b32_e32 v146, 16, v147
	v_and_b32_e32 v147, 0xffff0000, v147
	v_pk_add_f32 v[120:121], v[120:121], v[146:147]
	v_lshlrev_b32_e32 v146, 16, v148
	v_and_b32_e32 v147, 0xffff0000, v148
	v_lshlrev_b32_e32 v148, 16, v149
	v_and_b32_e32 v149, 0xffff0000, v149
	v_pk_add_f32 v[118:119], v[118:119], v[150:151]
	s_lshl_b32 s78, s10, 2
	v_pk_add_f32 v[116:117], v[116:117], v[148:149]
	v_pk_add_f32 v[114:115], v[114:115], v[146:147]
	v_cndmask_b32_e64 v150, 0, 1, s[68:69]
	s_ashr_i32 s79, s78, 31
	v_cvt_pk_bf16_f32 v146, v118, v119
	v_cvt_pk_bf16_f32 v147, v120, v121
	v_cvt_pk_bf16_f32 v148, v114, v115
	v_cvt_pk_bf16_f32 v149, v116, v117
	v_cmp_ne_u32_e64 s[10:11], 1, v150
	s_andn2_b64 vcc, exec, s[68:69]
	global_store_dwordx4 v[182:183], v[146:149], off offset:256
	s_cbranch_vccnz .LBB0_782
	v_mul_f32_e32 v131, v131, v131
	v_mul_f32_e32 v127, v127, v127
	v_mul_f32_e32 v115, v115, v115
	v_fmac_f32_e32 v131, v130, v130
	v_mul_f32_e32 v130, v133, v133
	v_fmac_f32_e32 v127, v126, v126
	v_mul_f32_e32 v126, v129, v129
	v_mul_f32_e32 v119, v119, v119
	v_fmac_f32_e32 v115, v114, v114
	v_mul_f32_e32 v114, v117, v117
	v_fmac_f32_e32 v130, v132, v132
	v_fmac_f32_e32 v126, v128, v128
	v_fmac_f32_e32 v119, v118, v118
	v_mul_f32_e32 v118, v121, v121
	v_fmac_f32_e32 v114, v116, v116
	v_and_b32_e32 v116, 64, v251
	v_add_f32_e32 v130, v131, v130
	v_add_f32_e32 v126, v127, v126
	v_fmac_f32_e32 v118, v120, v120
	v_add_f32_e32 v114, v115, v114
	v_xor_b32_e32 v115, 16, v251
	v_add_u32_e32 v116, 64, v116
	v_add_f32_e32 v126, v130, v126
	v_add_f32_e32 v118, v119, v118
	v_cmp_lt_i32_e32 vcc, v115, v116
	v_add_f32_e32 v118, v126, v118
	v_add_f32_e32 v114, v118, v114
	v_cndmask_b32_e32 v115, v251, v115, vcc
	v_lshlrev_b32_e32 v115, 2, v115
	ds_bpermute_b32 v115, v115, v114
	s_waitcnt lgkmcnt(0)
	v_add_f32_e32 v114, v114, v115
	v_xor_b32_e32 v115, 32, v251
	v_cmp_lt_i32_e32 vcc, v115, v116
	s_nop 1
	v_cndmask_b32_e32 v115, v251, v115, vcc
	v_lshlrev_b32_e32 v115, 2, v115
	v_mov_b32_e32 v115, v114
	v_mov_b32_e32 v245, v114
	s_nop 1
	v_permlane32_swap_b32_e32 v115, v245
	s_and_saveexec_b64 s[16:17], s[4:5]
	s_cbranch_execz .LBB0_781
	v_lshlrev_b64 v[116:117], 8, v[176:177]
	v_lshl_add_u64 v[116:117], s[62:63], 0, v[116:117]
	v_lshl_add_u64 v[116:117], s[78:79], 2, v[116:117]
	s_lshl_b32 s18, s28, 2
	v_lshl_add_u64 v[116:117], v[116:117], 0, s[18:19]
	s_waitcnt lgkmcnt(0)
	v_add_f32_e32 v114, v115, v245
	global_store_dword v[116:117], v114, off

; __device__ __forceinline__ unsigned pk2(float lo, float hi) { f32x2 v = {lo, hi}; bf16x2_t b = __builtin_convertvector(v, bf16x2_t); return __builtin_bit_cast(unsigned, b); }
; __device__ __forceinline__ float bflo(unsigned w) { return __uint_as_float(w << 16); }
; __device__ __forceinline__ float bfhi(unsigned w) { return __uint_as_float(w & 0xffff0000u); }
;     __device__ __forceinline__ void operator()(const f32x4 (&acc)[2][2][4][2], const Unit& u, int wr, int wc, int fr, int fq) const {
;     ...
;                 for (int n = 0; n < 2; ++n) { const int cc = bj * HALF + 4 * n;
;                     f32x4 v = acc[ai][bj][m][n];
;                     if (bias) { v = (v + *(const f32x4*)(bias + col0 + cc)) * *(const f32x4*)(scale + col0 + cc); }
;                     f32x4 b;
;                     if (MODE >= 3) b = (f32x4){0.f, 0.f, 0.f, 0.f};
;                     else if (MODE == 0) b = __builtin_bit_cast(f32x4, cur[bj][n]);
;                     else { const unsigned w0 = n ? cur[bj][0].z : cur[bj][0].x, w1 = n ? cur[bj][0].w : cur[bj][0].y; b = (f32x4){bflo(w0), bfhi(w0), bflo(w1), bfhi(w1)}; }
;                     o[n] = b + v;
;                     if (MODE == 2 || MODE == 4) *(f32x4*)(out + off + cc) = o[n];
;                     ss += (o[n][0] * o[n][0] + o[n][1] * o[n][1]) + (o[n][2] * o[n][2] + o[n][3] * o[n][3]); }
;                 if (MODE != 2 && MODE != 4) { u32x4 w; w.x = pk2(o[0][0], o[0][1]); w.y = pk2(o[0][2], o[0][3]); w.z = pk2(o[1][0], o[1][1]); w.w = pk2(o[1][2], o[1][3]); *(u32x4*)(xb + off + bj * HALF) = w; } }
;             if (MODE != 2 && MODE != 4 && rsq) { ss += __shfl_xor(ss, 16); ss += __shfl_xor(ss, 32); if (fq == 0) rsq[(size_t)row * 64 + u.pn * 4 + wc] = ss; }
.LBB0_790:
	v_lshlrev_b32_e32 v130, 16, v138
	v_and_b32_e32 v131, 0xffff0000, v138
	v_lshlrev_b32_e32 v132, 16, v139
	v_and_b32_e32 v133, 0xffff0000, v139
	v_pk_add_f32 v[104:105], v[104:105], v[132:133]
	v_pk_add_f32 v[102:103], v[102:103], v[130:131]
	v_lshlrev_b32_e32 v130, 16, v140
	v_and_b32_e32 v131, 0xffff0000, v140
	v_lshlrev_b32_e32 v132, 16, v141
	v_and_b32_e32 v133, 0xffff0000, v141
	v_pk_add_f32 v[100:101], v[100:101], v[132:133]
	v_pk_add_f32 v[98:99], v[98:99], v[130:131]
	v_cvt_pk_bf16_f32 v130, v102, v103
	v_cvt_pk_bf16_f32 v131, v104, v105
	v_cvt_pk_bf16_f32 v132, v98, v99
	v_cvt_pk_bf16_f32 v133, v100, v101
	s_and_b64 vcc, exec, s[10:11]
	global_store_dwordx4 v[180:181], v[130:133], off offset:256
	s_cbranch_vccnz .LBB0_794
	v_mul_f32_e32 v111, v111, v111
	v_mul_f32_e32 v107, v107, v107
	v_mul_f32_e32 v99, v99, v99
	v_fmac_f32_e32 v111, v110, v110
	v_mul_f32_e32 v110, v113, v113
	v_fmac_f32_e32 v107, v106, v106
	v_mul_f32_e32 v106, v109, v109
	v_mul_f32_e32 v103, v103, v103
	v_fmac_f32_e32 v99, v98, v98
	v_mul_f32_e32 v98, v101, v101
	v_fmac_f32_e32 v110, v112, v112
	v_fmac_f32_e32 v106, v108, v108
	v_fmac_f32_e32 v103, v102, v102
	v_mul_f32_e32 v102, v105, v105
	v_fmac_f32_e32 v98, v100, v100
	v_and_b32_e32 v100, 64, v251
	v_add_f32_e32 v110, v111, v110
	v_add_f32_e32 v106, v107, v106
	v_fmac_f32_e32 v102, v104, v104
	v_add_f32_e32 v98, v99, v98
	v_xor_b32_e32 v99, 16, v251
	v_add_u32_e32 v100, 64, v100
	v_add_f32_e32 v106, v110, v106
	v_add_f32_e32 v102, v103, v102
	v_cmp_lt_i32_e32 vcc, v99, v100
	v_add_f32_e32 v102, v106, v102
	v_add_f32_e32 v98, v102, v98
	v_cndmask_b32_e32 v99, v251, v99, vcc
	v_lshlrev_b32_e32 v99, 2, v99
	ds_bpermute_b32 v99, v99, v98
	s_waitcnt lgkmcnt(0)
	v_add_f32_e32 v98, v98, v99
	v_xor_b32_e32 v99, 32, v251
	v_cmp_lt_i32_e32 vcc, v99, v100
	s_nop 1
	v_cndmask_b32_e32 v99, v251, v99, vcc
	v_lshlrev_b32_e32 v99, 2, v99
	v_mov_b32_e32 v99, v98
	v_mov_b32_e32 v245, v98
	s_nop 1
	v_permlane32_swap_b32_e32 v99, v245
	s_and_saveexec_b64 s[16:17], s[4:5]
	s_cbranch_execz .LBB0_793
	v_lshlrev_b64 v[100:101], 8, v[178:179]
	v_lshl_add_u64 v[100:101], s[62:63], 0, v[100:101]
	v_lshl_add_u64 v[100:101], s[78:79], 2, v[100:101]
	s_lshl_b32 s18, s28, 2
	v_lshl_add_u64 v[100:101], v[100:101], 0, s[18:19]
	s_waitcnt lgkmcnt(0)
	v_add_f32_e32 v98, v99, v245
	global_store_dword v[100:101], v98, off

; __device__ __forceinline__ unsigned pk2(float lo, float hi) { f32x2 v = {lo, hi}; bf16x2_t b = __builtin_convertvector(v, bf16x2_t); return __builtin_bit_cast(unsigned, b); }
; __device__ __forceinline__ float bflo(unsigned w) { return __uint_as_float(w << 16); }
; __device__ __forceinline__ float bfhi(unsigned w) { return __uint_as_float(w & 0xffff0000u); }
;     __device__ __forceinline__ void operator()(const f32x4 (&acc)[2][2][4][2], const Unit& u, int wr, int wc, int fr, int fq) const {
;     ...
;                 for (int n = 0; n < 2; ++n) { const int cc = bj * HALF + 4 * n;
;                     f32x4 v = acc[ai][bj][m][n];
;                     if (bias) { v = (v + *(const f32x4*)(bias + col0 + cc)) * *(const f32x4*)(scale + col0 + cc); }
;                     f32x4 b;
;                     if (MODE >= 3) b = (f32x4){0.f, 0.f, 0.f, 0.f};
;                     else if (MODE == 0) b = __builtin_bit_cast(f32x4, cur[bj][n]);
;                     else { const unsigned w0 = n ? cur[bj][0].z : cur[bj][0].x, w1 = n ? cur[bj][0].w : cur[bj][0].y; b = (f32x4){bflo(w0), bfhi(w0), bflo(w1), bfhi(w1)}; }
;                     o[n] = b + v;
;                     if (MODE == 2 || MODE == 4) *(f32x4*)(out + off + cc) = o[n];
;                     ss += (o[n][0] * o[n][0] + o[n][1] * o[n][1]) + (o[n][2] * o[n][2] + o[n][3] * o[n][3]); }
;                 if (MODE != 2 && MODE != 4) { u32x4 w; w.x = pk2(o[0][0], o[0][1]); w.y = pk2(o[0][2], o[0][3]); w.z = pk2(o[1][0], o[1][1]); w.w = pk2(o[1][2], o[1][3]); *(u32x4*)(xb + off + bj * HALF) = w; } }
;             if (MODE != 2 && MODE != 4 && rsq) { ss += __shfl_xor(ss, 16); ss += __shfl_xor(ss, 32); if (fq == 0) rsq[(size_t)row * 64 + u.pn * 4 + wc] = ss; }
.LBB0_802:
	v_lshlrev_b32_e32 v110, 16, v122
	v_and_b32_e32 v111, 0xffff0000, v122
	v_lshlrev_b32_e32 v112, 16, v123
	v_and_b32_e32 v113, 0xffff0000, v123
	v_pk_add_f32 v[86:87], v[86:87], v[112:113]
	v_pk_add_f32 v[84:85], v[84:85], v[110:111]
	v_lshlrev_b32_e32 v110, 16, v124
	v_and_b32_e32 v111, 0xffff0000, v124
	v_lshlrev_b32_e32 v112, 16, v125
	v_and_b32_e32 v113, 0xffff0000, v125
	v_pk_add_f32 v[82:83], v[82:83], v[112:113]
	v_pk_add_f32 v[80:81], v[80:81], v[110:111]
	v_cvt_pk_bf16_f32 v110, v84, v85
	v_cvt_pk_bf16_f32 v111, v86, v87
	v_cvt_pk_bf16_f32 v112, v80, v81
	v_cvt_pk_bf16_f32 v113, v82, v83
	s_and_b64 vcc, exec, s[10:11]
	global_store_dwordx4 v[174:175], v[110:113], off offset:256
	s_cbranch_vccnz .LBB0_806
	v_mul_f32_e32 v93, v93, v93
	v_mul_f32_e32 v89, v89, v89
	v_mul_f32_e32 v81, v81, v81
	v_fmac_f32_e32 v93, v92, v92
	v_mul_f32_e32 v92, v95, v95
	v_fmac_f32_e32 v89, v88, v88
	v_mul_f32_e32 v88, v91, v91
	v_mul_f32_e32 v85, v85, v85
	v_fmac_f32_e32 v81, v80, v80
	v_mul_f32_e32 v80, v83, v83
	v_fmac_f32_e32 v92, v94, v94
	v_fmac_f32_e32 v88, v90, v90
	v_fmac_f32_e32 v85, v84, v84
	v_mul_f32_e32 v84, v87, v87
	v_fmac_f32_e32 v80, v82, v82
	v_and_b32_e32 v82, 64, v251
	v_add_f32_e32 v92, v93, v92
	v_add_f32_e32 v88, v89, v88
	v_fmac_f32_e32 v84, v86, v86
	v_add_f32_e32 v80, v81, v80
	v_xor_b32_e32 v81, 16, v251
	v_add_u32_e32 v82, 64, v82
	v_add_f32_e32 v88, v92, v88
	v_add_f32_e32 v84, v85, v84
	v_cmp_lt_i32_e32 vcc, v81, v82
	v_add_f32_e32 v84, v88, v84
	v_add_f32_e32 v80, v84, v80
	v_cndmask_b32_e32 v81, v251, v81, vcc
	v_lshlrev_b32_e32 v81, 2, v81
	ds_bpermute_b32 v81, v81, v80
	s_waitcnt lgkmcnt(0)
	v_add_f32_e32 v80, v80, v81
	v_xor_b32_e32 v81, 32, v251
	v_cmp_lt_i32_e32 vcc, v81, v82
	s_nop 1
	v_cndmask_b32_e32 v81, v251, v81, vcc
	v_lshlrev_b32_e32 v81, 2, v81
	v_mov_b32_e32 v81, v80
	v_mov_b32_e32 v245, v80
	s_nop 1
	v_permlane32_swap_b32_e32 v81, v245
	s_and_saveexec_b64 s[16:17], s[4:5]
	s_cbranch_execz .LBB0_805
	v_lshlrev_b64 v[82:83], 8, v[172:173]
	v_lshl_add_u64 v[82:83], s[62:63], 0, v[82:83]
	v_lshl_add_u64 v[82:83], s[78:79], 2, v[82:83]
	s_lshl_b32 s18, s28, 2
	v_lshl_add_u64 v[82:83], v[82:83], 0, s[18:19]
	s_waitcnt lgkmcnt(0)
	v_add_f32_e32 v80, v81, v245
	global_store_dword v[82:83], v80, off

; __device__ __forceinline__ unsigned pk2(float lo, float hi) { f32x2 v = {lo, hi}; bf16x2_t b = __builtin_convertvector(v, bf16x2_t); return __builtin_bit_cast(unsigned, b); }
; __device__ __forceinline__ float bflo(unsigned w) { return __uint_as_float(w << 16); }
; __device__ __forceinline__ float bfhi(unsigned w) { return __uint_as_float(w & 0xffff0000u); }
;     __device__ __forceinline__ void operator()(const f32x4 (&acc)[2][2][4][2], const Unit& u, int wr, int wc, int fr, int fq) const {
;     ...
;                 for (int n = 0; n < 2; ++n) { const int cc = bj * HALF + 4 * n;
;                     f32x4 v = acc[ai][bj][m][n];
;                     if (bias) { v = (v + *(const f32x4*)(bias + col0 + cc)) * *(const f32x4*)(scale + col0 + cc); }
;                     f32x4 b;
;                     if (MODE >= 3) b = (f32x4){0.f, 0.f, 0.f, 0.f};
;                     else if (MODE == 0) b = __builtin_bit_cast(f32x4, cur[bj][n]);
;                     else { const unsigned w0 = n ? cur[bj][0].z : cur[bj][0].x, w1 = n ? cur[bj][0].w : cur[bj][0].y; b = (f32x4){bflo(w0), bfhi(w0), bflo(w1), bfhi(w1)}; }
;                     o[n] = b + v;
;                     if (MODE == 2 || MODE == 4) *(f32x4*)(out + off + cc) = o[n];
;                     ss += (o[n][0] * o[n][0] + o[n][1] * o[n][1]) + (o[n][2] * o[n][2] + o[n][3] * o[n][3]); }
;                 if (MODE != 2 && MODE != 4) { u32x4 w; w.x = pk2(o[0][0], o[0][1]); w.y = pk2(o[0][2], o[0][3]); w.z = pk2(o[1][0], o[1][1]); w.w = pk2(o[1][2], o[1][3]); *(u32x4*)(xb + off + bj * HALF) = w; } }
;             if (MODE != 2 && MODE != 4 && rsq) { ss += __shfl_xor(ss, 16); ss += __shfl_xor(ss, 32); if (fq == 0) rsq[(size_t)row * 64 + u.pn * 4 + wc] = ss; }
.LBB0_814:
	s_waitcnt vmcnt(9)
	v_lshlrev_b32_e32 v90, 16, v114
	v_and_b32_e32 v91, 0xffff0000, v114
	v_lshlrev_b32_e32 v92, 16, v115
	v_and_b32_e32 v93, 0xffff0000, v115
	v_pk_add_f32 v[70:71], v[70:71], v[92:93]
	v_pk_add_f32 v[68:69], v[68:69], v[90:91]
	v_lshlrev_b32_e32 v90, 16, v116
	v_and_b32_e32 v91, 0xffff0000, v116
	v_lshlrev_b32_e32 v92, 16, v117
	v_and_b32_e32 v93, 0xffff0000, v117
	v_pk_add_f32 v[66:67], v[66:67], v[92:93]
	v_pk_add_f32 v[64:65], v[64:65], v[90:91]
	v_cvt_pk_bf16_f32 v90, v68, v69
	v_cvt_pk_bf16_f32 v91, v70, v71
	v_cvt_pk_bf16_f32 v92, v64, v65
	v_cvt_pk_bf16_f32 v93, v66, v67
	s_and_b64 vcc, exec, s[10:11]
	global_store_dwordx4 v[128:129], v[90:93], off offset:256
	s_cbranch_vccnz .LBB0_818
	v_mul_f32_e32 v77, v77, v77
	v_mul_f32_e32 v73, v73, v73
	v_mul_f32_e32 v65, v65, v65
	v_fmac_f32_e32 v77, v76, v76
	v_mul_f32_e32 v76, v79, v79
	v_fmac_f32_e32 v73, v72, v72
	v_mul_f32_e32 v72, v75, v75
	v_mul_f32_e32 v69, v69, v69
	v_fmac_f32_e32 v65, v64, v64
	v_mul_f32_e32 v64, v67, v67
	v_fmac_f32_e32 v76, v78, v78
	v_fmac_f32_e32 v72, v74, v74
	v_fmac_f32_e32 v69, v68, v68
	v_mul_f32_e32 v68, v71, v71
	v_fmac_f32_e32 v64, v66, v66
	v_and_b32_e32 v66, 64, v251
	v_add_f32_e32 v76, v77, v76
	v_add_f32_e32 v72, v73, v72
	v_fmac_f32_e32 v68, v70, v70
	v_add_f32_e32 v64, v65, v64
	v_xor_b32_e32 v65, 16, v251
	v_add_u32_e32 v66, 64, v66
	v_add_f32_e32 v72, v76, v72
	v_add_f32_e32 v68, v69, v68
	v_cmp_lt_i32_e32 vcc, v65, v66
	v_add_f32_e32 v68, v72, v68
	v_add_f32_e32 v64, v68, v64
	v_cndmask_b32_e32 v65, v251, v65, vcc
	v_lshlrev_b32_e32 v65, 2, v65
	ds_bpermute_b32 v65, v65, v64
	s_waitcnt lgkmcnt(0)
	v_add_f32_e32 v64, v64, v65
	v_xor_b32_e32 v65, 32, v251
	v_cmp_lt_i32_e32 vcc, v65, v66
	s_nop 1
	v_cndmask_b32_e32 v65, v251, v65, vcc
	v_lshlrev_b32_e32 v65, 2, v65
	v_mov_b32_e32 v65, v64
	v_mov_b32_e32 v245, v64
	s_nop 1
	v_permlane32_swap_b32_e32 v65, v245
	s_and_saveexec_b64 s[16:17], s[4:5]
	s_cbranch_execz .LBB0_817
	v_lshlrev_b64 v[66:67], 8, v[126:127]
	v_lshl_add_u64 v[66:67], s[62:63], 0, v[66:67]
	v_lshl_add_u64 v[66:67], s[78:79], 2, v[66:67]
	s_lshl_b32 s18, s28, 2
	v_lshl_add_u64 v[66:67], v[66:67], 0, s[18:19]
	s_waitcnt lgkmcnt(0)
	v_add_f32_e32 v64, v65, v245
	global_store_dword v[66:67], v64, off

; __device__ __forceinline__ unsigned pk2(float lo, float hi) { f32x2 v = {lo, hi}; bf16x2_t b = __builtin_convertvector(v, bf16x2_t); return __builtin_bit_cast(unsigned, b); }
; __device__ __forceinline__ float bflo(unsigned w) { return __uint_as_float(w << 16); }
; __device__ __forceinline__ float bfhi(unsigned w) { return __uint_as_float(w & 0xffff0000u); }
;     __device__ __forceinline__ void operator()(const f32x4 (&acc)[2][2][4][2], const Unit& u, int wr, int wc, int fr, int fq) const {
;     ...
;                 for (int n = 0; n < 2; ++n) { const int cc = bj * HALF + 4 * n;
;                     f32x4 v = acc[ai][bj][m][n];
;                     if (bias) { v = (v + *(const f32x4*)(bias + col0 + cc)) * *(const f32x4*)(scale + col0 + cc); }
;                     f32x4 b;
;                     if (MODE >= 3) b = (f32x4){0.f, 0.f, 0.f, 0.f};
;                     else if (MODE == 0) b = __builtin_bit_cast(f32x4, cur[bj][n]);
;                     else { const unsigned w0 = n ? cur[bj][0].z : cur[bj][0].x, w1 = n ? cur[bj][0].w : cur[bj][0].y; b = (f32x4){bflo(w0), bfhi(w0), bflo(w1), bfhi(w1)}; }
;                     o[n] = b + v;
;                     if (MODE == 2 || MODE == 4) *(f32x4*)(out + off + cc) = o[n];
;                     ss += (o[n][0] * o[n][0] + o[n][1] * o[n][1]) + (o[n][2] * o[n][2] + o[n][3] * o[n][3]); }
;                 if (MODE != 2 && MODE != 4) { u32x4 w; w.x = pk2(o[0][0], o[0][1]); w.y = pk2(o[0][2], o[0][3]); w.z = pk2(o[1][0], o[1][1]); w.w = pk2(o[1][2], o[1][3]); *(u32x4*)(xb + off + bj * HALF) = w; } }
;             if (MODE != 2 && MODE != 4 && rsq) { ss += __shfl_xor(ss, 16); ss += __shfl_xor(ss, 32); if (fq == 0) rsq[(size_t)row * 64 + u.pn * 4 + wc] = ss; }
.LBB0_826:
	s_waitcnt vmcnt(9)
	v_lshlrev_b32_e32 v76, 16, v98
	v_and_b32_e32 v77, 0xffff0000, v98
	v_lshlrev_b32_e32 v78, 16, v99
	v_and_b32_e32 v79, 0xffff0000, v99
	v_pk_add_f32 v[54:55], v[54:55], v[78:79]
	v_pk_add_f32 v[52:53], v[52:53], v[76:77]
	v_lshlrev_b32_e32 v76, 16, v100
	v_and_b32_e32 v77, 0xffff0000, v100
	v_lshlrev_b32_e32 v78, 16, v101
	v_and_b32_e32 v79, 0xffff0000, v101
	v_pk_add_f32 v[50:51], v[50:51], v[78:79]
	v_pk_add_f32 v[48:49], v[48:49], v[76:77]
	v_cvt_pk_bf16_f32 v76, v52, v53
	v_cvt_pk_bf16_f32 v77, v54, v55
	v_cvt_pk_bf16_f32 v78, v48, v49
	v_cvt_pk_bf16_f32 v79, v50, v51
	s_and_b64 vcc, exec, s[10:11]
	global_store_dwordx4 v[108:109], v[76:79], off offset:256
	s_cbranch_vccnz .LBB0_830
	v_mul_f32_e32 v61, v61, v61
	v_mul_f32_e32 v57, v57, v57
	v_mul_f32_e32 v49, v49, v49
	v_fmac_f32_e32 v61, v60, v60
	v_mul_f32_e32 v60, v63, v63
	v_fmac_f32_e32 v57, v56, v56
	v_mul_f32_e32 v56, v59, v59
	v_mul_f32_e32 v53, v53, v53
	v_fmac_f32_e32 v49, v48, v48
	v_mul_f32_e32 v48, v51, v51
	v_fmac_f32_e32 v60, v62, v62
	v_fmac_f32_e32 v56, v58, v58
	v_fmac_f32_e32 v53, v52, v52
	v_mul_f32_e32 v52, v55, v55
	v_fmac_f32_e32 v48, v50, v50
	v_and_b32_e32 v50, 64, v251
	v_add_f32_e32 v60, v61, v60
	v_add_f32_e32 v56, v57, v56
	v_fmac_f32_e32 v52, v54, v54
	v_add_f32_e32 v48, v49, v48
	v_xor_b32_e32 v49, 16, v251
	v_add_u32_e32 v50, 64, v50
	v_add_f32_e32 v56, v60, v56
	v_add_f32_e32 v52, v53, v52
	v_cmp_lt_i32_e32 vcc, v49, v50
	v_add_f32_e32 v52, v56, v52
	v_add_f32_e32 v48, v52, v48
	v_cndmask_b32_e32 v49, v251, v49, vcc
	v_lshlrev_b32_e32 v49, 2, v49
	ds_bpermute_b32 v49, v49, v48
	s_waitcnt lgkmcnt(0)
	v_add_f32_e32 v48, v48, v49
	v_xor_b32_e32 v49, 32, v251
	v_cmp_lt_i32_e32 vcc, v49, v50
	s_nop 1
	v_cndmask_b32_e32 v49, v251, v49, vcc
	v_lshlrev_b32_e32 v49, 2, v49
	v_mov_b32_e32 v49, v48
	v_mov_b32_e32 v245, v48
	s_nop 1
	v_permlane32_swap_b32_e32 v49, v245
	s_and_saveexec_b64 s[16:17], s[4:5]
	s_cbranch_execz .LBB0_829
	v_lshlrev_b64 v[50:51], 8, v[106:107]
	v_lshl_add_u64 v[50:51], s[62:63], 0, v[50:51]
	v_lshl_add_u64 v[50:51], s[78:79], 2, v[50:51]
	s_lshl_b32 s18, s28, 2
	v_lshl_add_u64 v[50:51], v[50:51], 0, s[18:19]
	s_waitcnt lgkmcnt(0)
	v_add_f32_e32 v48, v49, v245
	global_store_dword v[50:51], v48, off

; __device__ __forceinline__ unsigned pk2(float lo, float hi) { f32x2 v = {lo, hi}; bf16x2_t b = __builtin_convertvector(v, bf16x2_t); return __builtin_bit_cast(unsigned, b); }
; __device__ __forceinline__ float bflo(unsigned w) { return __uint_as_float(w << 16); }
; __device__ __forceinline__ float bfhi(unsigned w) { return __uint_as_float(w & 0xffff0000u); }
;     __device__ __forceinline__ void operator()(const f32x4 (&acc)[2][2][4][2], const Unit& u, int wr, int wc, int fr, int fq) const {
;     ...
;                 for (int n = 0; n < 2; ++n) { const int cc = bj * HALF + 4 * n;
;                     f32x4 v = acc[ai][bj][m][n];
;                     if (bias) { v = (v + *(const f32x4*)(bias + col0 + cc)) * *(const f32x4*)(scale + col0 + cc); }
;                     f32x4 b;
;                     if (MODE >= 3) b = (f32x4){0.f, 0.f, 0.f, 0.f};
;                     else if (MODE == 0) b = __builtin_bit_cast(f32x4, cur[bj][n]);
;                     else { const unsigned w0 = n ? cur[bj][0].z : cur[bj][0].x, w1 = n ? cur[bj][0].w : cur[bj][0].y; b = (f32x4){bflo(w0), bfhi(w0), bflo(w1), bfhi(w1)}; }
;                     o[n] = b + v;
;                     if (MODE == 2 || MODE == 4) *(f32x4*)(out + off + cc) = o[n];
;                     ss += (o[n][0] * o[n][0] + o[n][1] * o[n][1]) + (o[n][2] * o[n][2] + o[n][3] * o[n][3]); }
;                 if (MODE != 2 && MODE != 4) { u32x4 w; w.x = pk2(o[0][0], o[0][1]); w.y = pk2(o[0][2], o[0][3]); w.z = pk2(o[1][0], o[1][1]); w.w = pk2(o[1][2], o[1][3]); *(u32x4*)(xb + off + bj * HALF) = w; } }
;             if (MODE != 2 && MODE != 4 && rsq) { ss += __shfl_xor(ss, 16); ss += __shfl_xor(ss, 32); if (fq == 0) rsq[(size_t)row * 64 + u.pn * 4 + wc] = ss; }
.LBB0_838:
	s_waitcnt vmcnt(9)
	v_lshlrev_b32_e32 v60, 16, v80
	v_and_b32_e32 v61, 0xffff0000, v80
	v_lshlrev_b32_e32 v62, 16, v81
	v_and_b32_e32 v63, 0xffff0000, v81
	v_pk_add_f32 v[38:39], v[38:39], v[62:63]
	v_pk_add_f32 v[36:37], v[36:37], v[60:61]
	v_lshlrev_b32_e32 v60, 16, v82
	v_and_b32_e32 v61, 0xffff0000, v82
	v_lshlrev_b32_e32 v62, 16, v83
	v_and_b32_e32 v63, 0xffff0000, v83
	v_pk_add_f32 v[34:35], v[34:35], v[62:63]
	v_pk_add_f32 v[32:33], v[32:33], v[60:61]
	v_cvt_pk_bf16_f32 v60, v36, v37
	v_cvt_pk_bf16_f32 v61, v38, v39
	v_cvt_pk_bf16_f32 v62, v32, v33
	v_cvt_pk_bf16_f32 v63, v34, v35
	s_and_b64 vcc, exec, s[10:11]
	global_store_dwordx4 v[88:89], v[60:63], off offset:256
	s_cbranch_vccnz .LBB0_842
	v_mul_f32_e32 v45, v45, v45
	v_mul_f32_e32 v41, v41, v41
	v_mul_f32_e32 v33, v33, v33
	v_fmac_f32_e32 v45, v44, v44
	v_mul_f32_e32 v44, v47, v47
	v_fmac_f32_e32 v41, v40, v40
	v_mul_f32_e32 v40, v43, v43
	v_mul_f32_e32 v37, v37, v37
	v_fmac_f32_e32 v33, v32, v32
	v_mul_f32_e32 v32, v35, v35
	v_fmac_f32_e32 v44, v46, v46
	v_fmac_f32_e32 v40, v42, v42
	v_fmac_f32_e32 v37, v36, v36
	v_mul_f32_e32 v36, v39, v39
	v_fmac_f32_e32 v32, v34, v34
	v_and_b32_e32 v34, 64, v251
	v_add_f32_e32 v44, v45, v44
	v_add_f32_e32 v40, v41, v40
	v_fmac_f32_e32 v36, v38, v38
	v_add_f32_e32 v32, v33, v32
	v_xor_b32_e32 v33, 16, v251
	v_add_u32_e32 v34, 64, v34
	v_add_f32_e32 v40, v44, v40
	v_add_f32_e32 v36, v37, v36
	v_cmp_lt_i32_e32 vcc, v33, v34
	v_add_f32_e32 v36, v40, v36
	v_add_f32_e32 v32, v36, v32
	v_cndmask_b32_e32 v33, v251, v33, vcc
	v_lshlrev_b32_e32 v33, 2, v33
	ds_bpermute_b32 v33, v33, v32
	s_waitcnt lgkmcnt(0)
	v_add_f32_e32 v32, v32, v33
	v_xor_b32_e32 v33, 32, v251
	v_cmp_lt_i32_e32 vcc, v33, v34
	s_nop 1
	v_cndmask_b32_e32 v33, v251, v33, vcc
	v_lshlrev_b32_e32 v33, 2, v33
	v_mov_b32_e32 v33, v32
	v_mov_b32_e32 v245, v32
	s_nop 1
	v_permlane32_swap_b32_e32 v33, v245
	s_and_saveexec_b64 s[16:17], s[4:5]
	s_cbranch_execz .LBB0_841
	v_or_b32_e32 v34, 16, v106
	v_ashrrev_i32_e32 v35, 31, v34
	v_lshlrev_b64 v[34:35], 8, v[34:35]
	v_lshl_add_u64 v[34:35], s[62:63], 0, v[34:35]
	v_lshl_add_u64 v[34:35], s[78:79], 2, v[34:35]
	s_lshl_b32 s18, s28, 2
	v_lshl_add_u64 v[34:35], v[34:35], 0, s[18:19]
	s_waitcnt lgkmcnt(0)
	v_add_f32_e32 v32, v33, v245
	global_store_dword v[34:35], v32, off

; __device__ __forceinline__ unsigned pk2(float lo, float hi) { f32x2 v = {lo, hi}; bf16x2_t b = __builtin_convertvector(v, bf16x2_t); return __builtin_bit_cast(unsigned, b); }
; __device__ __forceinline__ float bflo(unsigned w) { return __uint_as_float(w << 16); }
; __device__ __forceinline__ float bfhi(unsigned w) { return __uint_as_float(w & 0xffff0000u); }
;     __device__ __forceinline__ void operator()(const f32x4 (&acc)[2][2][4][2], const Unit& u, int wr, int wc, int fr, int fq) const {
;     ...
;                 for (int n = 0; n < 2; ++n) { const int cc = bj * HALF + 4 * n;
;                     f32x4 v = acc[ai][bj][m][n];
;                     if (bias) { v = (v + *(const f32x4*)(bias + col0 + cc)) * *(const f32x4*)(scale + col0 + cc); }
;                     f32x4 b;
;                     if (MODE >= 3) b = (f32x4){0.f, 0.f, 0.f, 0.f};
;                     else if (MODE == 0) b = __builtin_bit_cast(f32x4, cur[bj][n]);
;                     else { const unsigned w0 = n ? cur[bj][0].z : cur[bj][0].x, w1 = n ? cur[bj][0].w : cur[bj][0].y; b = (f32x4){bflo(w0), bfhi(w0), bflo(w1), bfhi(w1)}; }
;                     o[n] = b + v;
;                     if (MODE == 2 || MODE == 4) *(f32x4*)(out + off + cc) = o[n];
;                     ss += (o[n][0] * o[n][0] + o[n][1] * o[n][1]) + (o[n][2] * o[n][2] + o[n][3] * o[n][3]); }
;                 if (MODE != 2 && MODE != 4) { u32x4 w; w.x = pk2(o[0][0], o[0][1]); w.y = pk2(o[0][2], o[0][3]); w.z = pk2(o[1][0], o[1][1]); w.w = pk2(o[1][2], o[1][3]); *(u32x4*)(xb + off + bj * HALF) = w; } }
;             if (MODE != 2 && MODE != 4 && rsq) { ss += __shfl_xor(ss, 16); ss += __shfl_xor(ss, 32); if (fq == 0) rsq[(size_t)row * 64 + u.pn * 4 + wc] = ss; }
.LBB0_850:
	s_waitcnt vmcnt(7)
	v_lshlrev_b32_e32 v32, 16, v64
	v_and_b32_e32 v33, 0xffff0000, v64
	v_lshlrev_b32_e32 v34, 16, v65
	v_and_b32_e32 v35, 0xffff0000, v65
	v_pk_add_f32 v[22:23], v[22:23], v[34:35]
	v_pk_add_f32 v[20:21], v[20:21], v[32:33]
	v_lshlrev_b32_e32 v32, 16, v66
	v_and_b32_e32 v33, 0xffff0000, v66
	v_lshlrev_b32_e32 v34, 16, v67
	v_and_b32_e32 v35, 0xffff0000, v67
	v_pk_add_f32 v[18:19], v[18:19], v[34:35]
	v_pk_add_f32 v[16:17], v[16:17], v[32:33]
	v_cvt_pk_bf16_f32 v32, v20, v21
	v_cvt_pk_bf16_f32 v33, v22, v23
	v_cvt_pk_bf16_f32 v34, v16, v17
	v_cvt_pk_bf16_f32 v35, v18, v19
	s_and_b64 vcc, exec, s[10:11]
	global_store_dwordx4 v[74:75], v[32:35], off offset:256
	s_cbranch_vccnz .LBB0_854
	v_mul_f32_e32 v29, v29, v29
	v_mul_f32_e32 v25, v25, v25
	v_mul_f32_e32 v17, v17, v17
	v_fmac_f32_e32 v29, v28, v28
	v_mul_f32_e32 v28, v31, v31
	v_fmac_f32_e32 v25, v24, v24
	v_mul_f32_e32 v24, v27, v27
	v_mul_f32_e32 v21, v21, v21
	v_fmac_f32_e32 v17, v16, v16
	v_mul_f32_e32 v16, v19, v19
	v_fmac_f32_e32 v28, v30, v30
	v_fmac_f32_e32 v24, v26, v26
	v_fmac_f32_e32 v21, v20, v20
	v_mul_f32_e32 v20, v23, v23
	v_fmac_f32_e32 v16, v18, v18
	v_and_b32_e32 v18, 64, v251
	v_add_f32_e32 v28, v29, v28
	v_add_f32_e32 v24, v25, v24
	v_fmac_f32_e32 v20, v22, v22
	v_add_f32_e32 v16, v17, v16
	v_xor_b32_e32 v17, 16, v251
	v_add_u32_e32 v18, 64, v18
	v_add_f32_e32 v24, v28, v24
	v_add_f32_e32 v20, v21, v20
	v_cmp_lt_i32_e32 vcc, v17, v18
	v_add_f32_e32 v20, v24, v20
	v_add_f32_e32 v16, v20, v16
	v_cndmask_b32_e32 v17, v251, v17, vcc
	v_lshlrev_b32_e32 v17, 2, v17
	ds_bpermute_b32 v17, v17, v16
	s_waitcnt lgkmcnt(0)
	v_add_f32_e32 v16, v16, v17
	v_xor_b32_e32 v17, 32, v251
	v_cmp_lt_i32_e32 vcc, v17, v18
	s_nop 1
	v_cndmask_b32_e32 v17, v251, v17, vcc
	v_lshlrev_b32_e32 v17, 2, v17
	v_mov_b32_e32 v17, v16
	v_mov_b32_e32 v245, v16
	s_nop 1
	v_permlane32_swap_b32_e32 v17, v245
	s_and_saveexec_b64 s[16:17], s[4:5]
	s_cbranch_execz .LBB0_853
	v_lshlrev_b64 v[18:19], 8, v[72:73]
	v_lshl_add_u64 v[18:19], s[62:63], 0, v[18:19]
	v_lshl_add_u64 v[18:19], s[78:79], 2, v[18:19]
	s_lshl_b32 s18, s28, 2
	v_lshl_add_u64 v[18:19], v[18:19], 0, s[18:19]
	s_waitcnt lgkmcnt(0)
	v_add_f32_e32 v16, v17, v245
	global_store_dword v[18:19], v16, off

; __device__ __forceinline__ unsigned pk2(float lo, float hi) { f32x2 v = {lo, hi}; bf16x2_t b = __builtin_convertvector(v, bf16x2_t); return __builtin_bit_cast(unsigned, b); }
; __device__ __forceinline__ float bflo(unsigned w) { return __uint_as_float(w << 16); }
; __device__ __forceinline__ float bfhi(unsigned w) { return __uint_as_float(w & 0xffff0000u); }
;     __device__ __forceinline__ void operator()(const f32x4 (&acc)[2][2][4][2], const Unit& u, int wr, int wc, int fr, int fq) const {
;     ...
;                 for (int n = 0; n < 2; ++n) { const int cc = bj * HALF + 4 * n;
;                     f32x4 v = acc[ai][bj][m][n];
;                     if (bias) { v = (v + *(const f32x4*)(bias + col0 + cc)) * *(const f32x4*)(scale + col0 + cc); }
;                     f32x4 b;
;                     if (MODE >= 3) b = (f32x4){0.f, 0.f, 0.f, 0.f};
;                     else if (MODE == 0) b = __builtin_bit_cast(f32x4, cur[bj][n]);
;                     else { const unsigned w0 = n ? cur[bj][0].z : cur[bj][0].x, w1 = n ? cur[bj][0].w : cur[bj][0].y; b = (f32x4){bflo(w0), bfhi(w0), bflo(w1), bfhi(w1)}; }
;                     o[n] = b + v;
;                     if (MODE == 2 || MODE == 4) *(f32x4*)(out + off + cc) = o[n];
;                     ss += (o[n][0] * o[n][0] + o[n][1] * o[n][1]) + (o[n][2] * o[n][2] + o[n][3] * o[n][3]); }
;                 if (MODE != 2 && MODE != 4) { u32x4 w; w.x = pk2(o[0][0], o[0][1]); w.y = pk2(o[0][2], o[0][3]); w.z = pk2(o[1][0], o[1][1]); w.w = pk2(o[1][2], o[1][3]); *(u32x4*)(xb + off + bj * HALF) = w; } }
;             if (MODE != 2 && MODE != 4 && rsq) { ss += __shfl_xor(ss, 16); ss += __shfl_xor(ss, 32); if (fq == 0) rsq[(size_t)row * 64 + u.pn * 4 + wc] = ss; }
.LBB0_862:
	s_waitcnt vmcnt(5)
	v_lshlrev_b32_e32 v16, 16, v48
	v_and_b32_e32 v17, 0xffff0000, v48
	v_lshlrev_b32_e32 v18, 16, v49
	v_and_b32_e32 v19, 0xffff0000, v49
	v_pk_add_f32 v[6:7], v[6:7], v[18:19]
	v_pk_add_f32 v[4:5], v[4:5], v[16:17]
	v_lshlrev_b32_e32 v16, 16, v50
	v_and_b32_e32 v17, 0xffff0000, v50
	v_lshlrev_b32_e32 v18, 16, v51
	v_and_b32_e32 v19, 0xffff0000, v51
	v_pk_add_f32 v[2:3], v[2:3], v[18:19]
	v_pk_add_f32 v[0:1], v[0:1], v[16:17]
	v_cvt_pk_bf16_f32 v16, v4, v5
	v_cvt_pk_bf16_f32 v17, v6, v7
	v_cvt_pk_bf16_f32 v18, v0, v1
	v_cvt_pk_bf16_f32 v19, v2, v3
	s_and_b64 vcc, exec, s[10:11]
	global_store_dwordx4 v[58:59], v[16:19], off offset:256
	s_cbranch_vccnz .LBB0_866
	v_mul_f32_e32 v13, v13, v13
	v_mul_f32_e32 v9, v9, v9
	v_mul_f32_e32 v1, v1, v1
	v_fmac_f32_e32 v13, v12, v12
	v_mul_f32_e32 v12, v15, v15
	v_fmac_f32_e32 v9, v8, v8
	v_mul_f32_e32 v8, v11, v11
	v_mul_f32_e32 v5, v5, v5
	v_fmac_f32_e32 v1, v0, v0
	v_mul_f32_e32 v0, v3, v3
	v_fmac_f32_e32 v12, v14, v14
	v_fmac_f32_e32 v8, v10, v10
	v_fmac_f32_e32 v5, v4, v4
	v_mul_f32_e32 v4, v7, v7
	v_fmac_f32_e32 v0, v2, v2
	v_and_b32_e32 v2, 64, v251
	v_add_f32_e32 v12, v13, v12
	v_add_f32_e32 v8, v9, v8
	v_fmac_f32_e32 v4, v6, v6
	v_add_f32_e32 v0, v1, v0
	v_xor_b32_e32 v1, 16, v251
	v_add_u32_e32 v2, 64, v2
	v_add_f32_e32 v8, v12, v8
	v_add_f32_e32 v4, v5, v4
	v_cmp_lt_i32_e32 vcc, v1, v2
	v_add_f32_e32 v4, v8, v4
	v_add_f32_e32 v0, v4, v0
	v_cndmask_b32_e32 v1, v251, v1, vcc
	v_lshlrev_b32_e32 v1, 2, v1
	ds_bpermute_b32 v1, v1, v0
	s_waitcnt lgkmcnt(0)
	v_add_f32_e32 v0, v0, v1
	v_xor_b32_e32 v1, 32, v251
	v_cmp_lt_i32_e32 vcc, v1, v2
	s_nop 1
	v_cndmask_b32_e32 v1, v251, v1, vcc
	v_lshlrev_b32_e32 v1, 2, v1
	v_mov_b32_e32 v1, v0
	v_mov_b32_e32 v245, v0
	s_nop 1
	v_permlane32_swap_b32_e32 v1, v245
	s_and_saveexec_b64 s[8:9], s[4:5]
	s_cbranch_execz .LBB0_865
	v_lshlrev_b64 v[2:3], 8, v[56:57]
	v_lshl_add_u64 v[2:3], s[62:63], 0, v[2:3]
	v_lshl_add_u64 v[2:3], s[78:79], 2, v[2:3]
	s_lshl_b32 s18, s28, 2
	v_lshl_add_u64 v[2:3], v[2:3], 0, s[18:19]
	s_waitcnt lgkmcnt(0)
	v_add_f32_e32 v0, v1, v245
	global_store_dword v[2:3], v0, off

; __device__ __forceinline__ unsigned pk2(float lo, float hi) { f32x2 v = {lo, hi}; bf16x2_t b = __builtin_convertvector(v, bf16x2_t); return __builtin_bit_cast(unsigned, b); }
; __device__ __forceinline__ float bflo(unsigned w) { return __uint_as_float(w << 16); }
; __device__ __forceinline__ float bfhi(unsigned w) { return __uint_as_float(w & 0xffff0000u); }
;     __device__ __forceinline__ void operator()(const f32x4 (&acc)[2][2][4][2], const Unit& u, int wr, int wc, int fr, int fq) const {
;     ...
;                 for (int n = 0; n < 2; ++n) { const int cc = bj * HALF + 4 * n;
;                     f32x4 v = acc[ai][bj][m][n];
;                     if (bias) { v = (v + *(const f32x4*)(bias + col0 + cc)) * *(const f32x4*)(scale + col0 + cc); }
;                     f32x4 b;
;                     if (MODE >= 3) b = (f32x4){0.f, 0.f, 0.f, 0.f};
;                     else if (MODE == 0) b = __builtin_bit_cast(f32x4, cur[bj][n]);
;                     else { const unsigned w0 = n ? cur[bj][0].z : cur[bj][0].x, w1 = n ? cur[bj][0].w : cur[bj][0].y; b = (f32x4){bflo(w0), bfhi(w0), bflo(w1), bfhi(w1)}; }
;                     o[n] = b + v;
;                     if (MODE == 2 || MODE == 4) *(f32x4*)(out + off + cc) = o[n];
;                     ss += (o[n][0] * o[n][0] + o[n][1] * o[n][1]) + (o[n][2] * o[n][2] + o[n][3] * o[n][3]); }
;                 if (MODE != 2 && MODE != 4) { u32x4 w; w.x = pk2(o[0][0], o[0][1]); w.y = pk2(o[0][2], o[0][3]); w.z = pk2(o[1][0], o[1][1]); w.w = pk2(o[1][2], o[1][3]); *(u32x4*)(xb + off + bj * HALF) = w; } }
;             if (MODE != 2 && MODE != 4 && rsq) { ss += __shfl_xor(ss, 16); ss += __shfl_xor(ss, 32); if (fq == 0) rsq[(size_t)row * 64 + u.pn * 4 + wc] = ss; }
.LBB0_904:
	v_pk_add_f32 v[120:121], v[168:169], v[120:121]
	v_pk_add_f32 v[118:119], v[166:167], v[118:119]
	s_lshl_b32 s52, s10, 2
	v_pk_add_f32 v[116:117], v[164:165], v[116:117]
	v_pk_add_f32 v[114:115], v[162:163], v[114:115]
	v_cndmask_b32_e64 v166, 0, 1, s[70:71]
	s_ashr_i32 s53, s52, 31
	v_cvt_pk_bf16_f32 v162, v118, v119
	v_cvt_pk_bf16_f32 v163, v120, v121
	v_cvt_pk_bf16_f32 v164, v114, v115
	v_cvt_pk_bf16_f32 v165, v116, v117
	v_cmp_ne_u32_e64 s[10:11], 1, v166
	s_andn2_b64 vcc, exec, s[70:71]
	global_store_dwordx4 v[170:171], v[162:165], off offset:256
	s_cbranch_vccnz .LBB0_908
	v_mul_f32_e32 v135, v135, v135
	v_mul_f32_e32 v127, v127, v127
	v_mul_f32_e32 v115, v115, v115
	v_fmac_f32_e32 v135, v134, v134
	v_mul_f32_e32 v134, v137, v137
	v_fmac_f32_e32 v127, v126, v126
	v_mul_f32_e32 v126, v129, v129
	v_mul_f32_e32 v119, v119, v119
	v_fmac_f32_e32 v115, v114, v114
	v_mul_f32_e32 v114, v117, v117
	v_fmac_f32_e32 v134, v136, v136
	v_fmac_f32_e32 v126, v128, v128
	v_fmac_f32_e32 v119, v118, v118
	v_mul_f32_e32 v118, v121, v121
	v_fmac_f32_e32 v114, v116, v116
	v_and_b32_e32 v116, 64, v251
	v_add_f32_e32 v134, v135, v134
	v_add_f32_e32 v126, v127, v126
	v_fmac_f32_e32 v118, v120, v120
	v_add_f32_e32 v114, v115, v114
	v_xor_b32_e32 v115, 16, v251
	v_add_u32_e32 v116, 64, v116
	v_add_f32_e32 v126, v134, v126
	v_add_f32_e32 v118, v119, v118
	v_cmp_lt_i32_e32 vcc, v115, v116
	v_add_f32_e32 v118, v126, v118
	v_add_f32_e32 v114, v118, v114
	v_cndmask_b32_e32 v115, v251, v115, vcc
	v_lshlrev_b32_e32 v115, 2, v115
	ds_bpermute_b32 v115, v115, v114
	s_waitcnt lgkmcnt(0)
	v_add_f32_e32 v114, v114, v115
	v_xor_b32_e32 v115, 32, v251
	v_cmp_lt_i32_e32 vcc, v115, v116
	s_nop 1
	v_cndmask_b32_e32 v115, v251, v115, vcc
	v_lshlrev_b32_e32 v115, 2, v115
	v_mov_b32_e32 v115, v114
	v_mov_b32_e32 v245, v114
	s_nop 1
	v_permlane32_swap_b32_e32 v115, v245
	s_and_saveexec_b64 s[16:17], s[4:5]
	s_cbranch_execz .LBB0_907
	v_lshlrev_b64 v[116:117], 8, v[198:199]
	v_lshl_add_u64 v[116:117], s[64:65], 0, v[116:117]
	v_lshl_add_u64 v[116:117], s[52:53], 2, v[116:117]
	s_lshl_b32 s18, s28, 2
	v_lshl_add_u64 v[116:117], v[116:117], 0, s[18:19]
	s_waitcnt lgkmcnt(0)
	v_add_f32_e32 v114, v115, v245
	global_store_dword v[116:117], v114, off

; __device__ __forceinline__ unsigned pk2(float lo, float hi) { f32x2 v = {lo, hi}; bf16x2_t b = __builtin_convertvector(v, bf16x2_t); return __builtin_bit_cast(unsigned, b); }
; __device__ __forceinline__ float bflo(unsigned w) { return __uint_as_float(w << 16); }
; __device__ __forceinline__ float bfhi(unsigned w) { return __uint_as_float(w & 0xffff0000u); }
;     __device__ __forceinline__ void operator()(const f32x4 (&acc)[2][2][4][2], const Unit& u, int wr, int wc, int fr, int fq) const {
;     ...
;                 for (int n = 0; n < 2; ++n) { const int cc = bj * HALF + 4 * n;
;                     f32x4 v = acc[ai][bj][m][n];
;                     if (bias) { v = (v + *(const f32x4*)(bias + col0 + cc)) * *(const f32x4*)(scale + col0 + cc); }
;                     f32x4 b;
;                     if (MODE >= 3) b = (f32x4){0.f, 0.f, 0.f, 0.f};
;                     else if (MODE == 0) b = __builtin_bit_cast(f32x4, cur[bj][n]);
;                     else { const unsigned w0 = n ? cur[bj][0].z : cur[bj][0].x, w1 = n ? cur[bj][0].w : cur[bj][0].y; b = (f32x4){bflo(w0), bfhi(w0), bflo(w1), bfhi(w1)}; }
;                     o[n] = b + v;
;                     if (MODE == 2 || MODE == 4) *(f32x4*)(out + off + cc) = o[n];
;                     ss += (o[n][0] * o[n][0] + o[n][1] * o[n][1]) + (o[n][2] * o[n][2] + o[n][3] * o[n][3]); }
;                 if (MODE != 2 && MODE != 4) { u32x4 w; w.x = pk2(o[0][0], o[0][1]); w.y = pk2(o[0][2], o[0][3]); w.z = pk2(o[1][0], o[1][1]); w.w = pk2(o[1][2], o[1][3]); *(u32x4*)(xb + off + bj * HALF) = w; } }
;             if (MODE != 2 && MODE != 4 && rsq) { ss += __shfl_xor(ss, 16); ss += __shfl_xor(ss, 32); if (fq == 0) rsq[(size_t)row * 64 + u.pn * 4 + wc] = ss; }
.LBB0_916:
	v_pk_add_f32 v[104:105], v[152:153], v[104:105]
	v_pk_add_f32 v[102:103], v[150:151], v[102:103]
	v_pk_add_f32 v[100:101], v[148:149], v[100:101]
	v_pk_add_f32 v[98:99], v[146:147], v[98:99]
	v_cvt_pk_bf16_f32 v146, v102, v103
	v_cvt_pk_bf16_f32 v147, v104, v105
	v_cvt_pk_bf16_f32 v148, v98, v99
	v_cvt_pk_bf16_f32 v149, v100, v101
	s_and_b64 vcc, exec, s[10:11]
	global_store_dwordx4 v[154:155], v[146:149], off offset:256
	s_cbranch_vccnz .LBB0_920
	v_mul_f32_e32 v111, v111, v111
	v_mul_f32_e32 v107, v107, v107
	v_mul_f32_e32 v99, v99, v99
	v_fmac_f32_e32 v111, v110, v110
	v_mul_f32_e32 v110, v113, v113
	v_fmac_f32_e32 v107, v106, v106
	v_mul_f32_e32 v106, v109, v109
	v_mul_f32_e32 v103, v103, v103
	v_fmac_f32_e32 v99, v98, v98
	v_mul_f32_e32 v98, v101, v101
	v_fmac_f32_e32 v110, v112, v112
	v_fmac_f32_e32 v106, v108, v108
	v_fmac_f32_e32 v103, v102, v102
	v_mul_f32_e32 v102, v105, v105
	v_fmac_f32_e32 v98, v100, v100
	v_and_b32_e32 v100, 64, v251
	v_add_f32_e32 v110, v111, v110
	v_add_f32_e32 v106, v107, v106
	v_fmac_f32_e32 v102, v104, v104
	v_add_f32_e32 v98, v99, v98
	v_xor_b32_e32 v99, 16, v251
	v_add_u32_e32 v100, 64, v100
	v_add_f32_e32 v106, v110, v106
	v_add_f32_e32 v102, v103, v102
	v_cmp_lt_i32_e32 vcc, v99, v100
	v_add_f32_e32 v102, v106, v102
	v_add_f32_e32 v98, v102, v98
	v_cndmask_b32_e32 v99, v251, v99, vcc
	v_lshlrev_b32_e32 v99, 2, v99
	ds_bpermute_b32 v99, v99, v98
	s_waitcnt lgkmcnt(0)
	v_add_f32_e32 v98, v98, v99
	v_xor_b32_e32 v99, 32, v251
	v_cmp_lt_i32_e32 vcc, v99, v100
	s_nop 1
	v_cndmask_b32_e32 v99, v251, v99, vcc
	v_lshlrev_b32_e32 v99, 2, v99
	v_mov_b32_e32 v99, v98
	v_mov_b32_e32 v245, v98
	s_nop 1
	v_permlane32_swap_b32_e32 v99, v245
	s_and_saveexec_b64 s[16:17], s[4:5]
	s_cbranch_execz .LBB0_919
	v_lshlrev_b64 v[100:101], 8, v[200:201]
	v_lshl_add_u64 v[100:101], s[64:65], 0, v[100:101]
	v_lshl_add_u64 v[100:101], s[52:53], 2, v[100:101]
	s_lshl_b32 s18, s28, 2
	v_lshl_add_u64 v[100:101], v[100:101], 0, s[18:19]
	s_waitcnt lgkmcnt(0)
	v_add_f32_e32 v98, v99, v245
	global_store_dword v[100:101], v98, off

; __device__ __forceinline__ unsigned pk2(float lo, float hi) { f32x2 v = {lo, hi}; bf16x2_t b = __builtin_convertvector(v, bf16x2_t); return __builtin_bit_cast(unsigned, b); }
; __device__ __forceinline__ float bflo(unsigned w) { return __uint_as_float(w << 16); }
; __device__ __forceinline__ float bfhi(unsigned w) { return __uint_as_float(w & 0xffff0000u); }
;     __device__ __forceinline__ void operator()(const f32x4 (&acc)[2][2][4][2], const Unit& u, int wr, int wc, int fr, int fq) const {
;     ...
;                 for (int n = 0; n < 2; ++n) { const int cc = bj * HALF + 4 * n;
;                     f32x4 v = acc[ai][bj][m][n];
;                     if (bias) { v = (v + *(const f32x4*)(bias + col0 + cc)) * *(const f32x4*)(scale + col0 + cc); }
;                     f32x4 b;
;                     if (MODE >= 3) b = (f32x4){0.f, 0.f, 0.f, 0.f};
;                     else if (MODE == 0) b = __builtin_bit_cast(f32x4, cur[bj][n]);
;                     else { const unsigned w0 = n ? cur[bj][0].z : cur[bj][0].x, w1 = n ? cur[bj][0].w : cur[bj][0].y; b = (f32x4){bflo(w0), bfhi(w0), bflo(w1), bfhi(w1)}; }
;                     o[n] = b + v;
;                     if (MODE == 2 || MODE == 4) *(f32x4*)(out + off + cc) = o[n];
;                     ss += (o[n][0] * o[n][0] + o[n][1] * o[n][1]) + (o[n][2] * o[n][2] + o[n][3] * o[n][3]); }
;                 if (MODE != 2 && MODE != 4) { u32x4 w; w.x = pk2(o[0][0], o[0][1]); w.y = pk2(o[0][2], o[0][3]); w.z = pk2(o[1][0], o[1][1]); w.w = pk2(o[1][2], o[1][3]); *(u32x4*)(xb + off + bj * HALF) = w; } }
;             if (MODE != 2 && MODE != 4 && rsq) { ss += __shfl_xor(ss, 16); ss += __shfl_xor(ss, 32); if (fq == 0) rsq[(size_t)row * 64 + u.pn * 4 + wc] = ss; }
.LBB0_928:
	v_pk_add_f32 v[86:87], v[132:133], v[86:87]
	v_pk_add_f32 v[84:85], v[130:131], v[84:85]
	v_pk_add_f32 v[82:83], v[124:125], v[82:83]
	v_pk_add_f32 v[80:81], v[122:123], v[80:81]
	v_cvt_pk_bf16_f32 v122, v84, v85
	v_cvt_pk_bf16_f32 v123, v86, v87
	v_cvt_pk_bf16_f32 v124, v80, v81
	v_cvt_pk_bf16_f32 v125, v82, v83
	s_and_b64 vcc, exec, s[10:11]
	global_store_dwordx4 v[138:139], v[122:125], off offset:256
	s_cbranch_vccnz .LBB0_932
	v_mul_f32_e32 v93, v93, v93
	v_mul_f32_e32 v89, v89, v89
	v_mul_f32_e32 v81, v81, v81
	v_fmac_f32_e32 v93, v92, v92
	v_mul_f32_e32 v92, v95, v95
	v_fmac_f32_e32 v89, v88, v88
	v_mul_f32_e32 v88, v91, v91
	v_mul_f32_e32 v85, v85, v85
	v_fmac_f32_e32 v81, v80, v80
	v_mul_f32_e32 v80, v83, v83
	v_fmac_f32_e32 v92, v94, v94
	v_fmac_f32_e32 v88, v90, v90
	v_fmac_f32_e32 v85, v84, v84
	v_mul_f32_e32 v84, v87, v87
	v_fmac_f32_e32 v80, v82, v82
	v_and_b32_e32 v82, 64, v251
	v_add_f32_e32 v92, v93, v92
	v_add_f32_e32 v88, v89, v88
	v_fmac_f32_e32 v84, v86, v86
	v_add_f32_e32 v80, v81, v80
	v_xor_b32_e32 v81, 16, v251
	v_add_u32_e32 v82, 64, v82
	v_add_f32_e32 v88, v92, v88
	v_add_f32_e32 v84, v85, v84
	v_cmp_lt_i32_e32 vcc, v81, v82
	v_add_f32_e32 v84, v88, v84
	v_add_f32_e32 v80, v84, v80
	v_cndmask_b32_e32 v81, v251, v81, vcc
	v_lshlrev_b32_e32 v81, 2, v81
	ds_bpermute_b32 v81, v81, v80
	s_waitcnt lgkmcnt(0)
	v_add_f32_e32 v80, v80, v81
	v_xor_b32_e32 v81, 32, v251
	v_cmp_lt_i32_e32 vcc, v81, v82
	s_nop 1
	v_cndmask_b32_e32 v81, v251, v81, vcc
	v_lshlrev_b32_e32 v81, 2, v81
	v_mov_b32_e32 v81, v80
	v_mov_b32_e32 v245, v80
	s_nop 1
	v_permlane32_swap_b32_e32 v81, v245
	s_and_saveexec_b64 s[16:17], s[4:5]
	s_cbranch_execz .LBB0_931
	v_lshlrev_b64 v[82:83], 8, v[196:197]
	v_lshl_add_u64 v[82:83], s[64:65], 0, v[82:83]
	v_lshl_add_u64 v[82:83], s[52:53], 2, v[82:83]
	s_lshl_b32 s18, s28, 2
	v_lshl_add_u64 v[82:83], v[82:83], 0, s[18:19]
	s_waitcnt lgkmcnt(0)
	v_add_f32_e32 v80, v81, v245
	global_store_dword v[82:83], v80, off

; __device__ __forceinline__ unsigned pk2(float lo, float hi) { f32x2 v = {lo, hi}; bf16x2_t b = __builtin_convertvector(v, bf16x2_t); return __builtin_bit_cast(unsigned, b); }
; __device__ __forceinline__ float bflo(unsigned w) { return __uint_as_float(w << 16); }
; __device__ __forceinline__ float bfhi(unsigned w) { return __uint_as_float(w & 0xffff0000u); }
;     __device__ __forceinline__ void operator()(const f32x4 (&acc)[2][2][4][2], const Unit& u, int wr, int wc, int fr, int fq) const {
;     ...
;                 for (int n = 0; n < 2; ++n) { const int cc = bj * HALF + 4 * n;
;                     f32x4 v = acc[ai][bj][m][n];
;                     if (bias) { v = (v + *(const f32x4*)(bias + col0 + cc)) * *(const f32x4*)(scale + col0 + cc); }
;                     f32x4 b;
;                     if (MODE >= 3) b = (f32x4){0.f, 0.f, 0.f, 0.f};
;                     else if (MODE == 0) b = __builtin_bit_cast(f32x4, cur[bj][n]);
;                     else { const unsigned w0 = n ? cur[bj][0].z : cur[bj][0].x, w1 = n ? cur[bj][0].w : cur[bj][0].y; b = (f32x4){bflo(w0), bfhi(w0), bflo(w1), bfhi(w1)}; }
;                     o[n] = b + v;
;                     if (MODE == 2 || MODE == 4) *(f32x4*)(out + off + cc) = o[n];
;                     ss += (o[n][0] * o[n][0] + o[n][1] * o[n][1]) + (o[n][2] * o[n][2] + o[n][3] * o[n][3]); }
;                 if (MODE != 2 && MODE != 4) { u32x4 w; w.x = pk2(o[0][0], o[0][1]); w.y = pk2(o[0][2], o[0][3]); w.z = pk2(o[1][0], o[1][1]); w.w = pk2(o[1][2], o[1][3]); *(u32x4*)(xb + off + bj * HALF) = w; } }
;             if (MODE != 2 && MODE != 4 && rsq) { ss += __shfl_xor(ss, 16); ss += __shfl_xor(ss, 32); if (fq == 0) rsq[(size_t)row * 64 + u.pn * 4 + wc] = ss; }
.LBB0_940:
	s_waitcnt vmcnt(13)
	v_pk_add_f32 v[70:71], v[120:121], v[70:71]
	v_pk_add_f32 v[68:69], v[118:119], v[68:69]
	v_pk_add_f32 v[66:67], v[116:117], v[66:67]
	v_pk_add_f32 v[64:65], v[114:115], v[64:65]
	v_cvt_pk_bf16_f32 v114, v68, v69
	v_cvt_pk_bf16_f32 v115, v70, v71
	v_cvt_pk_bf16_f32 v116, v64, v65
	v_cvt_pk_bf16_f32 v117, v66, v67
	s_and_b64 vcc, exec, s[10:11]
	global_store_dwordx4 v[122:123], v[114:117], off offset:256
	s_cbranch_vccnz .LBB0_944
	v_mul_f32_e32 v77, v77, v77
	v_mul_f32_e32 v73, v73, v73
	v_mul_f32_e32 v65, v65, v65
	v_fmac_f32_e32 v77, v76, v76
	v_mul_f32_e32 v76, v79, v79
	v_fmac_f32_e32 v73, v72, v72
	v_mul_f32_e32 v72, v75, v75
	v_mul_f32_e32 v69, v69, v69
	v_fmac_f32_e32 v65, v64, v64
	v_mul_f32_e32 v64, v67, v67
	v_fmac_f32_e32 v76, v78, v78
	v_fmac_f32_e32 v72, v74, v74
	v_fmac_f32_e32 v69, v68, v68
	v_mul_f32_e32 v68, v71, v71
	v_fmac_f32_e32 v64, v66, v66
	v_and_b32_e32 v66, 64, v251
	v_add_f32_e32 v76, v77, v76
	v_add_f32_e32 v72, v73, v72
	v_fmac_f32_e32 v68, v70, v70
	v_add_f32_e32 v64, v65, v64
	v_xor_b32_e32 v65, 16, v251
	v_add_u32_e32 v66, 64, v66
	v_add_f32_e32 v72, v76, v72
	v_add_f32_e32 v68, v69, v68
	v_cmp_lt_i32_e32 vcc, v65, v66
	v_add_f32_e32 v68, v72, v68
	v_add_f32_e32 v64, v68, v64
	v_cndmask_b32_e32 v65, v251, v65, vcc
	v_lshlrev_b32_e32 v65, 2, v65
	ds_bpermute_b32 v65, v65, v64
	s_waitcnt lgkmcnt(0)
	v_add_f32_e32 v64, v64, v65
	v_xor_b32_e32 v65, 32, v251
	v_cmp_lt_i32_e32 vcc, v65, v66
	s_nop 1
	v_cndmask_b32_e32 v65, v251, v65, vcc
	v_lshlrev_b32_e32 v65, 2, v65
	v_mov_b32_e32 v65, v64
	v_mov_b32_e32 v245, v64
	s_nop 1
	v_permlane32_swap_b32_e32 v65, v245
	s_and_saveexec_b64 s[16:17], s[4:5]
	s_cbranch_execz .LBB0_943
	v_lshlrev_b64 v[66:67], 8, v[162:163]
	v_lshl_add_u64 v[66:67], s[64:65], 0, v[66:67]
	v_lshl_add_u64 v[66:67], s[52:53], 2, v[66:67]
	s_lshl_b32 s18, s28, 2
	v_lshl_add_u64 v[66:67], v[66:67], 0, s[18:19]
	s_waitcnt lgkmcnt(0)
	v_add_f32_e32 v64, v65, v245
	global_store_dword v[66:67], v64, off

; __device__ __forceinline__ unsigned pk2(float lo, float hi) { f32x2 v = {lo, hi}; bf16x2_t b = __builtin_convertvector(v, bf16x2_t); return __builtin_bit_cast(unsigned, b); }
; __device__ __forceinline__ float bflo(unsigned w) { return __uint_as_float(w << 16); }
; __device__ __forceinline__ float bfhi(unsigned w) { return __uint_as_float(w & 0xffff0000u); }
;     __device__ __forceinline__ void operator()(const f32x4 (&acc)[2][2][4][2], const Unit& u, int wr, int wc, int fr, int fq) const {
;     ...
;                 for (int n = 0; n < 2; ++n) { const int cc = bj * HALF + 4 * n;
;                     f32x4 v = acc[ai][bj][m][n];
;                     if (bias) { v = (v + *(const f32x4*)(bias + col0 + cc)) * *(const f32x4*)(scale + col0 + cc); }
;                     f32x4 b;
;                     if (MODE >= 3) b = (f32x4){0.f, 0.f, 0.f, 0.f};
;                     else if (MODE == 0) b = __builtin_bit_cast(f32x4, cur[bj][n]);
;                     else { const unsigned w0 = n ? cur[bj][0].z : cur[bj][0].x, w1 = n ? cur[bj][0].w : cur[bj][0].y; b = (f32x4){bflo(w0), bfhi(w0), bflo(w1), bfhi(w1)}; }
;                     o[n] = b + v;
;                     if (MODE == 2 || MODE == 4) *(f32x4*)(out + off + cc) = o[n];
;                     ss += (o[n][0] * o[n][0] + o[n][1] * o[n][1]) + (o[n][2] * o[n][2] + o[n][3] * o[n][3]); }
;                 if (MODE != 2 && MODE != 4) { u32x4 w; w.x = pk2(o[0][0], o[0][1]); w.y = pk2(o[0][2], o[0][3]); w.z = pk2(o[1][0], o[1][1]); w.w = pk2(o[1][2], o[1][3]); *(u32x4*)(xb + off + bj * HALF) = w; } }
;             if (MODE != 2 && MODE != 4 && rsq) { ss += __shfl_xor(ss, 16); ss += __shfl_xor(ss, 32); if (fq == 0) rsq[(size_t)row * 64 + u.pn * 4 + wc] = ss; }
.LBB0_952:
	s_waitcnt vmcnt(13)
	v_pk_add_f32 v[54:55], v[104:105], v[54:55]
	v_pk_add_f32 v[52:53], v[102:103], v[52:53]
	v_pk_add_f32 v[50:51], v[100:101], v[50:51]
	v_pk_add_f32 v[48:49], v[98:99], v[48:49]
	v_cvt_pk_bf16_f32 v98, v52, v53
	v_cvt_pk_bf16_f32 v99, v54, v55
	v_cvt_pk_bf16_f32 v100, v48, v49
	v_cvt_pk_bf16_f32 v101, v50, v51
	s_and_b64 vcc, exec, s[10:11]
	global_store_dwordx4 v[106:107], v[98:101], off offset:256
	s_cbranch_vccnz .LBB0_956
	v_mul_f32_e32 v61, v61, v61
	v_mul_f32_e32 v57, v57, v57
	v_mul_f32_e32 v49, v49, v49
	v_fmac_f32_e32 v61, v60, v60
	v_mul_f32_e32 v60, v63, v63
	v_fmac_f32_e32 v57, v56, v56
	v_mul_f32_e32 v56, v59, v59
	v_mul_f32_e32 v53, v53, v53
	v_fmac_f32_e32 v49, v48, v48
	v_mul_f32_e32 v48, v51, v51
	v_fmac_f32_e32 v60, v62, v62
	v_fmac_f32_e32 v56, v58, v58
	v_fmac_f32_e32 v53, v52, v52
	v_mul_f32_e32 v52, v55, v55
	v_fmac_f32_e32 v48, v50, v50
	v_and_b32_e32 v50, 64, v251
	v_add_f32_e32 v60, v61, v60
	v_add_f32_e32 v56, v57, v56
	v_fmac_f32_e32 v52, v54, v54
	v_add_f32_e32 v48, v49, v48
	v_xor_b32_e32 v49, 16, v251
	v_add_u32_e32 v50, 64, v50
	v_add_f32_e32 v56, v60, v56
	v_add_f32_e32 v52, v53, v52
	v_cmp_lt_i32_e32 vcc, v49, v50
	v_add_f32_e32 v52, v56, v52
	v_add_f32_e32 v48, v52, v48
	v_cndmask_b32_e32 v49, v251, v49, vcc
	v_lshlrev_b32_e32 v49, 2, v49
	ds_bpermute_b32 v49, v49, v48
	s_waitcnt lgkmcnt(0)
	v_add_f32_e32 v48, v48, v49
	v_xor_b32_e32 v49, 32, v251
	v_cmp_lt_i32_e32 vcc, v49, v50
	s_nop 1
	v_cndmask_b32_e32 v49, v251, v49, vcc
	v_lshlrev_b32_e32 v49, 2, v49
	v_mov_b32_e32 v49, v48
	v_mov_b32_e32 v245, v48
	s_nop 1
	v_permlane32_swap_b32_e32 v49, v245
	s_and_saveexec_b64 s[16:17], s[4:5]
	s_cbranch_execz .LBB0_955
	v_lshlrev_b64 v[50:51], 8, v[146:147]
	v_lshl_add_u64 v[50:51], s[64:65], 0, v[50:51]
	v_lshl_add_u64 v[50:51], s[52:53], 2, v[50:51]
	s_lshl_b32 s18, s28, 2
	v_lshl_add_u64 v[50:51], v[50:51], 0, s[18:19]
	s_waitcnt lgkmcnt(0)
	v_add_f32_e32 v48, v49, v245
	global_store_dword v[50:51], v48, off

; __device__ __forceinline__ unsigned pk2(float lo, float hi) { f32x2 v = {lo, hi}; bf16x2_t b = __builtin_convertvector(v, bf16x2_t); return __builtin_bit_cast(unsigned, b); }
; __device__ __forceinline__ float bflo(unsigned w) { return __uint_as_float(w << 16); }
; __device__ __forceinline__ float bfhi(unsigned w) { return __uint_as_float(w & 0xffff0000u); }
;     __device__ __forceinline__ void operator()(const f32x4 (&acc)[2][2][4][2], const Unit& u, int wr, int wc, int fr, int fq) const {
;     ...
;                 for (int n = 0; n < 2; ++n) { const int cc = bj * HALF + 4 * n;
;                     f32x4 v = acc[ai][bj][m][n];
;                     if (bias) { v = (v + *(const f32x4*)(bias + col0 + cc)) * *(const f32x4*)(scale + col0 + cc); }
;                     f32x4 b;
;                     if (MODE >= 3) b = (f32x4){0.f, 0.f, 0.f, 0.f};
;                     else if (MODE == 0) b = __builtin_bit_cast(f32x4, cur[bj][n]);
;                     else { const unsigned w0 = n ? cur[bj][0].z : cur[bj][0].x, w1 = n ? cur[bj][0].w : cur[bj][0].y; b = (f32x4){bflo(w0), bfhi(w0), bflo(w1), bfhi(w1)}; }
;                     o[n] = b + v;
;                     if (MODE == 2 || MODE == 4) *(f32x4*)(out + off + cc) = o[n];
;                     ss += (o[n][0] * o[n][0] + o[n][1] * o[n][1]) + (o[n][2] * o[n][2] + o[n][3] * o[n][3]); }
;                 if (MODE != 2 && MODE != 4) { u32x4 w; w.x = pk2(o[0][0], o[0][1]); w.y = pk2(o[0][2], o[0][3]); w.z = pk2(o[1][0], o[1][1]); w.w = pk2(o[1][2], o[1][3]); *(u32x4*)(xb + off + bj * HALF) = w; } }
;             if (MODE != 2 && MODE != 4 && rsq) { ss += __shfl_xor(ss, 16); ss += __shfl_xor(ss, 32); if (fq == 0) rsq[(size_t)row * 64 + u.pn * 4 + wc] = ss; }
.LBB0_964:
	s_waitcnt vmcnt(13)
	v_pk_add_f32 v[38:39], v[86:87], v[38:39]
	v_pk_add_f32 v[36:37], v[84:85], v[36:37]
	v_pk_add_f32 v[34:35], v[82:83], v[34:35]
	v_pk_add_f32 v[32:33], v[80:81], v[32:33]
	v_cvt_pk_bf16_f32 v80, v36, v37
	v_cvt_pk_bf16_f32 v81, v38, v39
	v_cvt_pk_bf16_f32 v82, v32, v33
	v_cvt_pk_bf16_f32 v83, v34, v35
	s_and_b64 vcc, exec, s[10:11]
	global_store_dwordx4 v[88:89], v[80:83], off offset:256
	s_cbranch_vccnz .LBB0_968
	v_mul_f32_e32 v41, v41, v41
	v_mul_f32_e32 v33, v33, v33
	v_mul_f32_e32 v80, v93, v93
	v_mul_f32_e32 v47, v47, v47
	v_fmac_f32_e32 v41, v40, v40
	v_mul_f32_e32 v40, v43, v43
	v_mul_f32_e32 v37, v37, v37
	v_fmac_f32_e32 v33, v32, v32
	v_mul_f32_e32 v32, v35, v35
	v_fmac_f32_e32 v80, v92, v92
	v_fmac_f32_e32 v47, v46, v46
	v_fmac_f32_e32 v40, v42, v42
	v_fmac_f32_e32 v37, v36, v36
	v_mul_f32_e32 v36, v39, v39
	v_fmac_f32_e32 v32, v34, v34
	v_and_b32_e32 v34, 64, v251
	v_add_f32_e32 v46, v80, v47
	v_add_f32_e32 v40, v41, v40
	v_fmac_f32_e32 v36, v38, v38
	v_add_f32_e32 v32, v33, v32
	v_xor_b32_e32 v33, 16, v251
	v_add_u32_e32 v34, 64, v34
	v_add_f32_e32 v40, v46, v40
	v_add_f32_e32 v36, v37, v36
	v_cmp_lt_i32_e32 vcc, v33, v34
	v_add_f32_e32 v36, v40, v36
	v_add_f32_e32 v32, v36, v32
	v_cndmask_b32_e32 v33, v251, v33, vcc
	v_lshlrev_b32_e32 v33, 2, v33
	ds_bpermute_b32 v33, v33, v32
	s_waitcnt lgkmcnt(0)
	v_add_f32_e32 v32, v32, v33
	v_xor_b32_e32 v33, 32, v251
	v_cmp_lt_i32_e32 vcc, v33, v34
	s_nop 1
	v_cndmask_b32_e32 v33, v251, v33, vcc
	v_lshlrev_b32_e32 v33, 2, v33
	v_mov_b32_e32 v33, v32
	v_mov_b32_e32 v245, v32
	s_nop 1
	v_permlane32_swap_b32_e32 v33, v245
	s_and_saveexec_b64 s[16:17], s[4:5]
	s_cbranch_execz .LBB0_967
	v_lshlrev_b64 v[34:35], 8, v[44:45]
	v_lshl_add_u64 v[34:35], s[64:65], 0, v[34:35]
	v_lshl_add_u64 v[34:35], s[52:53], 2, v[34:35]
	s_lshl_b32 s18, s28, 2
	v_lshl_add_u64 v[34:35], v[34:35], 0, s[18:19]
	s_waitcnt lgkmcnt(0)
	v_add_f32_e32 v32, v33, v245
	global_store_dword v[34:35], v32, off

; __device__ __forceinline__ unsigned pk2(float lo, float hi) { f32x2 v = {lo, hi}; bf16x2_t b = __builtin_convertvector(v, bf16x2_t); return __builtin_bit_cast(unsigned, b); }
; __device__ __forceinline__ float bflo(unsigned w) { return __uint_as_float(w << 16); }
; __device__ __forceinline__ float bfhi(unsigned w) { return __uint_as_float(w & 0xffff0000u); }
;     __device__ __forceinline__ void operator()(const f32x4 (&acc)[2][2][4][2], const Unit& u, int wr, int wc, int fr, int fq) const {
;     ...
;                 for (int n = 0; n < 2; ++n) { const int cc = bj * HALF + 4 * n;
;                     f32x4 v = acc[ai][bj][m][n];
;                     if (bias) { v = (v + *(const f32x4*)(bias + col0 + cc)) * *(const f32x4*)(scale + col0 + cc); }
;                     f32x4 b;
;                     if (MODE >= 3) b = (f32x4){0.f, 0.f, 0.f, 0.f};
;                     else if (MODE == 0) b = __builtin_bit_cast(f32x4, cur[bj][n]);
;                     else { const unsigned w0 = n ? cur[bj][0].z : cur[bj][0].x, w1 = n ? cur[bj][0].w : cur[bj][0].y; b = (f32x4){bflo(w0), bfhi(w0), bflo(w1), bfhi(w1)}; }
;                     o[n] = b + v;
;                     if (MODE == 2 || MODE == 4) *(f32x4*)(out + off + cc) = o[n];
;                     ss += (o[n][0] * o[n][0] + o[n][1] * o[n][1]) + (o[n][2] * o[n][2] + o[n][3] * o[n][3]); }
;                 if (MODE != 2 && MODE != 4) { u32x4 w; w.x = pk2(o[0][0], o[0][1]); w.y = pk2(o[0][2], o[0][3]); w.z = pk2(o[1][0], o[1][1]); w.w = pk2(o[1][2], o[1][3]); *(u32x4*)(xb + off + bj * HALF) = w; } }
;             if (MODE != 2 && MODE != 4 && rsq) { ss += __shfl_xor(ss, 16); ss += __shfl_xor(ss, 32); if (fq == 0) rsq[(size_t)row * 64 + u.pn * 4 + wc] = ss; }
.LBB0_976:
	s_waitcnt vmcnt(9)
	v_pk_add_f32 v[22:23], v[70:71], v[22:23]
	v_pk_add_f32 v[20:21], v[68:69], v[20:21]
	v_pk_add_f32 v[18:19], v[66:67], v[18:19]
	v_pk_add_f32 v[16:17], v[64:65], v[16:17]
	v_cvt_pk_bf16_f32 v34, v20, v21
	v_cvt_pk_bf16_f32 v35, v22, v23
	v_cvt_pk_bf16_f32 v36, v16, v17
	v_cvt_pk_bf16_f32 v37, v18, v19
	s_and_b64 vcc, exec, s[10:11]
	global_store_dwordx4 v[32:33], v[34:37], off offset:256
	s_cbranch_vccnz .LBB0_980
	v_mul_f32_e32 v29, v29, v29
	v_mul_f32_e32 v25, v25, v25
	v_mul_f32_e32 v17, v17, v17
	v_fmac_f32_e32 v29, v28, v28
	v_mul_f32_e32 v28, v31, v31
	v_fmac_f32_e32 v25, v24, v24
	v_mul_f32_e32 v24, v27, v27
	v_mul_f32_e32 v21, v21, v21
	v_fmac_f32_e32 v17, v16, v16
	v_mul_f32_e32 v16, v19, v19
	v_fmac_f32_e32 v28, v30, v30
	v_fmac_f32_e32 v24, v26, v26
	v_fmac_f32_e32 v21, v20, v20
	v_mul_f32_e32 v20, v23, v23
	v_fmac_f32_e32 v16, v18, v18
	v_and_b32_e32 v18, 64, v251
	v_add_f32_e32 v28, v29, v28
	v_add_f32_e32 v24, v25, v24
	v_fmac_f32_e32 v20, v22, v22
	v_add_f32_e32 v16, v17, v16
	v_xor_b32_e32 v17, 16, v251
	v_add_u32_e32 v18, 64, v18
	v_add_f32_e32 v24, v28, v24
	v_add_f32_e32 v20, v21, v20
	v_cmp_lt_i32_e32 vcc, v17, v18
	v_add_f32_e32 v20, v24, v20
	v_add_f32_e32 v16, v20, v16
	v_cndmask_b32_e32 v17, v251, v17, vcc
	v_lshlrev_b32_e32 v17, 2, v17
	ds_bpermute_b32 v17, v17, v16
	s_waitcnt lgkmcnt(0)
	v_add_f32_e32 v16, v16, v17
	v_xor_b32_e32 v17, 32, v251
	v_cmp_lt_i32_e32 vcc, v17, v18
	s_nop 1
	v_cndmask_b32_e32 v17, v251, v17, vcc
	v_lshlrev_b32_e32 v17, 2, v17
	v_mov_b32_e32 v17, v16
	v_mov_b32_e32 v245, v16
	s_nop 1
	v_permlane32_swap_b32_e32 v17, v245
	s_and_saveexec_b64 s[16:17], s[4:5]
	s_cbranch_execz .LBB0_979
	v_lshlrev_b64 v[18:19], 8, v[114:115]
	v_lshl_add_u64 v[18:19], s[64:65], 0, v[18:19]
	v_lshl_add_u64 v[18:19], s[52:53], 2, v[18:19]
	s_lshl_b32 s18, s28, 2
	v_lshl_add_u64 v[18:19], v[18:19], 0, s[18:19]
	s_waitcnt lgkmcnt(0)
	v_add_f32_e32 v16, v17, v245
	global_store_dword v[18:19], v16, off

; __device__ __forceinline__ unsigned pk2(float lo, float hi) { f32x2 v = {lo, hi}; bf16x2_t b = __builtin_convertvector(v, bf16x2_t); return __builtin_bit_cast(unsigned, b); }
; __device__ __forceinline__ float bflo(unsigned w) { return __uint_as_float(w << 16); }
; __device__ __forceinline__ float bfhi(unsigned w) { return __uint_as_float(w & 0xffff0000u); }
;     __device__ __forceinline__ void operator()(const f32x4 (&acc)[2][2][4][2], const Unit& u, int wr, int wc, int fr, int fq) const {
;     ...
;                 for (int n = 0; n < 2; ++n) { const int cc = bj * HALF + 4 * n;
;                     f32x4 v = acc[ai][bj][m][n];
;                     if (bias) { v = (v + *(const f32x4*)(bias + col0 + cc)) * *(const f32x4*)(scale + col0 + cc); }
;                     f32x4 b;
;                     if (MODE >= 3) b = (f32x4){0.f, 0.f, 0.f, 0.f};
;                     else if (MODE == 0) b = __builtin_bit_cast(f32x4, cur[bj][n]);
;                     else { const unsigned w0 = n ? cur[bj][0].z : cur[bj][0].x, w1 = n ? cur[bj][0].w : cur[bj][0].y; b = (f32x4){bflo(w0), bfhi(w0), bflo(w1), bfhi(w1)}; }
;                     o[n] = b + v;
;                     if (MODE == 2 || MODE == 4) *(f32x4*)(out + off + cc) = o[n];
;                     ss += (o[n][0] * o[n][0] + o[n][1] * o[n][1]) + (o[n][2] * o[n][2] + o[n][3] * o[n][3]); }
;                 if (MODE != 2 && MODE != 4) { u32x4 w; w.x = pk2(o[0][0], o[0][1]); w.y = pk2(o[0][2], o[0][3]); w.z = pk2(o[1][0], o[1][1]); w.w = pk2(o[1][2], o[1][3]); *(u32x4*)(xb + off + bj * HALF) = w; } }
;             if (MODE != 2 && MODE != 4 && rsq) { ss += __shfl_xor(ss, 16); ss += __shfl_xor(ss, 32); if (fq == 0) rsq[(size_t)row * 64 + u.pn * 4 + wc] = ss; }
.LBB0_988:
	s_waitcnt vmcnt(5)
	v_pk_add_f32 v[6:7], v[54:55], v[6:7]
	v_pk_add_f32 v[4:5], v[52:53], v[4:5]
	v_pk_add_f32 v[2:3], v[50:51], v[2:3]
	v_pk_add_f32 v[0:1], v[48:49], v[0:1]
	v_cvt_pk_bf16_f32 v18, v4, v5
	v_cvt_pk_bf16_f32 v19, v6, v7
	v_cvt_pk_bf16_f32 v20, v0, v1
	v_cvt_pk_bf16_f32 v21, v2, v3
	s_and_b64 vcc, exec, s[10:11]
	global_store_dwordx4 v[16:17], v[18:21], off offset:256
	s_cbranch_vccnz .LBB0_992
	v_mul_f32_e32 v13, v13, v13
	v_mul_f32_e32 v9, v9, v9
	v_mul_f32_e32 v1, v1, v1
	v_fmac_f32_e32 v13, v12, v12
	v_mul_f32_e32 v12, v15, v15
	v_fmac_f32_e32 v9, v8, v8
	v_mul_f32_e32 v8, v11, v11
	v_mul_f32_e32 v5, v5, v5
	v_fmac_f32_e32 v1, v0, v0
	v_mul_f32_e32 v0, v3, v3
	v_fmac_f32_e32 v12, v14, v14
	v_fmac_f32_e32 v8, v10, v10
	v_fmac_f32_e32 v5, v4, v4
	v_mul_f32_e32 v4, v7, v7
	v_fmac_f32_e32 v0, v2, v2
	v_and_b32_e32 v2, 64, v251
	v_add_f32_e32 v12, v13, v12
	v_add_f32_e32 v8, v9, v8
	v_fmac_f32_e32 v4, v6, v6
	v_add_f32_e32 v0, v1, v0
	v_xor_b32_e32 v1, 16, v251
	v_add_u32_e32 v2, 64, v2
	v_add_f32_e32 v8, v12, v8
	v_add_f32_e32 v4, v5, v4
	v_cmp_lt_i32_e32 vcc, v1, v2
	v_add_f32_e32 v4, v8, v4
	v_add_f32_e32 v0, v4, v0
	v_cndmask_b32_e32 v1, v251, v1, vcc
	v_lshlrev_b32_e32 v1, 2, v1
	ds_bpermute_b32 v1, v1, v0
	s_waitcnt lgkmcnt(0)
	v_add_f32_e32 v0, v0, v1
	v_xor_b32_e32 v1, 32, v251
	v_cmp_lt_i32_e32 vcc, v1, v2
	s_nop 1
	v_cndmask_b32_e32 v1, v251, v1, vcc
	v_lshlrev_b32_e32 v1, 2, v1
	v_mov_b32_e32 v1, v0
	v_mov_b32_e32 v245, v0
	s_nop 1
	v_permlane32_swap_b32_e32 v1, v245
	s_and_saveexec_b64 s[8:9], s[4:5]
	s_cbranch_execz .LBB0_991
	v_lshlrev_b64 v[2:3], 8, v[98:99]
	v_lshl_add_u64 v[2:3], s[64:65], 0, v[2:3]
	v_lshl_add_u64 v[2:3], s[52:53], 2, v[2:3]
	s_lshl_b32 s18, s28, 2
	v_lshl_add_u64 v[2:3], v[2:3], 0, s[18:19]
	s_waitcnt lgkmcnt(0)
	v_add_f32_e32 v0, v1, v245
	global_store_dword v[2:3], v0, off

; __device__ __forceinline__ unsigned pk2(float lo, float hi) { f32x2 v = {lo, hi}; bf16x2_t b = __builtin_convertvector(v, bf16x2_t); return __builtin_bit_cast(unsigned, b); }
; __device__ __forceinline__ float bflo(unsigned w) { return __uint_as_float(w << 16); }
; __device__ __forceinline__ float bfhi(unsigned w) { return __uint_as_float(w & 0xffff0000u); }
;     __device__ __forceinline__ void operator()(const f32x4 (&acc)[2][2][4][2], const Unit& u, int wr, int wc, int fr, int fq) const {
;     ...
;         for (int j = 0; j < 8; ++j) { const int ai = j >> 2, m = j & 3; const int row = row0 + ai * HALF + m * 16; const size_t off = (size_t)row * DM + col0; float ss = 0.f;
;             if (MODE < 3 && j < 6) ldgrp(nx2, (size_t)(row0 + ((j + 2) >> 2) * HALF + ((j + 2) & 3) * 16) * DM + col0);
; #pragma unroll
;             for (int bj = 0; bj < 2; ++bj) { f32x4 o[2];
; #pragma unroll
;                 for (int n = 0; n < 2; ++n) { const int cc = bj * HALF + 4 * n;
;                     f32x4 v = acc[ai][bj][m][n];
;                     if (bias) { v = (v + *(const f32x4*)(bias + col0 + cc)) * *(const f32x4*)(scale + col0 + cc); }
;                     f32x4 b;
;                     if (MODE >= 3) b = (f32x4){0.f, 0.f, 0.f, 0.f};
;                     else if (MODE == 0) b = __builtin_bit_cast(f32x4, cur[bj][n]);
;                     else { const unsigned w0 = n ? cur[bj][0].z : cur[bj][0].x, w1 = n ? cur[bj][0].w : cur[bj][0].y; b = (f32x4){bflo(w0), bfhi(w0), bflo(w1), bfhi(w1)}; }
;                     o[n] = b + v;
;                     if (MODE == 2 || MODE == 4) *(f32x4*)(out + off + cc) = o[n];
;                     ss += (o[n][0] * o[n][0] + o[n][1] * o[n][1]) + (o[n][2] * o[n][2] + o[n][3] * o[n][3]); }
;                 if (MODE != 2 && MODE != 4) { u32x4 w; w.x = pk2(o[0][0], o[0][1]); w.y = pk2(o[0][2], o[0][3]); w.z = pk2(o[1][0], o[1][1]); w.w = pk2(o[1][2], o[1][3]); *(u32x4*)(xb + off + bj * HALF) = w; } }
;             if (MODE != 2 && MODE != 4 && rsq) { ss += __shfl_xor(ss, 16); ss += __shfl_xor(ss, 32); if (fq == 0) rsq[(size_t)row * 64 + u.pn * 4 + wc] = ss; }
.LBB0_1373:
	v_lshl_add_u32 v142, s43, 8, v149
	v_ashrrev_i32_e32 v143, 31, v142
	v_lshl_or_b32 v140, s18, 8, v151
	v_lshlrev_b64 v[146:147], 12, v[142:143]
	v_ashrrev_i32_e32 v141, 31, v140
	v_pk_add_f32 v[144:145], v[114:115], 0 op_sel_hi:[1,0]
	v_pk_add_f32 v[114:115], v[120:121], 0 op_sel_hi:[1,0]
	v_pk_add_f32 v[120:121], v[118:119], 0 op_sel_hi:[1,0]
	v_lshl_add_u64 v[118:119], s[10:11], 0, v[146:147]
	s_lshl_b32 s16, s18, 2
	v_pk_add_f32 v[116:117], v[116:117], 0 op_sel_hi:[1,0]
	v_lshl_add_u64 v[158:159], v[140:141], 1, v[118:119]
	v_pk_add_f32 v[124:125], v[124:125], 0 op_sel_hi:[1,0]
	v_pk_add_f32 v[146:147], v[122:123], 0 op_sel_hi:[1,0]
	v_pk_add_f32 v[118:119], v[128:129], 0 op_sel_hi:[1,0]
	v_pk_add_f32 v[122:123], v[126:127], 0 op_sel_hi:[1,0]
	v_cndmask_b32_e64 v153, 0, 1, s[56:57]
	s_ashr_i32 s17, s16, 31
	v_cvt_pk_bf16_f32 v154, v144, v145
	v_cvt_pk_bf16_f32 v155, v116, v117
	v_cvt_pk_bf16_f32 v156, v120, v121
	v_cvt_pk_bf16_f32 v157, v114, v115
	v_cvt_pk_bf16_f32 v126, v146, v147
	v_cvt_pk_bf16_f32 v127, v124, v125
	v_cvt_pk_bf16_f32 v128, v122, v123
	v_cvt_pk_bf16_f32 v129, v118, v119
	v_cmp_ne_u32_e64 s[8:9], 1, v153
	s_andn2_b64 vcc, exec, s[56:57]
	global_store_dwordx4 v[158:159], v[154:157], off
	global_store_dwordx4 v[158:159], v[126:129], off offset:256
	s_cbranch_vccnz .LBB0_1377
	s_nop 0
	v_mul_f32_e32 v126, v145, v145
	v_mul_f32_e32 v117, v117, v117
	v_fmac_f32_e32 v126, v144, v144
	v_fmac_f32_e32 v117, v116, v116
	v_add_f32_e32 v116, v126, v117
	v_mul_f32_e32 v117, v121, v121
	v_mul_f32_e32 v115, v115, v115
	v_fmac_f32_e32 v117, v120, v120
	v_fmac_f32_e32 v115, v114, v114
	v_add_f32_e32 v114, v117, v115
	v_add_f32_e32 v114, v116, v114
	v_mul_f32_e32 v115, v147, v147
	v_mul_f32_e32 v116, v125, v125
	v_fmac_f32_e32 v115, v146, v146
	v_fmac_f32_e32 v116, v124, v124
	v_add_f32_e32 v115, v115, v116
	v_add_f32_e32 v114, v114, v115
	v_mul_f32_e32 v115, v123, v123
	v_mul_f32_e32 v116, v119, v119
	v_fmac_f32_e32 v115, v122, v122
	v_fmac_f32_e32 v116, v118, v118
	v_add_f32_e32 v115, v115, v116
	v_and_b32_e32 v116, 64, v251
	v_add_f32_e32 v114, v114, v115
	v_xor_b32_e32 v115, 16, v251
	v_add_u32_e32 v116, 64, v116
	v_cmp_lt_i32_e32 vcc, v115, v116
	s_nop 1
	v_cndmask_b32_e32 v115, v251, v115, vcc
	v_lshlrev_b32_e32 v115, 2, v115
	ds_bpermute_b32 v115, v115, v114
	s_waitcnt lgkmcnt(0)
	v_add_f32_e32 v114, v114, v115
	v_xor_b32_e32 v115, 32, v251
	v_cmp_lt_i32_e32 vcc, v115, v116
	s_nop 1
	v_cndmask_b32_e32 v115, v251, v115, vcc
	v_lshlrev_b32_e32 v115, 2, v115
	v_mov_b32_e32 v115, v114
	v_mov_b32_e32 v245, v114
	s_nop 1
	v_permlane32_swap_b32_e32 v115, v245
	s_and_saveexec_b64 s[54:55], s[4:5]
	s_cbranch_execz .LBB0_1376
	v_lshlrev_b64 v[116:117], 8, v[142:143]
	v_lshl_add_u64 v[116:117], s[14:15], 0, v[116:117]
	v_lshl_add_u64 v[116:117], s[16:17], 2, v[116:117]
	s_lshl_b32 s18, s2, 2
	v_lshl_add_u64 v[116:117], v[116:117], 0, s[18:19]
	s_waitcnt lgkmcnt(0)
	v_add_f32_e32 v114, v115, v245
	global_store_dword v[116:117], v114, off

; __device__ __forceinline__ unsigned pk2(float lo, float hi) { f32x2 v = {lo, hi}; bf16x2_t b = __builtin_convertvector(v, bf16x2_t); return __builtin_bit_cast(unsigned, b); }
; __device__ __forceinline__ float bflo(unsigned w) { return __uint_as_float(w << 16); }
; __device__ __forceinline__ float bfhi(unsigned w) { return __uint_as_float(w & 0xffff0000u); }
;     __device__ __forceinline__ void operator()(const f32x4 (&acc)[2][2][4][2], const Unit& u, int wr, int wc, int fr, int fq) const {
;     ...
;                 for (int n = 0; n < 2; ++n) { const int cc = bj * HALF + 4 * n;
;                     f32x4 v = acc[ai][bj][m][n];
;                     if (bias) { v = (v + *(const f32x4*)(bias + col0 + cc)) * *(const f32x4*)(scale + col0 + cc); }
;                     f32x4 b;
;                     if (MODE >= 3) b = (f32x4){0.f, 0.f, 0.f, 0.f};
;                     else if (MODE == 0) b = __builtin_bit_cast(f32x4, cur[bj][n]);
;                     else { const unsigned w0 = n ? cur[bj][0].z : cur[bj][0].x, w1 = n ? cur[bj][0].w : cur[bj][0].y; b = (f32x4){bflo(w0), bfhi(w0), bflo(w1), bfhi(w1)}; }
;                     o[n] = b + v;
;                     if (MODE == 2 || MODE == 4) *(f32x4*)(out + off + cc) = o[n];
;                     ss += (o[n][0] * o[n][0] + o[n][1] * o[n][1]) + (o[n][2] * o[n][2] + o[n][3] * o[n][3]); }
;                 if (MODE != 2 && MODE != 4) { u32x4 w; w.x = pk2(o[0][0], o[0][1]); w.y = pk2(o[0][2], o[0][3]); w.z = pk2(o[1][0], o[1][1]); w.w = pk2(o[1][2], o[1][3]); *(u32x4*)(xb + off + bj * HALF) = w; } }
;             if (MODE != 2 && MODE != 4 && rsq) { ss += __shfl_xor(ss, 16); ss += __shfl_xor(ss, 32); if (fq == 0) rsq[(size_t)row * 64 + u.pn * 4 + wc] = ss; }
.LBB0_1377:
	v_or_b32_e32 v114, 16, v142
	s_waitcnt lgkmcnt(0)
	v_ashrrev_i32_e32 v115, 31, v114
	v_lshlrev_b64 v[122:123], 12, v[114:115]
	v_pk_add_f32 v[100:101], v[100:101], 0 op_sel_hi:[1,0]
	v_pk_add_f32 v[116:117], v[98:99], 0 op_sel_hi:[1,0]
	v_pk_add_f32 v[98:99], v[104:105], 0 op_sel_hi:[1,0]
	v_pk_add_f32 v[104:105], v[102:103], 0 op_sel_hi:[1,0]
	v_lshl_add_u64 v[102:103], s[10:11], 0, v[122:123]
	v_cvt_pk_bf16_f32 v118, v116, v117
	v_cvt_pk_bf16_f32 v119, v100, v101
	v_cvt_pk_bf16_f32 v120, v104, v105
	v_cvt_pk_bf16_f32 v121, v98, v99
	v_lshl_add_u64 v[122:123], v[140:141], 1, v[102:103]
	global_store_dwordx4 v[122:123], v[118:121], off
	v_pk_add_f32 v[108:109], v[108:109], 0 op_sel_hi:[1,0]
	v_pk_add_f32 v[102:103], v[112:113], 0 op_sel_hi:[1,0]
	v_pk_add_f32 v[118:119], v[106:107], 0 op_sel_hi:[1,0]
	v_pk_add_f32 v[106:107], v[110:111], 0 op_sel_hi:[1,0]
	v_cvt_pk_bf16_f32 v110, v118, v119
	v_cvt_pk_bf16_f32 v111, v108, v109
	v_cvt_pk_bf16_f32 v112, v106, v107
	v_cvt_pk_bf16_f32 v113, v102, v103
	s_and_b64 vcc, exec, s[8:9]
	global_store_dwordx4 v[122:123], v[110:113], off offset:256
	s_cbranch_vccnz .LBB0_1381
	s_nop 0
	v_mul_f32_e32 v110, v117, v117
	v_mul_f32_e32 v101, v101, v101
	v_fmac_f32_e32 v110, v116, v116
	v_fmac_f32_e32 v101, v100, v100
	v_add_f32_e32 v100, v110, v101
	v_mul_f32_e32 v101, v105, v105
	v_mul_f32_e32 v99, v99, v99
	v_fmac_f32_e32 v101, v104, v104
	v_fmac_f32_e32 v99, v98, v98
	v_add_f32_e32 v98, v101, v99
	v_add_f32_e32 v98, v100, v98
	v_mul_f32_e32 v99, v119, v119
	v_mul_f32_e32 v100, v109, v109
	v_fmac_f32_e32 v99, v118, v118
	v_fmac_f32_e32 v100, v108, v108
	v_add_f32_e32 v99, v99, v100
	v_add_f32_e32 v98, v98, v99
	v_mul_f32_e32 v99, v107, v107
	v_mul_f32_e32 v100, v103, v103
	v_fmac_f32_e32 v99, v106, v106
	v_fmac_f32_e32 v100, v102, v102
	v_add_f32_e32 v99, v99, v100
	v_and_b32_e32 v100, 64, v251
	v_add_f32_e32 v98, v98, v99
	v_xor_b32_e32 v99, 16, v251
	v_add_u32_e32 v100, 64, v100
	v_cmp_lt_i32_e32 vcc, v99, v100
	s_nop 1
	v_cndmask_b32_e32 v99, v251, v99, vcc
	v_lshlrev_b32_e32 v99, 2, v99
	ds_bpermute_b32 v99, v99, v98
	s_waitcnt lgkmcnt(0)
	v_add_f32_e32 v98, v98, v99
	v_xor_b32_e32 v99, 32, v251
	v_cmp_lt_i32_e32 vcc, v99, v100
	s_nop 1
	v_cndmask_b32_e32 v99, v251, v99, vcc
	v_lshlrev_b32_e32 v99, 2, v99
	v_mov_b32_e32 v99, v98
	v_mov_b32_e32 v245, v98
	s_nop 1
	v_permlane32_swap_b32_e32 v99, v245
	s_and_saveexec_b64 s[54:55], s[4:5]
	s_cbranch_execz .LBB0_1380
	v_lshlrev_b64 v[100:101], 8, v[114:115]
	v_lshl_add_u64 v[100:101], s[14:15], 0, v[100:101]
	v_lshl_add_u64 v[100:101], s[16:17], 2, v[100:101]
	s_lshl_b32 s18, s2, 2
	v_lshl_add_u64 v[100:101], v[100:101], 0, s[18:19]
	s_waitcnt lgkmcnt(0)
	v_add_f32_e32 v98, v99, v245
	global_store_dword v[100:101], v98, off

; __device__ __forceinline__ unsigned pk2(float lo, float hi) { f32x2 v = {lo, hi}; bf16x2_t b = __builtin_convertvector(v, bf16x2_t); return __builtin_bit_cast(unsigned, b); }
; __device__ __forceinline__ float bflo(unsigned w) { return __uint_as_float(w << 16); }
; __device__ __forceinline__ float bfhi(unsigned w) { return __uint_as_float(w & 0xffff0000u); }
;     __device__ __forceinline__ void operator()(const f32x4 (&acc)[2][2][4][2], const Unit& u, int wr, int wc, int fr, int fq) const {
;     ...
;                 for (int n = 0; n < 2; ++n) { const int cc = bj * HALF + 4 * n;
;                     f32x4 v = acc[ai][bj][m][n];
;                     if (bias) { v = (v + *(const f32x4*)(bias + col0 + cc)) * *(const f32x4*)(scale + col0 + cc); }
;                     f32x4 b;
;                     if (MODE >= 3) b = (f32x4){0.f, 0.f, 0.f, 0.f};
;                     else if (MODE == 0) b = __builtin_bit_cast(f32x4, cur[bj][n]);
;                     else { const unsigned w0 = n ? cur[bj][0].z : cur[bj][0].x, w1 = n ? cur[bj][0].w : cur[bj][0].y; b = (f32x4){bflo(w0), bfhi(w0), bflo(w1), bfhi(w1)}; }
;                     o[n] = b + v;
;                     if (MODE == 2 || MODE == 4) *(f32x4*)(out + off + cc) = o[n];
;                     ss += (o[n][0] * o[n][0] + o[n][1] * o[n][1]) + (o[n][2] * o[n][2] + o[n][3] * o[n][3]); }
;                 if (MODE != 2 && MODE != 4) { u32x4 w; w.x = pk2(o[0][0], o[0][1]); w.y = pk2(o[0][2], o[0][3]); w.z = pk2(o[1][0], o[1][1]); w.w = pk2(o[1][2], o[1][3]); *(u32x4*)(xb + off + bj * HALF) = w; } }
;             if (MODE != 2 && MODE != 4 && rsq) { ss += __shfl_xor(ss, 16); ss += __shfl_xor(ss, 32); if (fq == 0) rsq[(size_t)row * 64 + u.pn * 4 + wc] = ss; }
.LBB0_1381:
	v_or_b32_e32 v98, 32, v142
	s_waitcnt lgkmcnt(0)
	v_ashrrev_i32_e32 v99, 31, v98
	v_lshlrev_b64 v[106:107], 12, v[98:99]
	v_pk_add_f32 v[82:83], v[82:83], 0 op_sel_hi:[1,0]
	v_pk_add_f32 v[100:101], v[80:81], 0 op_sel_hi:[1,0]
	v_pk_add_f32 v[80:81], v[86:87], 0 op_sel_hi:[1,0]
	v_pk_add_f32 v[86:87], v[84:85], 0 op_sel_hi:[1,0]
	v_lshl_add_u64 v[84:85], s[10:11], 0, v[106:107]
	v_cvt_pk_bf16_f32 v102, v100, v101
	v_cvt_pk_bf16_f32 v103, v82, v83
	v_cvt_pk_bf16_f32 v104, v86, v87
	v_cvt_pk_bf16_f32 v105, v80, v81
	v_lshl_add_u64 v[106:107], v[140:141], 1, v[84:85]
	global_store_dwordx4 v[106:107], v[102:105], off
	v_pk_add_f32 v[90:91], v[90:91], 0 op_sel_hi:[1,0]
	v_pk_add_f32 v[84:85], v[94:95], 0 op_sel_hi:[1,0]
	v_pk_add_f32 v[102:103], v[88:89], 0 op_sel_hi:[1,0]
	v_pk_add_f32 v[88:89], v[92:93], 0 op_sel_hi:[1,0]
	v_cvt_pk_bf16_f32 v92, v102, v103
	v_cvt_pk_bf16_f32 v93, v90, v91
	v_cvt_pk_bf16_f32 v94, v88, v89
	v_cvt_pk_bf16_f32 v95, v84, v85
	s_and_b64 vcc, exec, s[8:9]
	global_store_dwordx4 v[106:107], v[92:95], off offset:256
	s_cbranch_vccnz .LBB0_1385
	s_nop 0
	v_mul_f32_e32 v92, v101, v101
	v_mul_f32_e32 v83, v83, v83
	v_fmac_f32_e32 v92, v100, v100
	v_fmac_f32_e32 v83, v82, v82
	v_add_f32_e32 v82, v92, v83
	v_mul_f32_e32 v83, v87, v87
	v_mul_f32_e32 v81, v81, v81
	v_fmac_f32_e32 v83, v86, v86
	v_fmac_f32_e32 v81, v80, v80
	v_add_f32_e32 v80, v83, v81
	v_add_f32_e32 v80, v82, v80
	v_mul_f32_e32 v81, v103, v103
	v_mul_f32_e32 v82, v91, v91
	v_fmac_f32_e32 v81, v102, v102
	v_fmac_f32_e32 v82, v90, v90
	v_add_f32_e32 v81, v81, v82
	v_add_f32_e32 v80, v80, v81
	v_mul_f32_e32 v81, v89, v89
	v_mul_f32_e32 v82, v85, v85
	v_fmac_f32_e32 v81, v88, v88
	v_fmac_f32_e32 v82, v84, v84
	v_add_f32_e32 v81, v81, v82
	v_and_b32_e32 v82, 64, v251
	v_add_f32_e32 v80, v80, v81
	v_xor_b32_e32 v81, 16, v251
	v_add_u32_e32 v82, 64, v82
	v_cmp_lt_i32_e32 vcc, v81, v82
	s_nop 1
	v_cndmask_b32_e32 v81, v251, v81, vcc
	v_lshlrev_b32_e32 v81, 2, v81
	ds_bpermute_b32 v81, v81, v80
	s_waitcnt lgkmcnt(0)
	v_add_f32_e32 v80, v80, v81
	v_xor_b32_e32 v81, 32, v251
	v_cmp_lt_i32_e32 vcc, v81, v82
	s_nop 1
	v_cndmask_b32_e32 v81, v251, v81, vcc
	v_lshlrev_b32_e32 v81, 2, v81
	v_mov_b32_e32 v81, v80
	v_mov_b32_e32 v245, v80
	s_nop 1
	v_permlane32_swap_b32_e32 v81, v245
	s_and_saveexec_b64 s[54:55], s[4:5]
	s_cbranch_execz .LBB0_1384
	v_lshlrev_b64 v[82:83], 8, v[98:99]
	v_lshl_add_u64 v[82:83], s[14:15], 0, v[82:83]
	v_lshl_add_u64 v[82:83], s[16:17], 2, v[82:83]
	s_lshl_b32 s18, s2, 2
	v_lshl_add_u64 v[82:83], v[82:83], 0, s[18:19]
	s_waitcnt lgkmcnt(0)
	v_add_f32_e32 v80, v81, v245
	global_store_dword v[82:83], v80, off

; __device__ __forceinline__ unsigned pk2(float lo, float hi) { f32x2 v = {lo, hi}; bf16x2_t b = __builtin_convertvector(v, bf16x2_t); return __builtin_bit_cast(unsigned, b); }
; __device__ __forceinline__ float bflo(unsigned w) { return __uint_as_float(w << 16); }
; __device__ __forceinline__ float bfhi(unsigned w) { return __uint_as_float(w & 0xffff0000u); }
;     __device__ __forceinline__ void operator()(const f32x4 (&acc)[2][2][4][2], const Unit& u, int wr, int wc, int fr, int fq) const {
;     ...
;                 for (int n = 0; n < 2; ++n) { const int cc = bj * HALF + 4 * n;
;                     f32x4 v = acc[ai][bj][m][n];
;                     if (bias) { v = (v + *(const f32x4*)(bias + col0 + cc)) * *(const f32x4*)(scale + col0 + cc); }
;                     f32x4 b;
;                     if (MODE >= 3) b = (f32x4){0.f, 0.f, 0.f, 0.f};
;                     else if (MODE == 0) b = __builtin_bit_cast(f32x4, cur[bj][n]);
;                     else { const unsigned w0 = n ? cur[bj][0].z : cur[bj][0].x, w1 = n ? cur[bj][0].w : cur[bj][0].y; b = (f32x4){bflo(w0), bfhi(w0), bflo(w1), bfhi(w1)}; }
;                     o[n] = b + v;
;                     if (MODE == 2 || MODE == 4) *(f32x4*)(out + off + cc) = o[n];
;                     ss += (o[n][0] * o[n][0] + o[n][1] * o[n][1]) + (o[n][2] * o[n][2] + o[n][3] * o[n][3]); }
;                 if (MODE != 2 && MODE != 4) { u32x4 w; w.x = pk2(o[0][0], o[0][1]); w.y = pk2(o[0][2], o[0][3]); w.z = pk2(o[1][0], o[1][1]); w.w = pk2(o[1][2], o[1][3]); *(u32x4*)(xb + off + bj * HALF) = w; } }
;             if (MODE != 2 && MODE != 4 && rsq) { ss += __shfl_xor(ss, 16); ss += __shfl_xor(ss, 32); if (fq == 0) rsq[(size_t)row * 64 + u.pn * 4 + wc] = ss; }
.LBB0_1385:
	v_or_b32_e32 v80, 48, v142
	s_waitcnt lgkmcnt(0)
	v_ashrrev_i32_e32 v81, 31, v80
	v_lshlrev_b64 v[88:89], 12, v[80:81]
	v_pk_add_f32 v[50:51], v[50:51], 0 op_sel_hi:[1,0]
	v_pk_add_f32 v[82:83], v[48:49], 0 op_sel_hi:[1,0]
	v_pk_add_f32 v[48:49], v[54:55], 0 op_sel_hi:[1,0]
	v_pk_add_f32 v[54:55], v[52:53], 0 op_sel_hi:[1,0]
	v_lshl_add_u64 v[52:53], s[10:11], 0, v[88:89]
	v_cvt_pk_bf16_f32 v84, v82, v83
	v_cvt_pk_bf16_f32 v85, v50, v51
	v_cvt_pk_bf16_f32 v86, v54, v55
	v_cvt_pk_bf16_f32 v87, v48, v49
	v_lshl_add_u64 v[88:89], v[140:141], 1, v[52:53]
	global_store_dwordx4 v[88:89], v[84:87], off
	v_pk_add_f32 v[70:71], v[70:71], 0 op_sel_hi:[1,0]
	v_pk_add_f32 v[52:53], v[78:79], 0 op_sel_hi:[1,0]
	v_pk_add_f32 v[84:85], v[68:69], 0 op_sel_hi:[1,0]
	v_pk_add_f32 v[68:69], v[76:77], 0 op_sel_hi:[1,0]
	v_cvt_pk_bf16_f32 v76, v84, v85
	v_cvt_pk_bf16_f32 v77, v70, v71
	v_cvt_pk_bf16_f32 v78, v68, v69
	v_cvt_pk_bf16_f32 v79, v52, v53
	s_and_b64 vcc, exec, s[8:9]
	global_store_dwordx4 v[88:89], v[76:79], off offset:256
	s_cbranch_vccnz .LBB0_1389
	s_nop 0
	v_mul_f32_e32 v76, v83, v83
	v_mul_f32_e32 v51, v51, v51
	v_fmac_f32_e32 v76, v82, v82
	v_fmac_f32_e32 v51, v50, v50
	v_add_f32_e32 v50, v76, v51
	v_mul_f32_e32 v51, v55, v55
	v_mul_f32_e32 v49, v49, v49
	v_fmac_f32_e32 v51, v54, v54
	v_fmac_f32_e32 v49, v48, v48
	v_add_f32_e32 v48, v51, v49
	v_add_f32_e32 v48, v50, v48
	v_mul_f32_e32 v49, v85, v85
	v_mul_f32_e32 v50, v71, v71
	v_fmac_f32_e32 v49, v84, v84
	v_fmac_f32_e32 v50, v70, v70
	v_add_f32_e32 v49, v49, v50
	v_add_f32_e32 v48, v48, v49
	v_mul_f32_e32 v49, v69, v69
	v_mul_f32_e32 v50, v53, v53
	v_fmac_f32_e32 v49, v68, v68
	v_fmac_f32_e32 v50, v52, v52
	v_add_f32_e32 v49, v49, v50
	v_and_b32_e32 v50, 64, v251
	v_add_f32_e32 v48, v48, v49
	v_xor_b32_e32 v49, 16, v251
	v_add_u32_e32 v50, 64, v50
	v_cmp_lt_i32_e32 vcc, v49, v50
	s_nop 1
	v_cndmask_b32_e32 v49, v251, v49, vcc
	v_lshlrev_b32_e32 v49, 2, v49
	ds_bpermute_b32 v49, v49, v48
	s_waitcnt lgkmcnt(0)
	v_add_f32_e32 v48, v48, v49
	v_xor_b32_e32 v49, 32, v251
	v_cmp_lt_i32_e32 vcc, v49, v50
	s_nop 1
	v_cndmask_b32_e32 v49, v251, v49, vcc
	v_lshlrev_b32_e32 v49, 2, v49
	v_mov_b32_e32 v49, v48
	v_mov_b32_e32 v245, v48
	s_nop 1
	v_permlane32_swap_b32_e32 v49, v245
	s_and_saveexec_b64 s[54:55], s[4:5]
	s_cbranch_execz .LBB0_1388
	v_lshlrev_b64 v[50:51], 8, v[80:81]
	v_lshl_add_u64 v[50:51], s[14:15], 0, v[50:51]
	v_lshl_add_u64 v[50:51], s[16:17], 2, v[50:51]
	s_lshl_b32 s18, s2, 2
	v_lshl_add_u64 v[50:51], v[50:51], 0, s[18:19]
	s_waitcnt lgkmcnt(0)
	v_add_f32_e32 v48, v49, v245
	global_store_dword v[50:51], v48, off

; __device__ __forceinline__ unsigned pk2(float lo, float hi) { f32x2 v = {lo, hi}; bf16x2_t b = __builtin_convertvector(v, bf16x2_t); return __builtin_bit_cast(unsigned, b); }
; __device__ __forceinline__ float bflo(unsigned w) { return __uint_as_float(w << 16); }
; __device__ __forceinline__ float bfhi(unsigned w) { return __uint_as_float(w & 0xffff0000u); }
;     __device__ __forceinline__ void operator()(const f32x4 (&acc)[2][2][4][2], const Unit& u, int wr, int wc, int fr, int fq) const {
;     ...
;                 for (int n = 0; n < 2; ++n) { const int cc = bj * HALF + 4 * n;
;                     f32x4 v = acc[ai][bj][m][n];
;                     if (bias) { v = (v + *(const f32x4*)(bias + col0 + cc)) * *(const f32x4*)(scale + col0 + cc); }
;                     f32x4 b;
;                     if (MODE >= 3) b = (f32x4){0.f, 0.f, 0.f, 0.f};
;                     else if (MODE == 0) b = __builtin_bit_cast(f32x4, cur[bj][n]);
;                     else { const unsigned w0 = n ? cur[bj][0].z : cur[bj][0].x, w1 = n ? cur[bj][0].w : cur[bj][0].y; b = (f32x4){bflo(w0), bfhi(w0), bflo(w1), bfhi(w1)}; }
;                     o[n] = b + v;
;                     if (MODE == 2 || MODE == 4) *(f32x4*)(out + off + cc) = o[n];
;                     ss += (o[n][0] * o[n][0] + o[n][1] * o[n][1]) + (o[n][2] * o[n][2] + o[n][3] * o[n][3]); }
;                 if (MODE != 2 && MODE != 4) { u32x4 w; w.x = pk2(o[0][0], o[0][1]); w.y = pk2(o[0][2], o[0][3]); w.z = pk2(o[1][0], o[1][1]); w.w = pk2(o[1][2], o[1][3]); *(u32x4*)(xb + off + bj * HALF) = w; } }
;             if (MODE != 2 && MODE != 4 && rsq) { ss += __shfl_xor(ss, 16); ss += __shfl_xor(ss, 32); if (fq == 0) rsq[(size_t)row * 64 + u.pn * 4 + wc] = ss; }
.LBB0_1389:
	v_add_u32_e32 v48, 0x80, v142
	s_waitcnt lgkmcnt(0)
	v_ashrrev_i32_e32 v49, 31, v48
	v_lshlrev_b64 v[68:69], 12, v[48:49]
	v_pk_add_f32 v[38:39], v[38:39], 0 op_sel_hi:[1,0]
	v_pk_add_f32 v[50:51], v[36:37], 0 op_sel_hi:[1,0]
	v_pk_add_f32 v[36:37], v[46:47], 0 op_sel_hi:[1,0]
	v_pk_add_f32 v[46:47], v[44:45], 0 op_sel_hi:[1,0]
	v_lshl_add_u64 v[44:45], s[10:11], 0, v[68:69]
	v_cvt_pk_bf16_f32 v52, v50, v51
	v_cvt_pk_bf16_f32 v53, v38, v39
	v_cvt_pk_bf16_f32 v54, v46, v47
	v_cvt_pk_bf16_f32 v55, v36, v37
	v_lshl_add_u64 v[68:69], v[140:141], 1, v[44:45]
	global_store_dwordx4 v[68:69], v[52:55], off
	v_pk_add_f32 v[56:57], v[56:57], 0 op_sel_hi:[1,0]
	v_pk_add_f32 v[44:45], v[62:63], 0 op_sel_hi:[1,0]
	v_pk_add_f32 v[52:53], v[58:59], 0 op_sel_hi:[1,0]
	v_pk_add_f32 v[54:55], v[60:61], 0 op_sel_hi:[1,0]
	v_cvt_pk_bf16_f32 v58, v56, v57
	v_cvt_pk_bf16_f32 v59, v52, v53
	v_cvt_pk_bf16_f32 v60, v54, v55
	v_cvt_pk_bf16_f32 v61, v44, v45
	s_and_b64 vcc, exec, s[8:9]
	global_store_dwordx4 v[68:69], v[58:61], off offset:256
	s_cbranch_vccnz .LBB0_1393
	v_mul_f32_e32 v51, v51, v51
	v_mul_f32_e32 v39, v39, v39
	v_fmac_f32_e32 v51, v50, v50
	v_fmac_f32_e32 v39, v38, v38
	v_add_f32_e32 v38, v51, v39
	v_mul_f32_e32 v39, v47, v47
	v_mul_f32_e32 v37, v37, v37
	v_fmac_f32_e32 v39, v46, v46
	v_fmac_f32_e32 v37, v36, v36
	v_add_f32_e32 v36, v39, v37
	v_add_f32_e32 v36, v38, v36
	v_mul_f32_e32 v37, v57, v57
	v_mul_f32_e32 v38, v53, v53
	v_fmac_f32_e32 v37, v56, v56
	v_fmac_f32_e32 v38, v52, v52
	v_add_f32_e32 v37, v37, v38
	v_add_f32_e32 v36, v36, v37
	v_mul_f32_e32 v37, v55, v55
	v_mul_f32_e32 v38, v45, v45
	v_fmac_f32_e32 v37, v54, v54
	v_fmac_f32_e32 v38, v44, v44
	v_add_f32_e32 v37, v37, v38
	v_and_b32_e32 v38, 64, v251
	v_add_f32_e32 v36, v36, v37
	v_xor_b32_e32 v37, 16, v251
	v_add_u32_e32 v38, 64, v38
	v_cmp_lt_i32_e32 vcc, v37, v38
	s_nop 1
	v_cndmask_b32_e32 v37, v251, v37, vcc
	v_lshlrev_b32_e32 v37, 2, v37
	ds_bpermute_b32 v37, v37, v36
	s_waitcnt lgkmcnt(0)
	v_add_f32_e32 v36, v36, v37
	v_xor_b32_e32 v37, 32, v251
	v_cmp_lt_i32_e32 vcc, v37, v38
	s_nop 1
	v_cndmask_b32_e32 v37, v251, v37, vcc
	v_lshlrev_b32_e32 v37, 2, v37
	v_mov_b32_e32 v37, v36
	v_mov_b32_e32 v245, v36
	s_nop 1
	v_permlane32_swap_b32_e32 v37, v245
	s_and_saveexec_b64 s[54:55], s[4:5]
	s_cbranch_execz .LBB0_1392
	v_lshlrev_b64 v[38:39], 8, v[48:49]
	v_lshl_add_u64 v[38:39], s[14:15], 0, v[38:39]
	v_lshl_add_u64 v[38:39], s[16:17], 2, v[38:39]
	s_lshl_b32 s18, s2, 2
	v_lshl_add_u64 v[38:39], v[38:39], 0, s[18:19]
	s_waitcnt lgkmcnt(0)
	v_add_f32_e32 v36, v37, v245
	global_store_dword v[38:39], v36, off

; __device__ __forceinline__ unsigned pk2(float lo, float hi) { f32x2 v = {lo, hi}; bf16x2_t b = __builtin_convertvector(v, bf16x2_t); return __builtin_bit_cast(unsigned, b); }
; __device__ __forceinline__ float bflo(unsigned w) { return __uint_as_float(w << 16); }
; __device__ __forceinline__ float bfhi(unsigned w) { return __uint_as_float(w & 0xffff0000u); }
;     __device__ __forceinline__ void operator()(const f32x4 (&acc)[2][2][4][2], const Unit& u, int wr, int wc, int fr, int fq) const {
;     ...
;                 for (int n = 0; n < 2; ++n) { const int cc = bj * HALF + 4 * n;
;                     f32x4 v = acc[ai][bj][m][n];
;                     if (bias) { v = (v + *(const f32x4*)(bias + col0 + cc)) * *(const f32x4*)(scale + col0 + cc); }
;                     f32x4 b;
;                     if (MODE >= 3) b = (f32x4){0.f, 0.f, 0.f, 0.f};
;                     else if (MODE == 0) b = __builtin_bit_cast(f32x4, cur[bj][n]);
;                     else { const unsigned w0 = n ? cur[bj][0].z : cur[bj][0].x, w1 = n ? cur[bj][0].w : cur[bj][0].y; b = (f32x4){bflo(w0), bfhi(w0), bflo(w1), bfhi(w1)}; }
;                     o[n] = b + v;
;                     if (MODE == 2 || MODE == 4) *(f32x4*)(out + off + cc) = o[n];
;                     ss += (o[n][0] * o[n][0] + o[n][1] * o[n][1]) + (o[n][2] * o[n][2] + o[n][3] * o[n][3]); }
;                 if (MODE != 2 && MODE != 4) { u32x4 w; w.x = pk2(o[0][0], o[0][1]); w.y = pk2(o[0][2], o[0][3]); w.z = pk2(o[1][0], o[1][1]); w.w = pk2(o[1][2], o[1][3]); *(u32x4*)(xb + off + bj * HALF) = w; } }
;             if (MODE != 2 && MODE != 4 && rsq) { ss += __shfl_xor(ss, 16); ss += __shfl_xor(ss, 32); if (fq == 0) rsq[(size_t)row * 64 + u.pn * 4 + wc] = ss; }
.LBB0_1393:
	v_or_b32_e32 v36, 16, v48
	s_waitcnt lgkmcnt(0)
	v_ashrrev_i32_e32 v37, 31, v36
	v_lshlrev_b64 v[50:51], 12, v[36:37]
	v_pk_add_f32 v[14:15], v[14:15], 0 op_sel_hi:[1,0]
	v_pk_add_f32 v[38:39], v[12:13], 0 op_sel_hi:[1,0]
	v_pk_add_f32 v[12:13], v[22:23], 0 op_sel_hi:[1,0]
	v_pk_add_f32 v[22:23], v[20:21], 0 op_sel_hi:[1,0]
	v_lshl_add_u64 v[20:21], s[10:11], 0, v[50:51]
	v_cvt_pk_bf16_f32 v44, v38, v39
	v_cvt_pk_bf16_f32 v45, v14, v15
	v_cvt_pk_bf16_f32 v46, v22, v23
	v_cvt_pk_bf16_f32 v47, v12, v13
	v_lshl_add_u64 v[56:57], v[140:141], 1, v[20:21]
	global_store_dwordx4 v[56:57], v[44:47], off
	v_pk_add_f32 v[50:51], v[64:65], 0 op_sel_hi:[1,0]
	v_pk_add_f32 v[20:21], v[74:75], 0 op_sel_hi:[1,0]
	v_pk_add_f32 v[44:45], v[66:67], 0 op_sel_hi:[1,0]
	v_pk_add_f32 v[46:47], v[72:73], 0 op_sel_hi:[1,0]
	v_cvt_pk_bf16_f32 v52, v50, v51
	v_cvt_pk_bf16_f32 v53, v44, v45
	v_cvt_pk_bf16_f32 v54, v46, v47
	v_cvt_pk_bf16_f32 v55, v20, v21
	s_and_b64 vcc, exec, s[8:9]
	global_store_dwordx4 v[56:57], v[52:55], off offset:256
	s_cbranch_vccnz .LBB0_1397
	v_mul_f32_e32 v39, v39, v39
	v_mul_f32_e32 v15, v15, v15
	v_fmac_f32_e32 v39, v38, v38
	v_fmac_f32_e32 v15, v14, v14
	v_add_f32_e32 v14, v39, v15
	v_mul_f32_e32 v15, v23, v23
	v_mul_f32_e32 v13, v13, v13
	v_fmac_f32_e32 v15, v22, v22
	v_fmac_f32_e32 v13, v12, v12
	v_add_f32_e32 v12, v15, v13
	v_add_f32_e32 v12, v14, v12
	v_mul_f32_e32 v13, v51, v51
	v_mul_f32_e32 v14, v45, v45
	v_fmac_f32_e32 v13, v50, v50
	v_fmac_f32_e32 v14, v44, v44
	v_add_f32_e32 v13, v13, v14
	v_add_f32_e32 v12, v12, v13
	v_mul_f32_e32 v13, v47, v47
	v_mul_f32_e32 v14, v21, v21
	v_fmac_f32_e32 v13, v46, v46
	v_fmac_f32_e32 v14, v20, v20
	v_add_f32_e32 v13, v13, v14
	v_and_b32_e32 v14, 64, v251
	v_add_f32_e32 v12, v12, v13
	v_xor_b32_e32 v13, 16, v251
	v_add_u32_e32 v14, 64, v14
	v_cmp_lt_i32_e32 vcc, v13, v14
	s_nop 1
	v_cndmask_b32_e32 v13, v251, v13, vcc
	v_lshlrev_b32_e32 v13, 2, v13
	ds_bpermute_b32 v13, v13, v12
	s_waitcnt lgkmcnt(0)
	v_add_f32_e32 v12, v12, v13
	v_xor_b32_e32 v13, 32, v251
	v_cmp_lt_i32_e32 vcc, v13, v14
	s_nop 1
	v_cndmask_b32_e32 v13, v251, v13, vcc
	v_lshlrev_b32_e32 v13, 2, v13
	v_mov_b32_e32 v13, v12
	v_mov_b32_e32 v245, v12
	s_nop 1
	v_permlane32_swap_b32_e32 v13, v245
	s_and_saveexec_b64 s[54:55], s[4:5]
	s_cbranch_execz .LBB0_1396
	v_lshlrev_b64 v[14:15], 8, v[36:37]
	v_lshl_add_u64 v[14:15], s[14:15], 0, v[14:15]
	v_lshl_add_u64 v[14:15], s[16:17], 2, v[14:15]
	s_lshl_b32 s18, s2, 2
	v_lshl_add_u64 v[14:15], v[14:15], 0, s[18:19]
	s_waitcnt lgkmcnt(0)
	v_add_f32_e32 v12, v13, v245
	global_store_dword v[14:15], v12, off

; __device__ __forceinline__ unsigned pk2(float lo, float hi) { f32x2 v = {lo, hi}; bf16x2_t b = __builtin_convertvector(v, bf16x2_t); return __builtin_bit_cast(unsigned, b); }
; __device__ __forceinline__ float bflo(unsigned w) { return __uint_as_float(w << 16); }
; __device__ __forceinline__ float bfhi(unsigned w) { return __uint_as_float(w & 0xffff0000u); }
;     __device__ __forceinline__ void operator()(const f32x4 (&acc)[2][2][4][2], const Unit& u, int wr, int wc, int fr, int fq) const {
;     ...
;                 for (int n = 0; n < 2; ++n) { const int cc = bj * HALF + 4 * n;
;                     f32x4 v = acc[ai][bj][m][n];
;                     if (bias) { v = (v + *(const f32x4*)(bias + col0 + cc)) * *(const f32x4*)(scale + col0 + cc); }
;                     f32x4 b;
;                     if (MODE >= 3) b = (f32x4){0.f, 0.f, 0.f, 0.f};
;                     else if (MODE == 0) b = __builtin_bit_cast(f32x4, cur[bj][n]);
;                     else { const unsigned w0 = n ? cur[bj][0].z : cur[bj][0].x, w1 = n ? cur[bj][0].w : cur[bj][0].y; b = (f32x4){bflo(w0), bfhi(w0), bflo(w1), bfhi(w1)}; }
;                     o[n] = b + v;
;                     if (MODE == 2 || MODE == 4) *(f32x4*)(out + off + cc) = o[n];
;                     ss += (o[n][0] * o[n][0] + o[n][1] * o[n][1]) + (o[n][2] * o[n][2] + o[n][3] * o[n][3]); }
;                 if (MODE != 2 && MODE != 4) { u32x4 w; w.x = pk2(o[0][0], o[0][1]); w.y = pk2(o[0][2], o[0][3]); w.z = pk2(o[1][0], o[1][1]); w.w = pk2(o[1][2], o[1][3]); *(u32x4*)(xb + off + bj * HALF) = w; } }
;             if (MODE != 2 && MODE != 4 && rsq) { ss += __shfl_xor(ss, 16); ss += __shfl_xor(ss, 32); if (fq == 0) rsq[(size_t)row * 64 + u.pn * 4 + wc] = ss; }
.LBB0_1397:
	v_or_b32_e32 v12, 32, v48
	s_waitcnt lgkmcnt(0)
	v_ashrrev_i32_e32 v13, 31, v12
	v_lshlrev_b64 v[22:23], 12, v[12:13]
	v_pk_add_f32 v[20:21], v[26:27], 0 op_sel_hi:[1,0]
	v_pk_add_f32 v[26:27], v[24:25], 0 op_sel_hi:[1,0]
	v_pk_add_f32 v[14:15], v[30:31], 0 op_sel_hi:[1,0]
	v_pk_add_f32 v[24:25], v[28:29], 0 op_sel_hi:[1,0]
	v_lshl_add_u64 v[22:23], s[10:11], 0, v[22:23]
	v_cvt_pk_bf16_f32 v28, v26, v27
	v_cvt_pk_bf16_f32 v29, v20, v21
	v_cvt_pk_bf16_f32 v30, v24, v25
	v_cvt_pk_bf16_f32 v31, v14, v15
	v_lshl_add_u64 v[38:39], v[140:141], 1, v[22:23]
	global_store_dwordx4 v[38:39], v[28:31], off
	v_pk_add_f32 v[32:33], v[32:33], 0 op_sel_hi:[1,0]
	v_pk_add_f32 v[22:23], v[42:43], 0 op_sel_hi:[1,0]
	v_pk_add_f32 v[28:29], v[34:35], 0 op_sel_hi:[1,0]
	v_pk_add_f32 v[30:31], v[40:41], 0 op_sel_hi:[1,0]
	v_cvt_pk_bf16_f32 v34, v32, v33
	v_cvt_pk_bf16_f32 v35, v28, v29
	v_cvt_pk_bf16_f32 v36, v30, v31
	v_cvt_pk_bf16_f32 v37, v22, v23
	s_and_b64 vcc, exec, s[8:9]
	global_store_dwordx4 v[38:39], v[34:37], off offset:256
	s_cbranch_vccnz .LBB0_1401
	v_mul_f32_e32 v27, v27, v27
	v_mul_f32_e32 v21, v21, v21
	v_fmac_f32_e32 v27, v26, v26
	v_fmac_f32_e32 v21, v20, v20
	v_add_f32_e32 v20, v27, v21
	v_mul_f32_e32 v21, v25, v25
	v_mul_f32_e32 v15, v15, v15
	v_fmac_f32_e32 v21, v24, v24
	v_fmac_f32_e32 v15, v14, v14
	v_add_f32_e32 v14, v21, v15
	v_add_f32_e32 v14, v20, v14
	v_mul_f32_e32 v15, v33, v33
	v_mul_f32_e32 v20, v29, v29
	v_fmac_f32_e32 v15, v32, v32
	v_fmac_f32_e32 v20, v28, v28
	v_add_f32_e32 v15, v15, v20
	v_add_f32_e32 v14, v14, v15
	v_mul_f32_e32 v15, v31, v31
	v_mul_f32_e32 v20, v23, v23
	v_fmac_f32_e32 v15, v30, v30
	v_fmac_f32_e32 v20, v22, v22
	v_add_f32_e32 v15, v15, v20
	v_and_b32_e32 v20, 64, v251
	v_add_f32_e32 v14, v14, v15
	v_xor_b32_e32 v15, 16, v251
	v_add_u32_e32 v20, 64, v20
	v_cmp_lt_i32_e32 vcc, v15, v20
	s_nop 1
	v_cndmask_b32_e32 v15, v251, v15, vcc
	v_lshlrev_b32_e32 v15, 2, v15
	ds_bpermute_b32 v15, v15, v14
	s_waitcnt lgkmcnt(0)
	v_add_f32_e32 v14, v14, v15
	v_xor_b32_e32 v15, 32, v251
	v_cmp_lt_i32_e32 vcc, v15, v20
	s_nop 1
	v_cndmask_b32_e32 v15, v251, v15, vcc
	v_lshlrev_b32_e32 v15, 2, v15
	v_mov_b32_e32 v15, v14
	v_mov_b32_e32 v245, v14
	s_nop 1
	v_permlane32_swap_b32_e32 v15, v245
	s_and_saveexec_b64 s[54:55], s[4:5]
	s_cbranch_execz .LBB0_1400
	v_lshlrev_b64 v[12:13], 8, v[12:13]
	v_lshl_add_u64 v[12:13], s[14:15], 0, v[12:13]
	v_lshl_add_u64 v[12:13], s[16:17], 2, v[12:13]
	s_lshl_b32 s18, s2, 2
	v_lshl_add_u64 v[12:13], v[12:13], 0, s[18:19]
	s_waitcnt lgkmcnt(0)
	v_add_f32_e32 v14, v15, v245
	global_store_dword v[12:13], v14, off

; __device__ __forceinline__ unsigned pk2(float lo, float hi) { f32x2 v = {lo, hi}; bf16x2_t b = __builtin_convertvector(v, bf16x2_t); return __builtin_bit_cast(unsigned, b); }
; __device__ __forceinline__ float bflo(unsigned w) { return __uint_as_float(w << 16); }
; __device__ __forceinline__ float bfhi(unsigned w) { return __uint_as_float(w & 0xffff0000u); }
;     __device__ __forceinline__ void operator()(const f32x4 (&acc)[2][2][4][2], const Unit& u, int wr, int wc, int fr, int fq) const {
;     ...
;                 for (int n = 0; n < 2; ++n) { const int cc = bj * HALF + 4 * n;
;                     f32x4 v = acc[ai][bj][m][n];
;                     if (bias) { v = (v + *(const f32x4*)(bias + col0 + cc)) * *(const f32x4*)(scale + col0 + cc); }
;                     f32x4 b;
;                     if (MODE >= 3) b = (f32x4){0.f, 0.f, 0.f, 0.f};
;                     else if (MODE == 0) b = __builtin_bit_cast(f32x4, cur[bj][n]);
;                     else { const unsigned w0 = n ? cur[bj][0].z : cur[bj][0].x, w1 = n ? cur[bj][0].w : cur[bj][0].y; b = (f32x4){bflo(w0), bfhi(w0), bflo(w1), bfhi(w1)}; }
;                     o[n] = b + v;
;                     if (MODE == 2 || MODE == 4) *(f32x4*)(out + off + cc) = o[n];
;                     ss += (o[n][0] * o[n][0] + o[n][1] * o[n][1]) + (o[n][2] * o[n][2] + o[n][3] * o[n][3]); }
;                 if (MODE != 2 && MODE != 4) { u32x4 w; w.x = pk2(o[0][0], o[0][1]); w.y = pk2(o[0][2], o[0][3]); w.z = pk2(o[1][0], o[1][1]); w.w = pk2(o[1][2], o[1][3]); *(u32x4*)(xb + off + bj * HALF) = w; } }
;             if (MODE != 2 && MODE != 4 && rsq) { ss += __shfl_xor(ss, 16); ss += __shfl_xor(ss, 32); if (fq == 0) rsq[(size_t)row * 64 + u.pn * 4 + wc] = ss; }
.LBB0_1401:
	v_or_b32_e32 v12, 48, v48
	v_ashrrev_i32_e32 v13, 31, v12
	v_lshlrev_b64 v[24:25], 12, v[12:13]
	v_pk_add_f32 v[2:3], v[2:3], 0 op_sel_hi:[1,0]
	s_waitcnt lgkmcnt(0)
	v_pk_add_f32 v[14:15], v[0:1], 0 op_sel_hi:[1,0]
	v_pk_add_f32 v[0:1], v[6:7], 0 op_sel_hi:[1,0]
	v_pk_add_f32 v[6:7], v[4:5], 0 op_sel_hi:[1,0]
	v_lshl_add_u64 v[4:5], s[10:11], 0, v[24:25]
	v_cvt_pk_bf16_f32 v20, v14, v15
	v_cvt_pk_bf16_f32 v21, v2, v3
	v_cvt_pk_bf16_f32 v22, v6, v7
	v_cvt_pk_bf16_f32 v23, v0, v1
	v_lshl_add_u64 v[24:25], v[140:141], 1, v[4:5]
	global_store_dwordx4 v[24:25], v[20:23], off
	v_pk_add_f32 v[10:11], v[10:11], 0 op_sel_hi:[1,0]
	v_pk_add_f32 v[4:5], v[18:19], 0 op_sel_hi:[1,0]
	v_pk_add_f32 v[20:21], v[8:9], 0 op_sel_hi:[1,0]
	v_pk_add_f32 v[8:9], v[16:17], 0 op_sel_hi:[1,0]
	v_cvt_pk_bf16_f32 v16, v20, v21
	v_cvt_pk_bf16_f32 v17, v10, v11
	v_cvt_pk_bf16_f32 v18, v8, v9
	v_cvt_pk_bf16_f32 v19, v4, v5
	s_and_b64 vcc, exec, s[8:9]
	global_store_dwordx4 v[24:25], v[16:19], off offset:256
	s_cbranch_vccnz .LBB0_1405
	v_mul_f32_e32 v15, v15, v15
	v_mul_f32_e32 v3, v3, v3
	v_fmac_f32_e32 v15, v14, v14
	v_fmac_f32_e32 v3, v2, v2
	v_add_f32_e32 v2, v15, v3
	v_mul_f32_e32 v3, v7, v7
	v_mul_f32_e32 v1, v1, v1
	v_fmac_f32_e32 v3, v6, v6
	v_fmac_f32_e32 v1, v0, v0
	v_add_f32_e32 v0, v3, v1
	v_add_f32_e32 v0, v2, v0
	v_mul_f32_e32 v1, v21, v21
	v_mul_f32_e32 v2, v11, v11
	v_fmac_f32_e32 v1, v20, v20
	v_fmac_f32_e32 v2, v10, v10
	v_add_f32_e32 v1, v1, v2
	v_add_f32_e32 v0, v0, v1
	v_mul_f32_e32 v1, v9, v9
	v_mul_f32_e32 v2, v5, v5
	v_fmac_f32_e32 v1, v8, v8
	v_fmac_f32_e32 v2, v4, v4
	v_add_f32_e32 v1, v1, v2
	v_and_b32_e32 v2, 64, v251
	v_add_f32_e32 v0, v0, v1
	v_xor_b32_e32 v1, 16, v251
	v_add_u32_e32 v2, 64, v2
	v_cmp_lt_i32_e32 vcc, v1, v2
	s_nop 1
	v_cndmask_b32_e32 v1, v251, v1, vcc
	v_lshlrev_b32_e32 v1, 2, v1
	ds_bpermute_b32 v1, v1, v0
	s_waitcnt lgkmcnt(0)
	v_add_f32_e32 v0, v0, v1
	v_xor_b32_e32 v1, 32, v251
	v_cmp_lt_i32_e32 vcc, v1, v2
	s_nop 1
	v_cndmask_b32_e32 v1, v251, v1, vcc
	v_lshlrev_b32_e32 v1, 2, v1
	v_mov_b32_e32 v1, v0
	v_mov_b32_e32 v245, v0
	s_nop 1
	v_permlane32_swap_b32_e32 v1, v245
	s_and_saveexec_b64 s[8:9], s[4:5]
	s_cbranch_execz .LBB0_1404
	v_lshlrev_b64 v[2:3], 8, v[12:13]
	v_lshl_add_u64 v[2:3], s[14:15], 0, v[2:3]
	v_lshl_add_u64 v[2:3], s[16:17], 2, v[2:3]
	s_lshl_b32 s18, s2, 2
	v_lshl_add_u64 v[2:3], v[2:3], 0, s[18:19]
	s_waitcnt lgkmcnt(0)
	v_add_f32_e32 v0, v1, v245
	global_store_dword v[2:3], v0, off
